# plus fused-up epilogue: the two 8-byte bf16 stores of a row merged into one 16-byte store via v_permlane16_swap (6 of 8 row groups), vmcnt waits re-derived
# speedup vs baseline: 1.0857x; 1.0071x over previous
.LBB0_488:
	ds_read_b128 v[146:149], v220
	ds_read_b128 v[150:153], v220 offset:1024
	ds_read_b128 v[154:157], v220 offset:2048
	ds_read_b128 v[158:161], v220 offset:3072
	ds_read_b128 v[162:165], v221
	ds_read_b128 v[166:169], v221 offset:1024
	ds_read_b128 v[170:173], v221 offset:2048
	ds_read_b128 v[174:177], v221 offset:3072
	s_add_u32 s68, s66, 0xfffc0080
	s_addc_u32 s69, s67, -1
	s_cmp_eq_u32 s97, 12
	s_cselect_b32 s71, s57, s69
	s_cselect_b32 s70, s63, s68
	s_cselect_b32 s69, s55, s96
	s_cselect_b32 s68, s65, s95
	v_lshl_add_u64 v[210:211], s[66:67], 0, v[138:139]
	s_add_i32 m0, s77, 0xc000
	ds_read_b128 v[178:181], v222
	ds_read_b128 v[182:185], v222 offset:1024
	ds_read_b128 v[186:189], v222 offset:2048
	ds_read_b128 v[190:193], v222 offset:3072
	ds_read_b128 v[194:197], v222 offset:4096
	ds_read_b128 v[198:201], v222 offset:5120
	ds_read_b128 v[202:205], v222 offset:6144
	ds_read_b128 v[206:209], v222 offset:7168
	global_load_lds_dwordx4 v[210:211], off
	v_lshl_add_u64 v[210:211], s[66:67], 0, v[140:141]
	s_add_i32 m0, s77, 0xe000
	s_nop 0
	global_load_lds_dwordx4 v[210:211], off
	s_waitcnt vmcnt(8)
	s_waitcnt lgkmcnt(0)
	s_barrier
	s_setprio 1
	s_waitcnt lgkmcnt(0)
	v_mfma_f32_16x16x32_bf16 v[124:127], v[146:149], v[178:181], v[124:127]
	v_mfma_f32_16x16x32_bf16 v[60:63], v[154:157], v[178:181], v[60:63]
	v_mfma_f32_16x16x32_bf16 v[116:119], v[146:149], v[186:189], v[116:119]
	v_mfma_f32_16x16x32_bf16 v[52:55], v[154:157], v[186:189], v[52:55]
	v_mfma_f32_16x16x32_bf16 v[112:115], v[146:149], v[194:197], v[112:115]
	v_mfma_f32_16x16x32_bf16 v[48:51], v[154:157], v[194:197], v[48:51]
	v_mfma_f32_16x16x32_bf16 v[108:111], v[146:149], v[202:205], v[108:111]
	v_mfma_f32_16x16x32_bf16 v[40:43], v[154:157], v[202:205], v[40:43]
	v_mfma_f32_16x16x32_bf16 v[124:127], v[150:153], v[182:185], v[124:127]
	v_mfma_f32_16x16x32_bf16 v[60:63], v[158:161], v[182:185], v[60:63]
	v_mfma_f32_16x16x32_bf16 v[116:119], v[150:153], v[190:193], v[116:119]
	v_mfma_f32_16x16x32_bf16 v[52:55], v[158:161], v[190:193], v[52:55]
	v_mfma_f32_16x16x32_bf16 v[112:115], v[150:153], v[198:201], v[112:115]
	v_mfma_f32_16x16x32_bf16 v[48:51], v[158:161], v[198:201], v[48:51]
	v_mfma_f32_16x16x32_bf16 v[108:111], v[150:153], v[206:209], v[108:111]
	v_mfma_f32_16x16x32_bf16 v[40:43], v[158:161], v[206:209], v[40:43]
	s_setprio 0
	s_setprio 1
	v_mfma_f32_16x16x32_bf16 v[120:123], v[162:165], v[178:181], v[120:123]
	v_mfma_f32_16x16x32_bf16 v[56:59], v[170:173], v[178:181], v[56:59]
	v_mfma_f32_16x16x32_bf16 v[104:107], v[162:165], v[186:189], v[104:107]
	v_mfma_f32_16x16x32_bf16 v[44:47], v[170:173], v[186:189], v[44:47]
	v_mfma_f32_16x16x32_bf16 v[100:103], v[162:165], v[194:197], v[100:103]
	v_mfma_f32_16x16x32_bf16 v[36:39], v[170:173], v[194:197], v[36:39]
	v_mfma_f32_16x16x32_bf16 v[96:99], v[162:165], v[202:205], v[96:99]
	v_mfma_f32_16x16x32_bf16 v[32:35], v[170:173], v[202:205], v[32:35]
	v_mfma_f32_16x16x32_bf16 v[120:123], v[166:169], v[182:185], v[120:123]
	v_mfma_f32_16x16x32_bf16 v[56:59], v[174:177], v[182:185], v[56:59]
	v_mfma_f32_16x16x32_bf16 v[104:107], v[166:169], v[190:193], v[104:107]
	v_mfma_f32_16x16x32_bf16 v[44:47], v[174:177], v[190:193], v[44:47]
	v_mfma_f32_16x16x32_bf16 v[100:103], v[166:169], v[198:201], v[100:103]
	v_mfma_f32_16x16x32_bf16 v[36:39], v[174:177], v[198:201], v[36:39]
	v_mfma_f32_16x16x32_bf16 v[96:99], v[166:169], v[206:209], v[96:99]
	v_mfma_f32_16x16x32_bf16 v[32:35], v[174:177], v[206:209], v[32:35]
	s_setprio 0
	s_barrier
	s_add_i32 s72, s91, s76
	v_lshl_add_u64 v[210:211], s[68:69], 0, v[128:129]
	s_mov_b32 m0, s72
	ds_read_b128 v[178:181], v222 offset:16384
	ds_read_b128 v[182:185], v222 offset:17408
	ds_read_b128 v[186:189], v222 offset:18432
	ds_read_b128 v[190:193], v222 offset:19456
	ds_read_b128 v[194:197], v222 offset:20480
	ds_read_b128 v[198:201], v222 offset:21504
	ds_read_b128 v[202:205], v222 offset:22528
	ds_read_b128 v[206:209], v222 offset:23552
	global_load_lds_dwordx4 v[210:211], off
	s_add_i32 m0, s72, 0x2000
	s_add_u32 vcc_lo, s68, 0x40000
	v_lshl_add_u64 v[212:213], s[68:69], 0, v[130:131]
	s_addc_u32 vcc_hi, s69, 0
	s_add_i32 s72, s92, s76
	global_load_lds_dwordx4 v[212:213], off
	v_lshl_add_u64 v[224:225], vcc, 0, v[128:129]
	s_mov_b32 m0, s72
	v_lshl_add_u64 v[226:227], s[70:71], 0, v[130:131]
	global_load_lds_dwordx4 v[224:225], off
	v_lshl_add_u64 v[224:225], vcc, 0, v[130:131]
	s_add_i32 m0, s72, 0x2000
	s_nop 0
	global_load_lds_dwordx4 v[224:225], off
	v_lshl_add_u64 v[224:225], s[70:71], 0, v[128:129]
	s_mov_b32 m0, s77
	s_nop 0
	global_load_lds_dwordx4 v[224:225], off
	s_mov_b32 m0, s78
	s_nop 0
	global_load_lds_dwordx4 v[226:227], off
	s_waitcnt vmcnt(8)
	s_waitcnt lgkmcnt(0)
	s_barrier
	s_setprio 1
	s_waitcnt lgkmcnt(0)
	v_mfma_f32_16x16x32_bf16 v[92:95], v[146:149], v[178:181], v[92:95]
	v_mfma_f32_16x16x32_bf16 v[28:31], v[154:157], v[178:181], v[28:31]
	v_mfma_f32_16x16x32_bf16 v[84:87], v[146:149], v[186:189], v[84:87]
	v_mfma_f32_16x16x32_bf16 v[20:23], v[154:157], v[186:189], v[20:23]
	v_mfma_f32_16x16x32_bf16 v[80:83], v[146:149], v[194:197], v[80:83]
	v_mfma_f32_16x16x32_bf16 v[16:19], v[154:157], v[194:197], v[16:19]
	v_mfma_f32_16x16x32_bf16 v[76:79], v[146:149], v[202:205], v[76:79]
	v_mfma_f32_16x16x32_bf16 v[8:11], v[154:157], v[202:205], v[8:11]
	v_mfma_f32_16x16x32_bf16 v[92:95], v[150:153], v[182:185], v[92:95]
	v_mfma_f32_16x16x32_bf16 v[28:31], v[158:161], v[182:185], v[28:31]
	v_mfma_f32_16x16x32_bf16 v[84:87], v[150:153], v[190:193], v[84:87]
	v_mfma_f32_16x16x32_bf16 v[20:23], v[158:161], v[190:193], v[20:23]
	v_mfma_f32_16x16x32_bf16 v[80:83], v[150:153], v[198:201], v[80:83]
	v_mfma_f32_16x16x32_bf16 v[16:19], v[158:161], v[198:201], v[16:19]
	v_mfma_f32_16x16x32_bf16 v[76:79], v[150:153], v[206:209], v[76:79]
	v_mfma_f32_16x16x32_bf16 v[8:11], v[158:161], v[206:209], v[8:11]
	s_setprio 0
	s_setprio 1
	v_mfma_f32_16x16x32_bf16 v[88:91], v[162:165], v[178:181], v[88:91]
	v_mfma_f32_16x16x32_bf16 v[24:27], v[170:173], v[178:181], v[24:27]
	v_mfma_f32_16x16x32_bf16 v[72:75], v[162:165], v[186:189], v[72:75]
	v_mfma_f32_16x16x32_bf16 v[12:15], v[170:173], v[186:189], v[12:15]
	v_mfma_f32_16x16x32_bf16 v[68:71], v[162:165], v[194:197], v[68:71]
	v_mfma_f32_16x16x32_bf16 v[4:7], v[170:173], v[194:197], v[4:7]
	v_mfma_f32_16x16x32_bf16 v[64:67], v[162:165], v[202:205], v[64:67]
	v_mfma_f32_16x16x32_bf16 v[0:3], v[170:173], v[202:205], v[0:3]
	v_mfma_f32_16x16x32_bf16 v[88:91], v[166:169], v[182:185], v[88:91]
	v_mfma_f32_16x16x32_bf16 v[24:27], v[174:177], v[182:185], v[24:27]
	v_mfma_f32_16x16x32_bf16 v[72:75], v[166:169], v[190:193], v[72:75]
	v_mfma_f32_16x16x32_bf16 v[12:15], v[174:177], v[190:193], v[12:15]
	v_mfma_f32_16x16x32_bf16 v[68:71], v[166:169], v[198:201], v[68:71]
	v_mfma_f32_16x16x32_bf16 v[4:7], v[174:177], v[198:201], v[4:7]
	v_mfma_f32_16x16x32_bf16 v[64:67], v[166:169], v[206:209], v[64:67]
	v_mfma_f32_16x16x32_bf16 v[0:3], v[174:177], v[206:209], v[0:3]
	s_setprio 0
	s_barrier
	s_add_i32 s72, 0, 0x18000
	s_add_i32 vcc_lo, 0, 0x1c000
	v_add_u32_e32 v158, s72, v216
	v_add_u32_e32 v174, vcc_lo, v216
	ds_read_b128 v[146:149], v158
	ds_read_b128 v[150:153], v158 offset:1024
	ds_read_b128 v[154:157], v158 offset:2048
	ds_read_b128 v[158:161], v158 offset:3072
	ds_read_b128 v[162:165], v174
	ds_read_b128 v[166:169], v174 offset:1024
	ds_read_b128 v[170:173], v174 offset:2048
	ds_read_b128 v[174:177], v174 offset:3072
	s_add_u32 s70, s70, 0x40000
	s_addc_u32 s71, s71, 0
	s_mov_b32 m0, s79
	v_lshl_add_u64 v[228:229], s[70:71], 0, v[128:129]
	ds_read_b128 v[178:181], v222 offset:32768
	ds_read_b128 v[182:185], v222 offset:33792
	ds_read_b128 v[186:189], v222 offset:34816
	ds_read_b128 v[190:193], v222 offset:35840
	ds_read_b128 v[194:197], v222 offset:36864
	ds_read_b128 v[198:201], v222 offset:37888
	ds_read_b128 v[202:205], v222 offset:38912
	ds_read_b128 v[206:209], v222 offset:39936
	global_load_lds_dwordx4 v[228:229], off
	v_lshl_add_u64 v[228:229], s[70:71], 0, v[130:131]
	s_mov_b32 m0, s80
	s_nop 0
	global_load_lds_dwordx4 v[228:229], off
	s_waitcnt vmcnt(8)
	s_waitcnt lgkmcnt(0)
	s_barrier
	s_setprio 1
	s_waitcnt lgkmcnt(0)
	v_mfma_f32_16x16x32_bf16 v[124:127], v[146:149], v[178:181], v[124:127]
	v_mfma_f32_16x16x32_bf16 v[60:63], v[154:157], v[178:181], v[60:63]
	v_mfma_f32_16x16x32_bf16 v[116:119], v[146:149], v[186:189], v[116:119]
	v_mfma_f32_16x16x32_bf16 v[52:55], v[154:157], v[186:189], v[52:55]
	v_mfma_f32_16x16x32_bf16 v[112:115], v[146:149], v[194:197], v[112:115]
	v_mfma_f32_16x16x32_bf16 v[48:51], v[154:157], v[194:197], v[48:51]
	v_mfma_f32_16x16x32_bf16 v[108:111], v[146:149], v[202:205], v[108:111]
	v_mfma_f32_16x16x32_bf16 v[40:43], v[154:157], v[202:205], v[40:43]
	v_mfma_f32_16x16x32_bf16 v[124:127], v[150:153], v[182:185], v[124:127]
	v_mfma_f32_16x16x32_bf16 v[60:63], v[158:161], v[182:185], v[60:63]
	v_mfma_f32_16x16x32_bf16 v[116:119], v[150:153], v[190:193], v[116:119]
	v_mfma_f32_16x16x32_bf16 v[52:55], v[158:161], v[190:193], v[52:55]
	v_mfma_f32_16x16x32_bf16 v[112:115], v[150:153], v[198:201], v[112:115]
	v_mfma_f32_16x16x32_bf16 v[48:51], v[158:161], v[198:201], v[48:51]
	v_mfma_f32_16x16x32_bf16 v[108:111], v[150:153], v[206:209], v[108:111]
	v_mfma_f32_16x16x32_bf16 v[40:43], v[158:161], v[206:209], v[40:43]
	s_setprio 0
	s_setprio 1
	v_mfma_f32_16x16x32_bf16 v[120:123], v[162:165], v[178:181], v[120:123]
	v_mfma_f32_16x16x32_bf16 v[56:59], v[170:173], v[178:181], v[56:59]
	v_mfma_f32_16x16x32_bf16 v[104:107], v[162:165], v[186:189], v[104:107]
	v_mfma_f32_16x16x32_bf16 v[44:47], v[170:173], v[186:189], v[44:47]
	v_mfma_f32_16x16x32_bf16 v[100:103], v[162:165], v[194:197], v[100:103]
	v_mfma_f32_16x16x32_bf16 v[36:39], v[170:173], v[194:197], v[36:39]
	v_mfma_f32_16x16x32_bf16 v[96:99], v[162:165], v[202:205], v[96:99]
	v_mfma_f32_16x16x32_bf16 v[32:35], v[170:173], v[202:205], v[32:35]
	v_mfma_f32_16x16x32_bf16 v[120:123], v[166:169], v[182:185], v[120:123]
	v_mfma_f32_16x16x32_bf16 v[56:59], v[174:177], v[182:185], v[56:59]
	v_mfma_f32_16x16x32_bf16 v[104:107], v[166:169], v[190:193], v[104:107]
	v_mfma_f32_16x16x32_bf16 v[44:47], v[174:177], v[190:193], v[44:47]
	v_mfma_f32_16x16x32_bf16 v[100:103], v[166:169], v[198:201], v[100:103]
	v_mfma_f32_16x16x32_bf16 v[36:39], v[174:177], v[198:201], v[36:39]
	v_mfma_f32_16x16x32_bf16 v[96:99], v[166:169], v[206:209], v[96:99]
	v_mfma_f32_16x16x32_bf16 v[32:35], v[174:177], v[206:209], v[32:35]
	s_setprio 0
	s_barrier
	s_add_i32 s70, s72, s76
	v_lshl_add_u64 v[210:211], v[210:211], 0, s[20:21]
	s_mov_b32 m0, s70
	ds_read_b128 v[178:181], v222 offset:49152
	ds_read_b128 v[182:185], v222 offset:50176
	ds_read_b128 v[186:189], v222 offset:51200
	ds_read_b128 v[190:193], v222 offset:52224
	ds_read_b128 v[194:197], v222 offset:53248
	ds_read_b128 v[198:201], v222 offset:54272
	ds_read_b128 v[202:205], v222 offset:55296
	ds_read_b128 v[206:209], v222 offset:56320
	global_load_lds_dwordx4 v[210:211], off
	s_add_i32 m0, s70, 0x2000
	s_add_u32 s68, s68, 0x40080
	v_lshl_add_u64 v[210:211], v[212:213], 0, s[20:21]
	s_addc_u32 s69, s69, 0
	s_add_i32 s70, vcc_lo, s76
	global_load_lds_dwordx4 v[210:211], off
	v_lshl_add_u64 v[210:211], s[68:69], 0, v[128:129]
	s_mov_b32 m0, s70
	s_nop 0
	global_load_lds_dwordx4 v[210:211], off
	v_lshl_add_u64 v[210:211], s[68:69], 0, v[130:131]
	s_add_i32 m0, s70, 0x2000
	s_nop 0
	global_load_lds_dwordx4 v[210:211], off
	v_lshl_add_u64 v[210:211], v[224:225], 0, s[20:21]
	s_mov_b32 m0, s88
	s_nop 0
	global_load_lds_dwordx4 v[210:211], off
	v_lshl_add_u64 v[210:211], v[226:227], 0, s[20:21]
	s_mov_b32 m0, s89
	s_nop 0
	global_load_lds_dwordx4 v[210:211], off
	s_waitcnt vmcnt(8)
	s_waitcnt lgkmcnt(0)
	s_barrier
	s_setprio 1
	s_waitcnt lgkmcnt(0)
	v_mfma_f32_16x16x32_bf16 v[92:95], v[146:149], v[178:181], v[92:95]
	v_mfma_f32_16x16x32_bf16 v[28:31], v[154:157], v[178:181], v[28:31]
	v_mfma_f32_16x16x32_bf16 v[84:87], v[146:149], v[186:189], v[84:87]
	v_mfma_f32_16x16x32_bf16 v[20:23], v[154:157], v[186:189], v[20:23]
	v_mfma_f32_16x16x32_bf16 v[80:83], v[146:149], v[194:197], v[80:83]
	v_mfma_f32_16x16x32_bf16 v[16:19], v[154:157], v[194:197], v[16:19]
	v_mfma_f32_16x16x32_bf16 v[76:79], v[146:149], v[202:205], v[76:79]
	v_mfma_f32_16x16x32_bf16 v[8:11], v[154:157], v[202:205], v[8:11]
	v_mfma_f32_16x16x32_bf16 v[92:95], v[150:153], v[182:185], v[92:95]
	v_mfma_f32_16x16x32_bf16 v[28:31], v[158:161], v[182:185], v[28:31]
	v_mfma_f32_16x16x32_bf16 v[84:87], v[150:153], v[190:193], v[84:87]
	v_mfma_f32_16x16x32_bf16 v[20:23], v[158:161], v[190:193], v[20:23]
	v_mfma_f32_16x16x32_bf16 v[80:83], v[150:153], v[198:201], v[80:83]
	v_mfma_f32_16x16x32_bf16 v[16:19], v[158:161], v[198:201], v[16:19]
	v_mfma_f32_16x16x32_bf16 v[76:79], v[150:153], v[206:209], v[76:79]
	v_mfma_f32_16x16x32_bf16 v[8:11], v[158:161], v[206:209], v[8:11]
	s_setprio 0
	s_setprio 1
	v_mfma_f32_16x16x32_bf16 v[88:91], v[162:165], v[178:181], v[88:91]
	v_mfma_f32_16x16x32_bf16 v[24:27], v[170:173], v[178:181], v[24:27]
	v_mfma_f32_16x16x32_bf16 v[72:75], v[162:165], v[186:189], v[72:75]
	v_mfma_f32_16x16x32_bf16 v[12:15], v[170:173], v[186:189], v[12:15]
	v_mfma_f32_16x16x32_bf16 v[68:71], v[162:165], v[194:197], v[68:71]
	v_mfma_f32_16x16x32_bf16 v[4:7], v[170:173], v[194:197], v[4:7]
	v_mfma_f32_16x16x32_bf16 v[64:67], v[162:165], v[202:205], v[64:67]
	v_mfma_f32_16x16x32_bf16 v[0:3], v[170:173], v[202:205], v[0:3]
	v_mfma_f32_16x16x32_bf16 v[88:91], v[166:169], v[182:185], v[88:91]
	v_mfma_f32_16x16x32_bf16 v[24:27], v[174:177], v[182:185], v[24:27]
	v_mfma_f32_16x16x32_bf16 v[72:75], v[166:169], v[190:193], v[72:75]
	v_mfma_f32_16x16x32_bf16 v[12:15], v[174:177], v[190:193], v[12:15]
	v_mfma_f32_16x16x32_bf16 v[68:71], v[166:169], v[198:201], v[68:71]
	v_mfma_f32_16x16x32_bf16 v[4:7], v[174:177], v[198:201], v[4:7]
	v_mfma_f32_16x16x32_bf16 v[64:67], v[166:169], v[206:209], v[64:67]
	v_mfma_f32_16x16x32_bf16 v[0:3], v[174:177], v[206:209], v[0:3]
	s_setprio 0
	s_barrier
	s_add_i32 s97, s97, 2
	s_add_u32 s66, s66, 0x100
	s_addc_u32 s67, s67, 0
	s_add_u32 s95, s95, 0x100
	s_addc_u32 s96, s96, 0
	s_cmp_gt_u32 s97, 13
	s_cbranch_scc0 .LBB0_488
	v_mbcnt_lo_u32_b32 v238, -1, 0
	v_mbcnt_hi_u32_b32 v238, -1, v238
	v_bfe_u32 v238, v238, 4, 1
	v_mul_u32_u24_e32 v238, 24, v238
	v_mov_b32_e32 v239, 0
	s_and_b64 vcc, exec, s[22:23]
	s_cbranch_vccz .LBB0_491
	s_barrier

.LBB0_495:
	s_or_b64 exec, exec, s[64:65]
	s_ashr_i32 s55, s57, 12
	s_and_b32 s55, s55, -2
	v_pk_mul_f32 v[104:105], v[118:119], v[162:163] op_sel_hi:[1,0]
	v_pk_mul_f32 v[106:107], v[106:107], v[162:163] op_sel_hi:[1,0]
	v_pk_mul_f32 v[112:113], v[114:115], v[160:161] op_sel_hi:[1,0]
	v_pk_mul_f32 v[114:115], v[102:103], v[160:161] op_sel_hi:[1,0]
	v_pk_mul_f32 v[102:103], v[110:111], v[158:159] op_sel_hi:[1,0]
	v_pk_mul_f32 v[98:99], v[98:99], v[158:159] op_sel_hi:[1,0]
	s_addk_i32 s55, 0xe002
	v_mov_b32_dpp v85, v126 row_ror:1 row_mask:0xf bank_mask:0xf bound_ctrl:1
	v_mov_b32_dpp v84, v122 row_ror:1 row_mask:0xf bank_mask:0xf bound_ctrl:1
	v_mov_b32_e32 v120, v190
	v_mov_b32_dpp v85, v104 row_shr:1 row_mask:0xf bank_mask:0xf
	v_mov_b32_dpp v84, v106 row_shr:1 row_mask:0xf bank_mask:0xf
	v_mov_b32_e32 v121, v196
	v_mov_b32_dpp v111, v126 row_ror:2 row_mask:0xf bank_mask:0xf bound_ctrl:1
	v_mov_b32_dpp v110, v122 row_ror:2 row_mask:0xf bank_mask:0xf bound_ctrl:1
	v_mov_b32_e32 v116, v106
	v_mov_b32_e32 v117, v104
	v_mov_b32_e32 v118, v186
	v_mov_b32_e32 v119, v194
	v_pk_mul_f32 v[84:85], v[120:121], v[84:85]
	v_mov_b32_dpp v111, v104 row_shr:2 row_mask:0xf bank_mask:0xf
	v_mov_b32_dpp v110, v106 row_shr:2 row_mask:0xf bank_mask:0xf
	v_pk_fma_f32 v[84:85], v[116:117], v[118:119], v[84:85]
	v_mov_b32_e32 v124, v182
	v_mov_b32_e32 v125, v184
	v_pk_fma_f32 v[84:85], v[124:125], v[110:111], v[84:85]
	v_mov_b32_dpp v111, v127 row_ror:1 row_mask:0xf bank_mask:0xf bound_ctrl:1
	v_mov_b32_dpp v110, v123 row_ror:1 row_mask:0xf bank_mask:0xf bound_ctrl:1
	v_mov_b32_dpp v117, v127 row_ror:2 row_mask:0xf bank_mask:0xf bound_ctrl:1
	v_mov_b32_dpp v111, v105 row_shr:1 row_mask:0xf bank_mask:0xf
	v_mov_b32_dpp v110, v107 row_shr:1 row_mask:0xf bank_mask:0xf
	v_mov_b32_e32 v126, v191
	v_mov_b32_e32 v127, v197
	v_mov_b32_dpp v116, v123 row_ror:2 row_mask:0xf bank_mask:0xf bound_ctrl:1
	v_mov_b32_e32 v202, v107
	v_mov_b32_e32 v203, v105
	v_mov_b32_e32 v122, v187
	v_mov_b32_e32 v123, v195
	v_pk_mul_f32 v[110:111], v[126:127], v[110:111]
	v_mov_b32_dpp v117, v105 row_shr:2 row_mask:0xf bank_mask:0xf
	v_mov_b32_dpp v116, v107 row_shr:2 row_mask:0xf bank_mask:0xf
	v_pk_fma_f32 v[110:111], v[202:203], v[122:123], v[110:111]
	v_mov_b32_e32 v202, v183
	v_mov_b32_e32 v203, v185
	v_pk_fma_f32 v[110:111], v[202:203], v[116:117], v[110:111]
	v_mov_b32_e32 v204, v189
	v_mov_b32_e32 v205, v193
	v_mov_b32_e32 v200, v188
	v_mov_b32_e32 v201, v192
	v_pk_add_f32 v[110:111], v[204:205], v[110:111]
	v_pk_add_f32 v[84:85], v[200:201], v[84:85]
	v_mul_f32_e32 v77, 0xbfb8aa3b, v111
	v_mul_f32_e32 v73, 0xbfb8aa3b, v85
	v_exp_f32_e32 v77, v77
	v_exp_f32_e32 v73, v73
	v_add_f32_e32 v77, 1.0, v77
	v_add_f32_e32 v73, 1.0, v73
	v_rcp_f32_e32 v77, v77
	v_rcp_f32_e32 v73, v73
	v_mul_f32_e32 v77, v111, v77
	v_mul_f32_e32 v73, v85, v73
	v_mul_f32_e32 v77, v110, v77
	v_mov_b64_e32 v[110:111], s[48:49]
	v_mul_f32_e32 v73, v84, v73
	v_mad_i64_i32 v[84:85], s[64:65], v174, s93, v[110:111]
	v_lshlrev_b64 v[174:175], 1, v[146:147]
	v_lshl_add_u64 v[84:85], v[84:85], 0, v[174:175]
	v_cvt_pk_bf16_f32 v73, v73, v77
	v_mov_b32_e32 v230, v72
	v_mov_b32_e32 v231, v73
	s_nop 0
	v_mov_b32_dpp v73, v104 row_ror:1 row_mask:0xf bank_mask:0xf bound_ctrl:1
	v_mov_b32_dpp v72, v106 row_ror:1 row_mask:0xf bank_mask:0xf bound_ctrl:1
	v_mov_b32_dpp v117, v104 row_ror:2 row_mask:0xf bank_mask:0xf bound_ctrl:1
	v_mov_b32_dpp v73, v112 row_shr:1 row_mask:0xf bank_mask:0xf
	v_mov_b32_dpp v72, v114 row_shr:1 row_mask:0xf bank_mask:0xf
	v_mov_b32_dpp v116, v106 row_ror:2 row_mask:0xf bank_mask:0xf bound_ctrl:1
	v_mov_b32_e32 v206, v114
	v_mov_b32_e32 v207, v112
	v_pk_mul_f32 v[72:73], v[120:121], v[72:73]
	v_mov_b32_dpp v117, v112 row_shr:2 row_mask:0xf bank_mask:0xf
	v_mov_b32_dpp v116, v114 row_shr:2 row_mask:0xf bank_mask:0xf
	v_pk_fma_f32 v[72:73], v[206:207], v[118:119], v[72:73]
	v_mov_b32_dpp v104, v107 row_ror:2 row_mask:0xf bank_mask:0xf bound_ctrl:1
	v_pk_fma_f32 v[72:73], v[124:125], v[116:117], v[72:73]
	v_mov_b32_dpp v117, v105 row_ror:1 row_mask:0xf bank_mask:0xf bound_ctrl:1
	v_mov_b32_dpp v116, v107 row_ror:1 row_mask:0xf bank_mask:0xf bound_ctrl:1
	v_mov_b32_dpp v105, v105 row_ror:2 row_mask:0xf bank_mask:0xf bound_ctrl:1
	v_mov_b32_dpp v117, v113 row_shr:1 row_mask:0xf bank_mask:0xf
	v_mov_b32_dpp v116, v115 row_shr:1 row_mask:0xf bank_mask:0xf
	v_mov_b32_e32 v106, v115
	v_mov_b32_e32 v107, v113
	v_pk_mul_f32 v[116:117], v[126:127], v[116:117]
	v_mov_b32_dpp v105, v113 row_shr:2 row_mask:0xf bank_mask:0xf
	v_mov_b32_dpp v104, v115 row_shr:2 row_mask:0xf bank_mask:0xf
	v_pk_fma_f32 v[106:107], v[106:107], v[122:123], v[116:117]
	v_pk_add_f32 v[72:73], v[200:201], v[72:73]
	v_pk_fma_f32 v[104:105], v[202:203], v[104:105], v[106:107]
	v_mul_f32_e32 v77, 0xbfb8aa3b, v73
	v_pk_add_f32 v[104:105], v[204:205], v[104:105]
	v_exp_f32_e32 v77, v77
	v_mul_f32_e32 v106, 0xbfb8aa3b, v105
	v_exp_f32_e32 v106, v106
	v_add_f32_e32 v77, 1.0, v77
	v_rcp_f32_e32 v77, v77
	v_add_f32_e32 v106, 1.0, v106
	v_rcp_f32_e32 v106, v106
	v_mul_f32_e32 v73, v73, v77
	v_mul_f32_e32 v72, v72, v73
	v_mul_f32_e32 v73, v105, v106
	v_mul_f32_e32 v73, v104, v73
	v_cvt_pk_bf16_f32 v77, v72, v73
	v_mad_i64_i32 v[72:73], s[64:65], v172, s93, v[110:111]
	v_lshl_add_u64 v[104:105], v[72:73], 0, v[174:175]
	v_mov_b32_e32 v240, v76
	v_mov_b32_e32 v241, v77
	v_mov_b32_dpp v73, v112 row_ror:1 row_mask:0xf bank_mask:0xf bound_ctrl:1
	v_mov_b32_dpp v72, v114 row_ror:1 row_mask:0xf bank_mask:0xf bound_ctrl:1
	v_mov_b32_dpp v77, v112 row_ror:2 row_mask:0xf bank_mask:0xf bound_ctrl:1
	v_mov_b32_dpp v73, v102 row_shr:1 row_mask:0xf bank_mask:0xf
	v_mov_b32_dpp v72, v98 row_shr:1 row_mask:0xf bank_mask:0xf
	v_mov_b32_dpp v76, v114 row_ror:2 row_mask:0xf bank_mask:0xf bound_ctrl:1
	v_mov_b32_e32 v106, v98
	v_mov_b32_e32 v107, v102
	v_pk_mul_f32 v[72:73], v[120:121], v[72:73]
	v_mov_b32_dpp v77, v102 row_shr:2 row_mask:0xf bank_mask:0xf
	v_mov_b32_dpp v76, v98 row_shr:2 row_mask:0xf bank_mask:0xf
	v_pk_fma_f32 v[72:73], v[106:107], v[118:119], v[72:73]
	v_mov_b32_dpp v107, v113 row_ror:2 row_mask:0xf bank_mask:0xf bound_ctrl:1
	v_pk_fma_f32 v[72:73], v[124:125], v[76:77], v[72:73]
	v_mov_b32_dpp v77, v113 row_ror:1 row_mask:0xf bank_mask:0xf bound_ctrl:1
	v_pk_add_f32 v[72:73], v[200:201], v[72:73]
	v_mov_b32_dpp v106, v115 row_ror:2 row_mask:0xf bank_mask:0xf bound_ctrl:1
	v_mul_f32_e32 v76, 0xbfb8aa3b, v73
	v_exp_f32_e32 v109, v76
	v_mov_b32_dpp v77, v103 row_shr:1 row_mask:0xf bank_mask:0xf
	v_mov_b32_dpp v76, v115 row_ror:1 row_mask:0xf bank_mask:0xf bound_ctrl:1
	v_mov_b32_e32 v112, v99
	v_mov_b32_e32 v113, v103
	v_mov_b32_dpp v76, v99 row_shr:1 row_mask:0xf bank_mask:0xf
	v_pk_mul_f32 v[76:77], v[126:127], v[76:77]
	v_mov_b32_dpp v107, v103 row_shr:2 row_mask:0xf bank_mask:0xf
	v_mov_b32_dpp v106, v99 row_shr:2 row_mask:0xf bank_mask:0xf
	v_pk_fma_f32 v[76:77], v[112:113], v[122:123], v[76:77]
	s_nop 0
	v_pk_fma_f32 v[76:77], v[202:203], v[106:107], v[76:77]
	v_add_f32_e32 v107, 1.0, v109
	v_pk_add_f32 v[76:77], v[204:205], v[76:77]
	v_rcp_f32_e32 v107, v107
	v_mul_f32_e32 v106, 0xbfb8aa3b, v77
	v_exp_f32_e32 v106, v106
	v_mul_f32_e32 v73, v73, v107
	v_mul_f32_e32 v72, v72, v73
	v_add_f32_e32 v106, 1.0, v106
	v_rcp_f32_e32 v106, v106
	s_nop 0
	v_mul_f32_e32 v73, v77, v106
	v_mul_f32_e32 v73, v76, v73
	v_cvt_pk_bf16_f32 v109, v72, v73
	v_mad_i64_i32 v[72:73], s[64:65], v170, s93, v[110:111]
	v_lshl_add_u64 v[106:107], v[72:73], 0, v[174:175]
	v_lshl_add_u64 v[72:73], v[134:135], 0, s[62:63]
	v_lshl_add_u64 v[76:77], v[146:147], 2, v[72:73]
	v_and_b32_e32 v170, 0x1fff, v170
	v_mov_b32_e32 v242, v108
	v_mov_b32_e32 v243, v109
	s_and_saveexec_b64 s[62:63], s[4:5]
	s_cbranch_execz .LBB0_498
	v_add_co_u32_e32 v72, vcc, 0x2000, v76
	global_store_dwordx4 v[76:77], v[100:103], off
	s_nop 0
	v_addc_co_u32_e32 v73, vcc, 0, v77, vcc
	v_cmp_lt_u32_e32 vcc, s94, v170
	global_store_dwordx4 v[72:73], v[96:99], off offset:3072
	s_and_b64 exec, exec, vcc
	s_cbranch_execz .LBB0_498
	v_add_u32_e32 v72, s55, v170
	v_mul_hi_i32_i24_e32 v73, 0x5800, v72
	v_mul_i32_i24_e32 v72, 0x5800, v72
	v_lshl_add_u64 v[72:73], s[18:19], 0, v[72:73]
	v_lshl_add_u64 v[72:73], v[146:147], 2, v[72:73]
	global_store_dwordx4 v[72:73], v[100:103], off
	v_add_co_u32_e32 v72, vcc, 0x2000, v72
	s_nop 1
	v_addc_co_u32_e32 v73, vcc, 0, v73, vcc
	global_store_dwordx4 v[72:73], v[96:99], off offset:3072

.LBB0_502:
	s_or_b64 exec, exec, s[64:65]
	s_ashr_i32 s57, s57, 12
	s_and_b32 s57, s57, -2
	v_pk_mul_f32 v[86:87], v[86:87], v[152:153] op_sel_hi:[1,0]
	v_pk_mul_f32 v[74:75], v[74:75], v[152:153] op_sel_hi:[1,0]
	v_pk_mul_f32 v[92:93], v[70:71], v[150:151] op_sel_hi:[1,0]
	v_pk_mul_f32 v[70:71], v[78:79], v[148:149] op_sel_hi:[1,0]
	v_pk_mul_f32 v[66:67], v[66:67], v[148:149] op_sel_hi:[1,0]
	s_addk_i32 s57, 0xe002
	v_pk_mul_f32 v[88:89], v[82:83], v[150:151] op_sel_hi:[1,0]
	v_or_b32_e32 v149, 16, v157
	v_or_b32_e32 v151, 32, v157
	v_or_b32_e32 v153, 48, v157
	v_mov_b32_dpp v79, v94 row_ror:1 row_mask:0xf bank_mask:0xf bound_ctrl:1
	v_mov_b32_dpp v78, v90 row_ror:1 row_mask:0xf bank_mask:0xf bound_ctrl:1
	v_mov_b32_dpp v83, v94 row_ror:2 row_mask:0xf bank_mask:0xf bound_ctrl:1
	v_mov_b32_dpp v79, v86 row_shr:1 row_mask:0xf bank_mask:0xf
	v_mov_b32_dpp v78, v74 row_shr:1 row_mask:0xf bank_mask:0xf
	v_mov_b32_dpp v82, v90 row_ror:2 row_mask:0xf bank_mask:0xf bound_ctrl:1
	v_mov_b32_e32 v172, v74
	v_mov_b32_e32 v173, v86
	v_pk_mul_f32 v[78:79], v[120:121], v[78:79]
	v_mov_b32_dpp v83, v86 row_shr:2 row_mask:0xf bank_mask:0xf
	v_mov_b32_dpp v82, v74 row_shr:2 row_mask:0xf bank_mask:0xf
	v_pk_fma_f32 v[78:79], v[172:173], v[118:119], v[78:79]
	v_mov_b32_dpp v94, v91 row_ror:2 row_mask:0xf bank_mask:0xf bound_ctrl:1
	v_pk_fma_f32 v[78:79], v[124:125], v[82:83], v[78:79]
	v_mov_b32_dpp v83, v95 row_ror:1 row_mask:0xf bank_mask:0xf bound_ctrl:1
	v_pk_add_f32 v[78:79], v[200:201], v[78:79]
	v_mov_b32_dpp v95, v95 row_ror:2 row_mask:0xf bank_mask:0xf bound_ctrl:1
	v_mul_f32_e32 v82, 0xbfb8aa3b, v79
	v_exp_f32_e32 v155, v82
	v_mov_b32_dpp v83, v87 row_shr:1 row_mask:0xf bank_mask:0xf
	v_mov_b32_dpp v82, v91 row_ror:1 row_mask:0xf bank_mask:0xf bound_ctrl:1
	v_mov_b32_e32 v90, v75
	v_mov_b32_e32 v91, v87
	v_mov_b32_dpp v82, v75 row_shr:1 row_mask:0xf bank_mask:0xf
	v_pk_mul_f32 v[82:83], v[126:127], v[82:83]
	v_mov_b32_dpp v95, v87 row_shr:2 row_mask:0xf bank_mask:0xf
	v_mov_b32_dpp v94, v75 row_shr:2 row_mask:0xf bank_mask:0xf
	v_pk_fma_f32 v[82:83], v[90:91], v[122:123], v[82:83]
	v_add_f32_e32 v91, 1.0, v155
	v_pk_fma_f32 v[82:83], v[202:203], v[94:95], v[82:83]
	v_rcp_f32_e32 v91, v91
	v_pk_add_f32 v[82:83], v[204:205], v[82:83]
	v_mul_f32_e32 v79, v79, v91
	v_mul_f32_e32 v90, 0xbfb8aa3b, v83
	v_exp_f32_e32 v90, v90
	v_mul_f32_e32 v78, v78, v79
	v_add_f32_e32 v90, 1.0, v90
	v_rcp_f32_e32 v90, v90
	s_nop 0
	v_mul_f32_e32 v79, v83, v90
	v_mul_f32_e32 v79, v82, v79
	v_mov_b64_e32 v[90:91], s[48:49]
	v_cvt_pk_bf16_f32 v177, v78, v79
	v_mad_i64_i32 v[78:79], s[64:65], v149, s93, v[90:91]
	v_lshl_add_u64 v[78:79], v[78:79], 0, v[174:175]
	v_mov_b32_e32 v244, v176
	v_mov_b32_e32 v245, v177
	v_mov_b32_dpp v83, v86 row_ror:1 row_mask:0xf bank_mask:0xf bound_ctrl:1
	v_mov_b32_dpp v82, v74 row_ror:1 row_mask:0xf bank_mask:0xf bound_ctrl:1
	v_mov_b32_dpp v95, v86 row_ror:2 row_mask:0xf bank_mask:0xf bound_ctrl:1
	v_mov_b32_dpp v83, v88 row_shr:1 row_mask:0xf bank_mask:0xf
	v_mov_b32_dpp v82, v92 row_shr:1 row_mask:0xf bank_mask:0xf
	v_mov_b32_dpp v94, v74 row_ror:2 row_mask:0xf bank_mask:0xf bound_ctrl:1
	v_mov_b32_e32 v172, v92
	v_mov_b32_e32 v173, v88
	v_pk_mul_f32 v[82:83], v[120:121], v[82:83]
	v_mov_b32_dpp v95, v88 row_shr:2 row_mask:0xf bank_mask:0xf
	v_mov_b32_dpp v94, v92 row_shr:2 row_mask:0xf bank_mask:0xf
	v_pk_fma_f32 v[82:83], v[172:173], v[118:119], v[82:83]
	v_mov_b32_dpp v86, v75 row_ror:2 row_mask:0xf bank_mask:0xf bound_ctrl:1
	v_pk_fma_f32 v[82:83], v[124:125], v[94:95], v[82:83]
	v_mov_b32_dpp v95, v87 row_ror:1 row_mask:0xf bank_mask:0xf bound_ctrl:1
	v_pk_add_f32 v[82:83], v[200:201], v[82:83]
	v_mov_b32_dpp v94, v75 row_ror:1 row_mask:0xf bank_mask:0xf bound_ctrl:1
	v_mul_f32_e32 v74, 0xbfb8aa3b, v83
	v_mov_b32_dpp v95, v89 row_shr:1 row_mask:0xf bank_mask:0xf
	v_mov_b32_dpp v94, v93 row_shr:1 row_mask:0xf bank_mask:0xf
	v_exp_f32_e32 v149, v74
	v_mov_b32_dpp v87, v87 row_ror:2 row_mask:0xf bank_mask:0xf bound_ctrl:1
	v_mov_b32_e32 v74, v93
	v_mov_b32_e32 v75, v89
	v_pk_mul_f32 v[94:95], v[126:127], v[94:95]
	v_mov_b32_dpp v87, v89 row_shr:2 row_mask:0xf bank_mask:0xf
	v_mov_b32_dpp v86, v93 row_shr:2 row_mask:0xf bank_mask:0xf
	v_pk_fma_f32 v[74:75], v[74:75], v[122:123], v[94:95]
	s_nop 0
	v_pk_fma_f32 v[74:75], v[202:203], v[86:87], v[74:75]
	v_add_f32_e32 v87, 1.0, v149
	v_pk_add_f32 v[74:75], v[204:205], v[74:75]
	v_rcp_f32_e32 v87, v87
	v_mul_f32_e32 v86, 0xbfb8aa3b, v75
	v_exp_f32_e32 v86, v86
	v_mul_f32_e32 v83, v83, v87
	v_mul_f32_e32 v82, v82, v83
	v_add_f32_e32 v86, 1.0, v86
	v_rcp_f32_e32 v86, v86
	s_nop 0
	v_mul_f32_e32 v75, v75, v86
	v_mul_f32_e32 v74, v74, v75
	v_cvt_pk_bf16_f32 v179, v82, v74
	v_mad_i64_i32 v[74:75], s[64:65], v151, s93, v[90:91]
	v_lshl_add_u64 v[82:83], v[74:75], 0, v[174:175]
	v_mov_b32_e32 v246, v178
	v_mov_b32_e32 v247, v179
	v_mov_b32_dpp v75, v88 row_ror:1 row_mask:0xf bank_mask:0xf bound_ctrl:1
	v_mov_b32_dpp v74, v92 row_ror:1 row_mask:0xf bank_mask:0xf bound_ctrl:1
	v_mov_b32_dpp v87, v88 row_ror:2 row_mask:0xf bank_mask:0xf bound_ctrl:1
	v_mov_b32_dpp v75, v70 row_shr:1 row_mask:0xf bank_mask:0xf
	v_mov_b32_dpp v74, v66 row_shr:1 row_mask:0xf bank_mask:0xf
	v_mov_b32_dpp v86, v92 row_ror:2 row_mask:0xf bank_mask:0xf bound_ctrl:1
	v_mov_b32_e32 v94, v66
	v_mov_b32_e32 v95, v70
	v_pk_mul_f32 v[74:75], v[120:121], v[74:75]
	v_mov_b32_dpp v87, v70 row_shr:2 row_mask:0xf bank_mask:0xf
	v_mov_b32_dpp v86, v66 row_shr:2 row_mask:0xf bank_mask:0xf
	v_pk_fma_f32 v[74:75], v[94:95], v[118:119], v[74:75]
	v_mov_b32_dpp v88, v93 row_ror:2 row_mask:0xf bank_mask:0xf bound_ctrl:1
	v_pk_fma_f32 v[74:75], v[124:125], v[86:87], v[74:75]
	v_mov_b32_dpp v87, v89 row_ror:1 row_mask:0xf bank_mask:0xf bound_ctrl:1
	v_pk_add_f32 v[74:75], v[200:201], v[74:75]
	v_mov_b32_dpp v89, v89 row_ror:2 row_mask:0xf bank_mask:0xf bound_ctrl:1
	v_mul_f32_e32 v86, 0xbfb8aa3b, v75
	v_exp_f32_e32 v94, v86
	v_mov_b32_dpp v87, v71 row_shr:1 row_mask:0xf bank_mask:0xf
	v_mov_b32_dpp v86, v93 row_ror:1 row_mask:0xf bank_mask:0xf bound_ctrl:1
	v_mov_b32_e32 v92, v67
	v_mov_b32_e32 v93, v71
	v_mov_b32_dpp v86, v67 row_shr:1 row_mask:0xf bank_mask:0xf
	v_pk_mul_f32 v[86:87], v[126:127], v[86:87]
	v_mov_b32_dpp v89, v71 row_shr:2 row_mask:0xf bank_mask:0xf
	v_mov_b32_dpp v88, v67 row_shr:2 row_mask:0xf bank_mask:0xf
	v_pk_fma_f32 v[86:87], v[92:93], v[122:123], v[86:87]
	v_and_b32_e32 v122, 0x1fff, v153
	v_pk_fma_f32 v[86:87], v[202:203], v[88:89], v[86:87]
	v_add_f32_e32 v89, 1.0, v94
	v_pk_add_f32 v[86:87], v[204:205], v[86:87]
	v_rcp_f32_e32 v89, v89
	v_mul_f32_e32 v88, 0xbfb8aa3b, v87
	v_exp_f32_e32 v88, v88
	v_mul_f32_e32 v75, v75, v89
	v_mul_f32_e32 v74, v74, v75
	v_add_f32_e32 v88, 1.0, v88
	v_rcp_f32_e32 v88, v88
	s_nop 0
	v_mul_f32_e32 v75, v87, v88
	v_mul_f32_e32 v75, v86, v75
	v_cvt_pk_bf16_f32 v181, v74, v75
	v_mad_i64_i32 v[74:75], s[64:65], v153, s93, v[90:91]
	v_lshl_add_u64 v[86:87], v[74:75], 0, v[174:175]
	v_lshl_add_u64 v[74:75], v[134:135], 0, s[62:63]
	v_lshl_add_u64 v[74:75], v[146:147], 2, v[74:75]
	v_mov_b32_e32 v248, v180
	v_mov_b32_e32 v249, v181
	s_and_saveexec_b64 s[62:63], s[4:5]
	s_cbranch_execz .LBB0_505
	v_add_co_u32_e32 v88, vcc, 0x2000, v74
	global_store_dwordx4 v[74:75], v[68:71], off
	s_nop 0
	v_addc_co_u32_e32 v89, vcc, 0, v75, vcc
	v_cmp_lt_u32_e32 vcc, s94, v122
	global_store_dwordx4 v[88:89], v[64:67], off offset:3072
	s_and_b64 exec, exec, vcc
	s_cbranch_execz .LBB0_505
	v_add_u32_e32 v88, s57, v122
	v_mul_hi_i32_i24_e32 v89, 0x5800, v88
	v_mul_i32_i24_e32 v88, 0x5800, v88
	v_lshl_add_u64 v[88:89], s[18:19], 0, v[88:89]
	v_lshl_add_u64 v[88:89], v[146:147], 2, v[88:89]
	global_store_dwordx4 v[88:89], v[68:71], off
	s_nop 1
	v_add_co_u32_e32 v68, vcc, 0x2000, v88
	s_nop 1
	v_addc_co_u32_e32 v69, vcc, 0, v89, vcc
	global_store_dwordx4 v[68:69], v[64:67], off offset:3072
.LBB0_505:
	s_or_b64 exec, exec, s[62:63]
	v_mov_b32_e32 v169, v168
	v_mov_b32_e32 v163, v162
	v_mov_b32_e32 v161, v160
	v_mov_b32_e32 v159, v158
	v_mov_b32_e32 v155, v154
	v_mov_b32_e32 v153, v152
	v_mov_b32_e32 v151, v150
	v_mov_b32_e32 v149, v148
	v_mov_b32_e32 v64, v168
	v_mov_b32_e32 v65, v168
	v_pk_mul_f32 v[62:63], v[62:63], v[64:65]
	v_pk_mul_f32 v[60:61], v[60:61], v[168:169]
	v_pk_mul_f32 v[58:59], v[58:59], v[64:65]
	v_pk_mul_f32 v[56:57], v[56:57], v[168:169]
	v_pk_mul_f32 v[52:53], v[52:53], v[162:163]
	v_pk_mul_f32 v[64:65], v[44:45], v[162:163]
	v_pk_mul_f32 v[48:49], v[48:49], v[160:161]
	v_pk_mul_f32 v[44:45], v[36:37], v[160:161]
	v_pk_mul_f32 v[36:37], v[40:41], v[158:159]
	v_pk_mul_f32 v[32:33], v[32:33], v[158:159]
	v_pk_mul_f32 v[28:29], v[28:29], v[154:155]
	v_pk_mul_f32 v[24:25], v[24:25], v[154:155]
	v_pk_mul_f32 v[120:121], v[20:21], v[152:153]
	v_pk_mul_f32 v[12:13], v[12:13], v[152:153]
	v_pk_mul_f32 v[20:21], v[4:5], v[150:151]
	v_pk_mul_f32 v[4:5], v[8:9], v[148:149]
	v_pk_mul_f32 v[0:1], v[0:1], v[148:149]
	v_pk_mul_f32 v[118:119], v[16:17], v[150:151]
	s_waitcnt vmcnt(5)
	v_mul_f32_dpp v16, v60, v116 row_shr:1 row_mask:0xf bank_mask:0xf bound_ctrl:1
	v_mov_b32_dpp v9, v60 row_shr:2 row_mask:0xf bank_mask:0xf bound_ctrl:1
	s_waitcnt vmcnt(4)
	v_fmac_f32_e32 v16, v60, v114
	v_fmac_f32_e32 v16, v100, v9
	v_add_f32_e32 v16, v112, v16
	v_mul_f32_e32 v9, 0xbfb8aa3b, v16
	v_exp_f32_e32 v17, v9
	s_waitcnt vmcnt(2)
	v_mul_f32_dpp v41, v56, v110 row_shr:1 row_mask:0xf bank_mask:0xf bound_ctrl:1
	v_mov_b32_dpp v40, v56 row_shr:2 row_mask:0xf bank_mask:0xf bound_ctrl:1
	s_waitcnt vmcnt(1)
	v_fmac_f32_e32 v41, v56, v102
	v_add_f32_e32 v17, 1.0, v17
	v_rcp_f32_e32 v17, v17
	v_fmac_f32_e32 v41, v98, v40
	s_waitcnt vmcnt(0)
	v_add_f32_e32 v40, v108, v41
	v_mul_f32_dpp v66, v57, v111 row_shr:1 row_mask:0xf bank_mask:0xf bound_ctrl:1
	v_mul_f32_dpp v41, v61, v117 row_shr:1 row_mask:0xf bank_mask:0xf bound_ctrl:1
	v_mul_f32_e32 v16, v16, v17
	v_mov_b32_dpp v17, v61 row_shr:2 row_mask:0xf bank_mask:0xf bound_ctrl:1
	v_fmac_f32_e32 v41, v61, v115
	v_fmac_f32_e32 v41, v101, v17
	v_add_f32_e32 v17, v113, v41
	v_mul_f32_e32 v41, 0xbfb8aa3b, v17
	v_exp_f32_e32 v41, v41
	v_mul_f32_e32 v16, v40, v16
	v_mov_b32_dpp v40, v57 row_shr:2 row_mask:0xf bank_mask:0xf bound_ctrl:1
	v_fmac_f32_e32 v66, v57, v103
	v_add_f32_e32 v41, 1.0, v41
	v_rcp_f32_e32 v41, v41
	v_fmac_f32_e32 v66, v99, v40
	v_add_f32_e32 v40, v109, v66
	v_or_b32_e32 v8, 18, v146
	v_mul_f32_e32 v17, v17, v41
	v_mul_f32_e32 v17, v40, v17
	v_cvt_pk_bf16_f32 v94, v16, v17
	v_ashrrev_i32_e32 v9, 31, v8
	v_mov_b32_dpp v16, v60 row_ror:1 row_mask:0xf bank_mask:0xf bound_ctrl:1
	v_mov_b32_dpp v17, v60 row_ror:2 row_mask:0xf bank_mask:0xf bound_ctrl:1
	v_mov_b32_dpp v40, v56 row_ror:1 row_mask:0xf bank_mask:0xf bound_ctrl:1
	v_mov_b32_dpp v16, v52 row_shr:1 row_mask:0xf bank_mask:0xf
	v_mul_f32_e32 v16, v116, v16
	v_mov_b32_dpp v17, v52 row_shr:2 row_mask:0xf bank_mask:0xf
	v_fmac_f32_e32 v16, v52, v114
	v_fmac_f32_e32 v16, v100, v17
	v_add_f32_e32 v16, v112, v16
	v_mul_f32_e32 v17, 0xbfb8aa3b, v16
	v_exp_f32_e32 v17, v17
	v_mov_b32_dpp v40, v64 row_shr:1 row_mask:0xf bank_mask:0xf
	v_mov_b32_dpp v41, v56 row_ror:2 row_mask:0xf bank_mask:0xf bound_ctrl:1
	v_mul_f32_e32 v40, v110, v40
	v_add_f32_e32 v17, 1.0, v17
	v_rcp_f32_e32 v17, v17
	v_mov_b32_dpp v41, v64 row_shr:2 row_mask:0xf bank_mask:0xf
	v_fmac_f32_e32 v40, v64, v102
	v_fmac_f32_e32 v40, v98, v41
	v_mul_f32_e32 v16, v16, v17
	v_mov_b32_dpp v17, v61 row_ror:1 row_mask:0xf bank_mask:0xf bound_ctrl:1
	v_add_f32_e32 v40, v108, v40
	v_mul_f32_e32 v16, v40, v16
	v_mov_b32_dpp v17, v53 row_shr:1 row_mask:0xf bank_mask:0xf
	v_mov_b32_dpp v40, v61 row_ror:2 row_mask:0xf bank_mask:0xf bound_ctrl:1
	v_mul_f32_e32 v17, v117, v17
	v_fmac_f32_e32 v17, v53, v115
	v_mov_b32_dpp v40, v53 row_shr:2 row_mask:0xf bank_mask:0xf
	v_fmac_f32_e32 v17, v101, v40
	v_add_f32_e32 v17, v113, v17
	v_mul_f32_e32 v40, 0xbfb8aa3b, v17
	v_exp_f32_e32 v40, v40
	v_mov_b32_dpp v41, v57 row_ror:1 row_mask:0xf bank_mask:0xf bound_ctrl:1
	v_mov_b32_dpp v66, v57 row_ror:2 row_mask:0xf bank_mask:0xf bound_ctrl:1
	v_add_f32_e32 v40, 1.0, v40
	v_mov_b32_dpp v41, v65 row_shr:1 row_mask:0xf bank_mask:0xf
	v_rcp_f32_e32 v40, v40
	v_mul_f32_e32 v41, v111, v41
	v_mov_b32_dpp v66, v65 row_shr:2 row_mask:0xf bank_mask:0xf
	v_fmac_f32_e32 v41, v65, v103
	v_fmac_f32_e32 v41, v99, v66
	v_add_f32_e32 v41, v109, v41
	v_mul_f32_e32 v17, v17, v40
	v_mul_f32_e32 v17, v41, v17
	v_cvt_pk_bf16_f32 v88, v16, v17
	v_mov_b32_dpp v16, v52 row_ror:1 row_mask:0xf bank_mask:0xf bound_ctrl:1
	s_nop 0
	v_mov_b32_dpp v17, v52 row_ror:2 row_mask:0xf bank_mask:0xf bound_ctrl:1
	v_mov_b32_dpp v40, v64 row_ror:1 row_mask:0xf bank_mask:0xf bound_ctrl:1
	v_mov_b32_dpp v16, v48 row_shr:1 row_mask:0xf bank_mask:0xf
	v_mul_f32_e32 v16, v116, v16
	v_mov_b32_dpp v17, v48 row_shr:2 row_mask:0xf bank_mask:0xf
	v_fmac_f32_e32 v16, v48, v114
	v_fmac_f32_e32 v16, v100, v17
	v_add_f32_e32 v16, v112, v16
	v_mul_f32_e32 v17, 0xbfb8aa3b, v16
	v_exp_f32_e32 v17, v17
	v_mov_b32_dpp v40, v44 row_shr:1 row_mask:0xf bank_mask:0xf
	v_mov_b32_dpp v41, v64 row_ror:2 row_mask:0xf bank_mask:0xf bound_ctrl:1
	v_mul_f32_e32 v40, v110, v40
	v_add_f32_e32 v17, 1.0, v17
	v_rcp_f32_e32 v17, v17
	v_mov_b32_dpp v41, v44 row_shr:2 row_mask:0xf bank_mask:0xf
	v_fmac_f32_e32 v40, v44, v102
	v_fmac_f32_e32 v40, v98, v41
	v_mul_f32_e32 v16, v16, v17
	v_mov_b32_dpp v17, v53 row_ror:1 row_mask:0xf bank_mask:0xf bound_ctrl:1
	v_add_f32_e32 v40, v108, v40
	v_mul_f32_e32 v16, v40, v16
	v_mov_b32_dpp v17, v49 row_shr:1 row_mask:0xf bank_mask:0xf
	v_mov_b32_dpp v40, v53 row_ror:2 row_mask:0xf bank_mask:0xf bound_ctrl:1
	v_mul_f32_e32 v17, v117, v17
	v_fmac_f32_e32 v17, v49, v115
	v_mov_b32_dpp v40, v49 row_shr:2 row_mask:0xf bank_mask:0xf
	v_fmac_f32_e32 v17, v101, v40
	v_add_f32_e32 v17, v113, v17
	v_mul_f32_e32 v40, 0xbfb8aa3b, v17
	v_exp_f32_e32 v40, v40
	v_mov_b32_dpp v41, v65 row_ror:1 row_mask:0xf bank_mask:0xf bound_ctrl:1
	v_mov_b32_dpp v52, v65 row_ror:2 row_mask:0xf bank_mask:0xf bound_ctrl:1
	v_add_f32_e32 v40, 1.0, v40
	v_mov_b32_dpp v41, v45 row_shr:1 row_mask:0xf bank_mask:0xf
	v_rcp_f32_e32 v40, v40
	v_mul_f32_e32 v41, v111, v41
	v_mov_b32_dpp v52, v45 row_shr:2 row_mask:0xf bank_mask:0xf
	v_fmac_f32_e32 v41, v45, v103
	v_fmac_f32_e32 v41, v99, v52
	v_add_f32_e32 v41, v109, v41
	v_mul_f32_e32 v17, v17, v40
	v_mul_f32_e32 v17, v41, v17
	v_cvt_pk_bf16_f32 v90, v16, v17
	v_mov_b32_dpp v16, v48 row_ror:1 row_mask:0xf bank_mask:0xf bound_ctrl:1
	s_nop 0
	v_mov_b32_dpp v17, v48 row_ror:2 row_mask:0xf bank_mask:0xf bound_ctrl:1
	v_mov_b32_dpp v40, v44 row_ror:1 row_mask:0xf bank_mask:0xf bound_ctrl:1
	v_mov_b32_dpp v16, v36 row_shr:1 row_mask:0xf bank_mask:0xf
	v_mul_f32_e32 v16, v116, v16
	v_mov_b32_dpp v17, v36 row_shr:2 row_mask:0xf bank_mask:0xf
	v_fmac_f32_e32 v16, v36, v114
	v_fmac_f32_e32 v16, v100, v17
	v_add_f32_e32 v16, v112, v16
	v_mul_f32_e32 v17, 0xbfb8aa3b, v16
	v_exp_f32_e32 v17, v17
	v_mov_b32_dpp v40, v32 row_shr:1 row_mask:0xf bank_mask:0xf
	v_mov_b32_dpp v41, v44 row_ror:2 row_mask:0xf bank_mask:0xf bound_ctrl:1
	v_mul_f32_e32 v40, v110, v40
	v_add_f32_e32 v17, 1.0, v17
	v_rcp_f32_e32 v17, v17
	v_mov_b32_dpp v41, v32 row_shr:2 row_mask:0xf bank_mask:0xf
	v_fmac_f32_e32 v40, v32, v102
	v_fmac_f32_e32 v40, v98, v41
	v_mul_f32_e32 v16, v16, v17
	v_mov_b32_dpp v17, v49 row_ror:1 row_mask:0xf bank_mask:0xf bound_ctrl:1
	v_add_f32_e32 v40, v108, v40
	v_mul_f32_e32 v16, v40, v16
	v_mov_b32_dpp v17, v37 row_shr:1 row_mask:0xf bank_mask:0xf
	v_mov_b32_dpp v40, v49 row_ror:2 row_mask:0xf bank_mask:0xf bound_ctrl:1
	v_mul_f32_e32 v17, v117, v17
	v_fmac_f32_e32 v17, v37, v115
	v_mov_b32_dpp v40, v37 row_shr:2 row_mask:0xf bank_mask:0xf
	v_fmac_f32_e32 v17, v101, v40
	v_add_f32_e32 v17, v113, v17
	v_mul_f32_e32 v40, 0xbfb8aa3b, v17
	v_exp_f32_e32 v40, v40
	v_mov_b32_dpp v41, v45 row_ror:1 row_mask:0xf bank_mask:0xf bound_ctrl:1
	v_mov_b32_dpp v44, v45 row_ror:2 row_mask:0xf bank_mask:0xf bound_ctrl:1
	v_add_f32_e32 v40, 1.0, v40
	v_mov_b32_dpp v41, v33 row_shr:1 row_mask:0xf bank_mask:0xf
	v_rcp_f32_e32 v40, v40
	v_mul_f32_e32 v41, v111, v41
	v_mov_b32_dpp v44, v33 row_shr:2 row_mask:0xf bank_mask:0xf
	v_fmac_f32_e32 v41, v33, v103
	v_fmac_f32_e32 v41, v99, v44
	v_add_f32_e32 v41, v109, v41
	v_mul_f32_e32 v17, v17, v40
	v_mul_f32_e32 v17, v41, v17
	v_cvt_pk_bf16_f32 v92, v16, v17
	v_lshlrev_b64 v[8:9], 2, v[8:9]
	v_lshl_add_u64 v[16:17], s[16:17], 0, v[8:9]
	v_lshl_add_u64 v[52:53], s[28:29], 0, v[8:9]
	global_load_dwordx2 v[40:41], v[164:165], off offset:72
	v_lshl_add_u64 v[44:45], s[24:25], 0, v[8:9]
	global_load_dwordx2 v[64:65], v[166:167], off offset:72
	v_lshl_add_u64 v[48:49], s[26:27], 0, v[8:9]
	global_load_dwordx2 v[68:69], v[16:17], off
	global_load_dwordx2 v[66:67], v[44:45], off
	s_nop 0
	global_load_dwordx2 v[16:17], v[48:49], off
	s_nop 0
	global_load_dwordx2 v[52:53], v[52:53], off
	v_lshl_add_u64 v[44:45], s[30:31], 0, v[8:9]
	v_lshl_add_u64 v[8:9], s[52:53], 0, v[8:9]
	global_load_dwordx2 v[44:45], v[44:45], off
	v_mul_f32_dpp v71, v24, v110 row_shr:1 row_mask:0xf bank_mask:0xf bound_ctrl:1
	global_load_dwordx2 v[48:49], v[8:9], off
	v_mul_f32_dpp v9, v28, v116 row_shr:1 row_mask:0xf bank_mask:0xf bound_ctrl:1
	v_mov_b32_dpp v8, v28 row_shr:2 row_mask:0xf bank_mask:0xf bound_ctrl:1
	v_fmac_f32_e32 v9, v28, v114
	v_fmac_f32_e32 v9, v100, v8
	v_add_f32_e32 v8, v112, v9
	v_mul_f32_e32 v9, 0xbfb8aa3b, v8
	v_exp_f32_e32 v9, v9
	v_mov_b32_dpp v70, v24 row_shr:2 row_mask:0xf bank_mask:0xf bound_ctrl:1
	v_fmac_f32_e32 v71, v24, v102
	v_fmac_f32_e32 v71, v98, v70
	v_add_f32_e32 v9, 1.0, v9
	v_rcp_f32_e32 v9, v9
	v_add_f32_e32 v70, v108, v71
	v_mul_f32_dpp v71, v29, v117 row_shr:1 row_mask:0xf bank_mask:0xf bound_ctrl:1
	v_fmac_f32_e32 v71, v29, v115
	v_mul_f32_e32 v8, v8, v9
	v_mov_b32_dpp v9, v29 row_shr:2 row_mask:0xf bank_mask:0xf bound_ctrl:1
	v_fmac_f32_e32 v71, v101, v9
	v_add_f32_e32 v9, v113, v71
	v_mul_f32_e32 v71, 0xbfb8aa3b, v9
	v_exp_f32_e32 v71, v71
	v_mul_f32_dpp v89, v25, v111 row_shr:1 row_mask:0xf bank_mask:0xf bound_ctrl:1
	v_mul_f32_e32 v8, v70, v8
	v_mov_b32_dpp v70, v25 row_shr:2 row_mask:0xf bank_mask:0xf bound_ctrl:1
	v_add_f32_e32 v71, 1.0, v71
	v_rcp_f32_e32 v71, v71
	v_fmac_f32_e32 v89, v25, v103
	v_fmac_f32_e32 v89, v99, v70
	v_add_f32_e32 v70, v109, v89
	v_mul_f32_e32 v9, v9, v71
	v_mul_f32_e32 v9, v70, v9
	v_cvt_pk_bf16_f32 v70, v8, v9
	v_mov_b32_dpp v8, v28 row_ror:1 row_mask:0xf bank_mask:0xf bound_ctrl:1
	s_nop 0
	v_mov_b32_dpp v9, v28 row_ror:2 row_mask:0xf bank_mask:0xf bound_ctrl:1
	v_mov_b32_dpp v71, v24 row_ror:1 row_mask:0xf bank_mask:0xf bound_ctrl:1
	v_mov_b32_dpp v8, v120 row_shr:1 row_mask:0xf bank_mask:0xf
	v_mul_f32_e32 v8, v116, v8
	v_mov_b32_dpp v9, v120 row_shr:2 row_mask:0xf bank_mask:0xf
	v_fmac_f32_e32 v8, v120, v114
	v_fmac_f32_e32 v8, v100, v9
	v_add_f32_e32 v8, v112, v8
	v_mul_f32_e32 v9, 0xbfb8aa3b, v8
	v_exp_f32_e32 v9, v9
	v_mov_b32_dpp v71, v12 row_shr:1 row_mask:0xf bank_mask:0xf
	v_mov_b32_dpp v89, v24 row_ror:2 row_mask:0xf bank_mask:0xf bound_ctrl:1
	v_mul_f32_e32 v71, v110, v71
	v_add_f32_e32 v9, 1.0, v9
	v_rcp_f32_e32 v9, v9
	v_mov_b32_dpp v89, v12 row_shr:2 row_mask:0xf bank_mask:0xf
	v_fmac_f32_e32 v71, v12, v102
	v_fmac_f32_e32 v71, v98, v89
	v_mul_f32_e32 v8, v8, v9
	v_mov_b32_dpp v9, v29 row_ror:1 row_mask:0xf bank_mask:0xf bound_ctrl:1
	v_add_f32_e32 v71, v108, v71
	v_mul_f32_e32 v8, v71, v8
	v_mov_b32_dpp v9, v121 row_shr:1 row_mask:0xf bank_mask:0xf
	v_mov_b32_dpp v71, v29 row_ror:2 row_mask:0xf bank_mask:0xf bound_ctrl:1
	v_mul_f32_e32 v9, v117, v9
	v_fmac_f32_e32 v9, v121, v115
	v_mov_b32_dpp v71, v121 row_shr:2 row_mask:0xf bank_mask:0xf
	v_fmac_f32_e32 v9, v101, v71
	v_add_f32_e32 v9, v113, v9
	v_mul_f32_e32 v71, 0xbfb8aa3b, v9
	v_exp_f32_e32 v71, v71
	v_mov_b32_dpp v89, v25 row_ror:1 row_mask:0xf bank_mask:0xf bound_ctrl:1
	v_mov_b32_dpp v91, v25 row_ror:2 row_mask:0xf bank_mask:0xf bound_ctrl:1
	v_add_f32_e32 v71, 1.0, v71
	v_mov_b32_dpp v89, v13 row_shr:1 row_mask:0xf bank_mask:0xf
	v_rcp_f32_e32 v71, v71
	v_mul_f32_e32 v89, v111, v89
	v_mov_b32_dpp v91, v13 row_shr:2 row_mask:0xf bank_mask:0xf
	v_fmac_f32_e32 v89, v13, v103
	v_fmac_f32_e32 v89, v99, v91
	v_add_f32_e32 v89, v109, v89
	v_mul_f32_e32 v9, v9, v71
	v_mul_f32_e32 v9, v89, v9
	v_cvt_pk_bf16_f32 v8, v8, v9
	s_nop 1
	v_mov_b32_dpp v9, v120 row_ror:1 row_mask:0xf bank_mask:0xf bound_ctrl:1
	v_mov_b32_dpp v71, v120 row_ror:2 row_mask:0xf bank_mask:0xf bound_ctrl:1
	v_mov_b32_dpp v89, v12 row_ror:1 row_mask:0xf bank_mask:0xf bound_ctrl:1
	v_mov_b32_dpp v9, v118 row_shr:1 row_mask:0xf bank_mask:0xf
	v_mul_f32_e32 v9, v116, v9
	v_mov_b32_dpp v71, v118 row_shr:2 row_mask:0xf bank_mask:0xf
	v_fmac_f32_e32 v9, v118, v114
	v_fmac_f32_e32 v9, v100, v71
	v_add_f32_e32 v9, v112, v9
	v_mul_f32_e32 v71, 0xbfb8aa3b, v9
	v_exp_f32_e32 v71, v71
	v_mov_b32_dpp v89, v20 row_shr:1 row_mask:0xf bank_mask:0xf
	v_mov_b32_dpp v12, v12 row_ror:2 row_mask:0xf bank_mask:0xf bound_ctrl:1
	v_mul_f32_e32 v89, v110, v89
	v_add_f32_e32 v71, 1.0, v71
	v_rcp_f32_e32 v71, v71
	v_mov_b32_dpp v12, v20 row_shr:2 row_mask:0xf bank_mask:0xf
	v_fmac_f32_e32 v89, v20, v102
	v_fmac_f32_e32 v89, v98, v12
	v_add_f32_e32 v12, v108, v89
	v_mul_f32_e32 v9, v9, v71
	v_mul_f32_e32 v9, v12, v9
	v_mov_b32_dpp v12, v121 row_ror:1 row_mask:0xf bank_mask:0xf bound_ctrl:1
	v_mov_b32_dpp v71, v121 row_ror:2 row_mask:0xf bank_mask:0xf bound_ctrl:1
	v_mov_b32_dpp v89, v13 row_ror:1 row_mask:0xf bank_mask:0xf bound_ctrl:1
	v_mov_b32_dpp v12, v119 row_shr:1 row_mask:0xf bank_mask:0xf
	v_mul_f32_e32 v12, v117, v12
	v_mov_b32_dpp v71, v119 row_shr:2 row_mask:0xf bank_mask:0xf
	v_fmac_f32_e32 v12, v119, v115
	v_fmac_f32_e32 v12, v101, v71
	v_add_f32_e32 v12, v113, v12
	v_mul_f32_e32 v71, 0xbfb8aa3b, v12
	v_exp_f32_e32 v71, v71
	v_mov_b32_dpp v89, v21 row_shr:1 row_mask:0xf bank_mask:0xf
	v_mov_b32_dpp v13, v13 row_ror:2 row_mask:0xf bank_mask:0xf bound_ctrl:1
	v_mul_f32_e32 v89, v111, v89
	v_add_f32_e32 v71, 1.0, v71
	v_rcp_f32_e32 v71, v71
	v_mov_b32_dpp v13, v21 row_shr:2 row_mask:0xf bank_mask:0xf
	v_fmac_f32_e32 v89, v21, v103
	v_fmac_f32_e32 v89, v99, v13
	v_add_f32_e32 v13, v109, v89
	v_mul_f32_e32 v12, v12, v71
	v_mul_f32_e32 v12, v13, v12
	v_cvt_pk_bf16_f32 v12, v9, v12
	v_mov_b32_dpp v9, v118 row_ror:1 row_mask:0xf bank_mask:0xf bound_ctrl:1
	v_mov_b32_dpp v13, v118 row_ror:2 row_mask:0xf bank_mask:0xf bound_ctrl:1
	v_mov_b32_dpp v71, v20 row_ror:1 row_mask:0xf bank_mask:0xf bound_ctrl:1
	v_mov_b32_dpp v9, v4 row_shr:1 row_mask:0xf bank_mask:0xf
	v_mul_f32_e32 v9, v116, v9
	v_mov_b32_dpp v13, v4 row_shr:2 row_mask:0xf bank_mask:0xf
	v_fmac_f32_e32 v9, v4, v114
	v_fmac_f32_e32 v9, v100, v13
	v_add_f32_e32 v9, v112, v9
	v_mul_f32_e32 v13, 0xbfb8aa3b, v9
	v_exp_f32_e32 v13, v13
	v_mov_b32_dpp v71, v0 row_shr:1 row_mask:0xf bank_mask:0xf
	v_mov_b32_dpp v20, v20 row_ror:2 row_mask:0xf bank_mask:0xf bound_ctrl:1
	v_mul_f32_e32 v71, v110, v71
	v_add_f32_e32 v13, 1.0, v13
	v_rcp_f32_e32 v13, v13
	v_mov_b32_dpp v20, v0 row_shr:2 row_mask:0xf bank_mask:0xf
	v_fmac_f32_e32 v71, v0, v102
	v_fmac_f32_e32 v71, v98, v20
	v_mul_f32_e32 v9, v9, v13
	v_mov_b32_dpp v13, v119 row_ror:1 row_mask:0xf bank_mask:0xf bound_ctrl:1
	v_add_f32_e32 v20, v108, v71
	v_mul_f32_e32 v9, v20, v9
	v_mov_b32_dpp v13, v5 row_shr:1 row_mask:0xf bank_mask:0xf
	v_mov_b32_dpp v20, v119 row_ror:2 row_mask:0xf bank_mask:0xf bound_ctrl:1
	v_mul_f32_e32 v13, v117, v13
	v_fmac_f32_e32 v13, v5, v115
	v_mov_b32_dpp v20, v5 row_shr:2 row_mask:0xf bank_mask:0xf
	v_fmac_f32_e32 v13, v101, v20
	v_add_f32_e32 v13, v113, v13
	v_mul_f32_e32 v20, 0xbfb8aa3b, v13
	v_exp_f32_e32 v20, v20
	v_mov_b32_dpp v71, v21 row_ror:1 row_mask:0xf bank_mask:0xf bound_ctrl:1
	v_mov_b32_dpp v21, v21 row_ror:2 row_mask:0xf bank_mask:0xf bound_ctrl:1
	v_add_f32_e32 v20, 1.0, v20
	v_mov_b32_dpp v71, v1 row_shr:1 row_mask:0xf bank_mask:0xf
	v_rcp_f32_e32 v20, v20
	v_mul_f32_e32 v71, v111, v71
	v_mov_b32_dpp v21, v1 row_shr:2 row_mask:0xf bank_mask:0xf
	v_fmac_f32_e32 v71, v1, v103
	v_fmac_f32_e32 v71, v99, v21
	v_add_f32_e32 v21, v109, v71
	v_mul_f32_e32 v13, v13, v20
	v_mul_f32_e32 v13, v21, v13
	v_cvt_pk_bf16_f32 v20, v9, v13
	s_waitcnt vmcnt(5)
	s_nop 0
	v_mul_f32_dpp v13, v62, v68 row_shr:1 row_mask:0xf bank_mask:0xf bound_ctrl:1
	v_mov_b32_dpp v9, v62 row_shr:2 row_mask:0xf bank_mask:0xf bound_ctrl:1
	s_waitcnt vmcnt(4)
	v_fmac_f32_e32 v13, v62, v66
	v_fmac_f32_e32 v13, v40, v9
	v_add_f32_e32 v9, v64, v13
	v_mul_f32_e32 v13, 0xbfb8aa3b, v9
	v_exp_f32_e32 v13, v13
	s_waitcnt vmcnt(2)
	v_mul_f32_dpp v71, v58, v52 row_shr:1 row_mask:0xf bank_mask:0xf bound_ctrl:1
	v_mov_b32_dpp v21, v58 row_shr:2 row_mask:0xf bank_mask:0xf bound_ctrl:1
	s_waitcnt vmcnt(1)
	v_fmac_f32_e32 v71, v58, v44
	v_add_f32_e32 v13, 1.0, v13
	v_rcp_f32_e32 v13, v13
	v_fmac_f32_e32 v71, v16, v21
	s_waitcnt vmcnt(0)
	v_add_f32_e32 v21, v48, v71
	v_mul_f32_dpp v89, v59, v53 row_shr:1 row_mask:0xf bank_mask:0xf bound_ctrl:1
	v_mul_f32_dpp v71, v63, v69 row_shr:1 row_mask:0xf bank_mask:0xf bound_ctrl:1
	v_mul_f32_e32 v9, v9, v13
	v_mov_b32_dpp v13, v63 row_shr:2 row_mask:0xf bank_mask:0xf bound_ctrl:1
	v_fmac_f32_e32 v71, v63, v67
	v_fmac_f32_e32 v71, v41, v13
	v_add_f32_e32 v13, v65, v71
	v_mul_f32_e32 v71, 0xbfb8aa3b, v13
	v_exp_f32_e32 v71, v71
	v_mul_f32_e32 v9, v21, v9
	v_mov_b32_dpp v21, v59 row_shr:2 row_mask:0xf bank_mask:0xf bound_ctrl:1
	v_fmac_f32_e32 v89, v59, v45
	v_add_f32_e32 v71, 1.0, v71
	v_rcp_f32_e32 v71, v71
	v_fmac_f32_e32 v89, v17, v21
	v_add_f32_e32 v21, v49, v89
	v_mul_f32_e32 v13, v13, v71
	v_mul_f32_e32 v13, v21, v13
	v_cvt_pk_bf16_f32 v95, v9, v13
	s_and_saveexec_b64 s[62:63], s[2:3]
	s_xor_b64 s[62:63], exec, s[62:63]
	s_cbranch_execz .LBB0_507
	v_mov_b64_e32 v[80:81], s[48:49]
	v_mad_i64_i32 v[80:81], s[64:65], v156, s93, v[80:81]
	v_lshl_add_u64 v[80:81], v[146:147], 1, v[80:81]
	global_store_dwordx2 v[80:81], v[94:95], off offset:32

.LBB0_509:
	s_or_b64 exec, exec, s[62:63]
	v_mov_b32_e32 v161, v160
	v_mov_b32_e32 v159, v158
	v_mov_b32_e32 v163, v162
	v_pk_mul_f32 v[100:101], v[38:39], v[160:161]
	v_pk_mul_f32 v[38:39], v[42:43], v[158:159]
	v_pk_mul_f32 v[34:35], v[34:35], v[158:159]
	v_pk_mul_f32 v[80:81], v[54:55], v[162:163]
	v_pk_mul_f32 v[94:95], v[46:47], v[162:163]
	v_pk_mul_f32 v[98:99], v[50:51], v[160:161]
	v_mov_b32_dpp v51, v62 row_ror:1 row_mask:0xf bank_mask:0xf bound_ctrl:1
	v_mov_b32_dpp v50, v58 row_ror:1 row_mask:0xf bank_mask:0xf bound_ctrl:1
	v_mov_b32_e32 v46, v52
	v_mov_b32_dpp v51, v80 row_shr:1 row_mask:0xf bank_mask:0xf
	v_mov_b32_dpp v50, v94 row_shr:1 row_mask:0xf bank_mask:0xf
	v_mov_b32_e32 v47, v68
	v_mov_b32_dpp v55, v62 row_ror:2 row_mask:0xf bank_mask:0xf bound_ctrl:1
	v_mov_b32_dpp v54, v58 row_ror:2 row_mask:0xf bank_mask:0xf bound_ctrl:1
	v_mov_b32_e32 v56, v94
	v_mov_b32_e32 v57, v80
	v_mov_b32_e32 v42, v44
	v_mov_b32_e32 v43, v66
	v_pk_mul_f32 v[50:51], v[46:47], v[50:51]
	v_mov_b32_dpp v55, v80 row_shr:2 row_mask:0xf bank_mask:0xf
	v_mov_b32_dpp v54, v94 row_shr:2 row_mask:0xf bank_mask:0xf
	v_pk_fma_f32 v[56:57], v[56:57], v[42:43], v[50:51]
	v_mov_b32_e32 v50, v16
	v_mov_b32_e32 v51, v40
	v_mov_b32_dpp v61, v63 row_ror:1 row_mask:0xf bank_mask:0xf bound_ctrl:1
	v_mov_b32_dpp v60, v59 row_ror:1 row_mask:0xf bank_mask:0xf bound_ctrl:1
	v_pk_fma_f32 v[56:57], v[50:51], v[54:55], v[56:57]
	v_mov_b32_e32 v54, v48
	v_mov_b32_e32 v55, v64
	v_mov_b32_dpp v61, v81 row_shr:1 row_mask:0xf bank_mask:0xf
	v_mov_b32_dpp v60, v95 row_shr:1 row_mask:0xf bank_mask:0xf
	v_mov_b32_dpp v62, v59 row_ror:2 row_mask:0xf bank_mask:0xf bound_ctrl:1
	v_mov_b32_e32 v58, v53
	v_mov_b32_e32 v59, v69
	v_pk_add_f32 v[102:103], v[54:55], v[56:57]
	v_mov_b32_dpp v63, v63 row_ror:2 row_mask:0xf bank_mask:0xf bound_ctrl:1
	v_mov_b32_e32 v108, v95
	v_mov_b32_e32 v109, v81
	v_mov_b32_e32 v56, v45
	v_mov_b32_e32 v57, v67
	v_pk_mul_f32 v[60:61], v[58:59], v[60:61]
	v_mov_b32_dpp v63, v81 row_shr:2 row_mask:0xf bank_mask:0xf
	v_mov_b32_dpp v62, v95 row_shr:2 row_mask:0xf bank_mask:0xf
	v_pk_fma_f32 v[108:109], v[108:109], v[56:57], v[60:61]
	v_mov_b32_e32 v60, v17
	v_mov_b32_e32 v61, v41
	v_pk_fma_f32 v[108:109], v[60:61], v[62:63], v[108:109]
	v_mov_b32_e32 v62, v49
	v_mov_b32_e32 v63, v65
	v_pk_add_f32 v[108:109], v[62:63], v[108:109]
	v_mul_f32_e32 v9, 0xbfb8aa3b, v103
	v_mul_f32_e32 v13, 0xbfb8aa3b, v109
	v_exp_f32_e32 v9, v9
	v_exp_f32_e32 v13, v13
	v_add_f32_e32 v9, 1.0, v9
	v_add_f32_e32 v13, 1.0, v13
	v_rcp_f32_e32 v9, v9
	v_rcp_f32_e32 v13, v13
	v_mul_f32_e32 v9, v103, v9
	v_mul_f32_e32 v13, v109, v13
	v_mul_f32_e32 v9, v102, v9
	v_mul_f32_e32 v13, v108, v13
	v_cvt_pk_bf16_f32 v89, v9, v13
	v_mov_b32_e32 v232, v230
	v_mov_b32_e32 v233, v231
	v_mov_b32_e32 v234, v88
	v_mov_b32_e32 v235, v89
	s_nop 1
	v_permlane16_swap_b32_e32 v232, v234
	v_permlane16_swap_b32_e32 v233, v235
	v_lshl_add_u64 v[236:237], v[84:85], 0, v[238:239]
	global_store_dwordx4 v[236:237], v[232:235], off
	s_nop 1
	v_mov_b32_dpp v85, v80 row_ror:1 row_mask:0xf bank_mask:0xf bound_ctrl:1
	v_mov_b32_dpp v84, v94 row_ror:1 row_mask:0xf bank_mask:0xf bound_ctrl:1
	v_mov_b32_dpp v89, v80 row_ror:2 row_mask:0xf bank_mask:0xf bound_ctrl:1
	v_mov_b32_dpp v85, v98 row_shr:1 row_mask:0xf bank_mask:0xf
	v_mov_b32_dpp v84, v100 row_shr:1 row_mask:0xf bank_mask:0xf
	v_mov_b32_dpp v88, v94 row_ror:2 row_mask:0xf bank_mask:0xf bound_ctrl:1
	v_mov_b32_e32 v102, v100
	v_mov_b32_e32 v103, v98
	v_pk_mul_f32 v[84:85], v[46:47], v[84:85]
	v_mov_b32_dpp v89, v98 row_shr:2 row_mask:0xf bank_mask:0xf
	v_mov_b32_dpp v88, v100 row_shr:2 row_mask:0xf bank_mask:0xf
	v_pk_fma_f32 v[84:85], v[102:103], v[42:43], v[84:85]
	v_mov_b32_dpp v80, v95 row_ror:2 row_mask:0xf bank_mask:0xf bound_ctrl:1
	v_pk_fma_f32 v[84:85], v[50:51], v[88:89], v[84:85]
	v_mov_b32_dpp v89, v81 row_ror:1 row_mask:0xf bank_mask:0xf bound_ctrl:1
	v_mov_b32_dpp v88, v95 row_ror:1 row_mask:0xf bank_mask:0xf bound_ctrl:1
	v_mov_b32_dpp v81, v81 row_ror:2 row_mask:0xf bank_mask:0xf bound_ctrl:1
	v_mov_b32_dpp v89, v99 row_shr:1 row_mask:0xf bank_mask:0xf
	v_mov_b32_dpp v88, v101 row_shr:1 row_mask:0xf bank_mask:0xf
	v_mov_b32_e32 v94, v101
	v_mov_b32_e32 v95, v99
	v_pk_mul_f32 v[88:89], v[58:59], v[88:89]
	v_mov_b32_dpp v81, v99 row_shr:2 row_mask:0xf bank_mask:0xf
	v_mov_b32_dpp v80, v101 row_shr:2 row_mask:0xf bank_mask:0xf
	v_pk_fma_f32 v[88:89], v[94:95], v[56:57], v[88:89]
	v_pk_add_f32 v[84:85], v[54:55], v[84:85]
	v_pk_fma_f32 v[80:81], v[60:61], v[80:81], v[88:89]
	v_mul_f32_e32 v9, 0xbfb8aa3b, v85
	v_pk_add_f32 v[80:81], v[62:63], v[80:81]
	v_exp_f32_e32 v9, v9
	v_mul_f32_e32 v13, 0xbfb8aa3b, v81
	v_exp_f32_e32 v13, v13
	v_add_f32_e32 v9, 1.0, v9
	v_rcp_f32_e32 v9, v9
	v_add_f32_e32 v13, 1.0, v13
	v_rcp_f32_e32 v13, v13
	v_mul_f32_e32 v9, v85, v9
	v_mul_f32_e32 v9, v84, v9
	v_mul_f32_e32 v13, v81, v13
	v_mul_f32_e32 v13, v80, v13
	v_cvt_pk_bf16_f32 v91, v9, v13
	v_mov_b32_e32 v232, v240
	v_mov_b32_e32 v233, v241
	v_mov_b32_e32 v234, v90
	v_mov_b32_e32 v235, v91
	s_nop 1
	v_permlane16_swap_b32_e32 v232, v234
	v_permlane16_swap_b32_e32 v233, v235
	v_lshl_add_u64 v[236:237], v[104:105], 0, v[238:239]
	global_store_dwordx4 v[236:237], v[232:235], off
	s_nop 1
	v_mov_b32_dpp v81, v98 row_ror:1 row_mask:0xf bank_mask:0xf bound_ctrl:1
	v_mov_b32_dpp v80, v100 row_ror:1 row_mask:0xf bank_mask:0xf bound_ctrl:1
	v_mov_b32_dpp v85, v98 row_ror:2 row_mask:0xf bank_mask:0xf bound_ctrl:1
	v_mov_b32_dpp v81, v38 row_shr:1 row_mask:0xf bank_mask:0xf
	v_mov_b32_dpp v80, v34 row_shr:1 row_mask:0xf bank_mask:0xf
	v_mov_b32_dpp v84, v100 row_ror:2 row_mask:0xf bank_mask:0xf bound_ctrl:1
	v_mov_b32_e32 v88, v34
	v_mov_b32_e32 v89, v38
	v_pk_mul_f32 v[80:81], v[46:47], v[80:81]
	v_mov_b32_dpp v85, v38 row_shr:2 row_mask:0xf bank_mask:0xf
	v_mov_b32_dpp v84, v34 row_shr:2 row_mask:0xf bank_mask:0xf
	v_pk_fma_f32 v[80:81], v[88:89], v[42:43], v[80:81]
	v_mov_b32_dpp v89, v99 row_ror:2 row_mask:0xf bank_mask:0xf bound_ctrl:1
	v_pk_fma_f32 v[80:81], v[50:51], v[84:85], v[80:81]
	v_mov_b32_dpp v85, v99 row_ror:1 row_mask:0xf bank_mask:0xf bound_ctrl:1
	v_mov_b32_dpp v84, v101 row_ror:1 row_mask:0xf bank_mask:0xf bound_ctrl:1
	v_mov_b32_dpp v88, v101 row_ror:2 row_mask:0xf bank_mask:0xf bound_ctrl:1
	v_mov_b32_dpp v85, v39 row_shr:1 row_mask:0xf bank_mask:0xf
	v_mov_b32_dpp v84, v35 row_shr:1 row_mask:0xf bank_mask:0xf
	v_mov_b32_e32 v90, v35
	v_mov_b32_e32 v91, v39
	v_pk_mul_f32 v[84:85], v[58:59], v[84:85]
	v_mov_b32_dpp v89, v39 row_shr:2 row_mask:0xf bank_mask:0xf
	v_mov_b32_dpp v88, v35 row_shr:2 row_mask:0xf bank_mask:0xf
	v_pk_fma_f32 v[84:85], v[90:91], v[56:57], v[84:85]
	v_pk_add_f32 v[80:81], v[54:55], v[80:81]
	v_pk_fma_f32 v[84:85], v[60:61], v[88:89], v[84:85]
	v_mul_f32_e32 v9, 0xbfb8aa3b, v81
	v_pk_add_f32 v[84:85], v[62:63], v[84:85]
	v_exp_f32_e32 v9, v9
	v_mul_f32_e32 v13, 0xbfb8aa3b, v85
	v_exp_f32_e32 v13, v13
	v_add_f32_e32 v9, 1.0, v9
	v_rcp_f32_e32 v9, v9
	v_add_f32_e32 v13, 1.0, v13
	v_rcp_f32_e32 v13, v13
	v_mul_f32_e32 v9, v81, v9
	v_mul_f32_e32 v9, v80, v9
	v_mul_f32_e32 v13, v85, v13
	v_mul_f32_e32 v13, v84, v13
	v_cvt_pk_bf16_f32 v93, v9, v13
	v_mov_b32_e32 v232, v242
	v_mov_b32_e32 v233, v243
	v_mov_b32_e32 v234, v92
	v_mov_b32_e32 v235, v93
	s_nop 1
	v_permlane16_swap_b32_e32 v232, v234
	v_permlane16_swap_b32_e32 v233, v235
	v_lshl_add_u64 v[236:237], v[106:107], 0, v[238:239]
	global_store_dwordx4 v[236:237], v[232:235], off
	s_nop 1
	s_and_saveexec_b64 s[62:63], s[4:5]
	s_cbranch_execz .LBB0_512
	global_store_dwordx4 v[76:77], v[36:39], off offset:64
	v_add_co_u32_e32 v76, vcc, 0x2000, v76
	s_nop 1
	v_addc_co_u32_e32 v77, vcc, 0, v77, vcc
	v_cmp_lt_u32_e32 vcc, s94, v170
	global_store_dwordx4 v[76:77], v[32:35], off offset:3136
	s_and_b64 exec, exec, vcc
	s_cbranch_execz .LBB0_512
	v_add_u32_e32 v9, s55, v170
	v_mul_hi_i32_i24_e32 v77, 0x5800, v9
	v_mul_i32_i24_e32 v76, 0x5800, v9
	v_lshl_add_u64 v[76:77], s[18:19], 0, v[76:77]
	v_lshl_add_u64 v[80:81], v[146:147], 2, v[76:77]
	global_store_dwordx4 v[80:81], v[36:39], off offset:64
	s_nop 1
	v_lshl_add_u64 v[36:37], v[72:73], 2, v[76:77]
	v_add_co_u32_e32 v36, vcc, 0x2000, v36
	s_nop 1
	v_addc_co_u32_e32 v37, vcc, 0, v37, vcc
	global_store_dwordx4 v[36:37], v[32:35], off offset:3072

.LBB0_516:
	s_or_b64 exec, exec, s[62:63]
	v_mov_b32_e32 v153, v152
	v_mov_b32_e32 v151, v150
	v_mov_b32_e32 v149, v148
	v_pk_mul_f32 v[16:17], v[22:23], v[152:153]
	v_pk_mul_f32 v[22:23], v[6:7], v[150:151]
	v_pk_mul_f32 v[6:7], v[10:11], v[148:149]
	v_pk_mul_f32 v[2:3], v[2:3], v[148:149]
	v_pk_mul_f32 v[14:15], v[14:15], v[152:153]
	v_pk_mul_f32 v[18:19], v[18:19], v[150:151]
	v_mov_b32_dpp v11, v30 row_ror:1 row_mask:0xf bank_mask:0xf bound_ctrl:1
	v_mov_b32_dpp v10, v26 row_ror:1 row_mask:0xf bank_mask:0xf bound_ctrl:1
	v_mov_b32_dpp v25, v30 row_ror:2 row_mask:0xf bank_mask:0xf bound_ctrl:1
	v_mov_b32_dpp v11, v16 row_shr:1 row_mask:0xf bank_mask:0xf
	v_mov_b32_dpp v10, v14 row_shr:1 row_mask:0xf bank_mask:0xf
	v_mov_b32_dpp v24, v26 row_ror:2 row_mask:0xf bank_mask:0xf bound_ctrl:1
	v_mov_b32_e32 v28, v14
	v_mov_b32_e32 v29, v16
	v_pk_mul_f32 v[10:11], v[46:47], v[10:11]
	v_mov_b32_dpp v25, v16 row_shr:2 row_mask:0xf bank_mask:0xf
	v_mov_b32_dpp v24, v14 row_shr:2 row_mask:0xf bank_mask:0xf
	v_pk_fma_f32 v[10:11], v[28:29], v[42:43], v[10:11]
	v_mov_b32_dpp v29, v31 row_ror:2 row_mask:0xf bank_mask:0xf bound_ctrl:1
	v_pk_fma_f32 v[10:11], v[50:51], v[24:25], v[10:11]
	v_mov_b32_dpp v25, v31 row_ror:1 row_mask:0xf bank_mask:0xf bound_ctrl:1
	v_mov_b32_dpp v24, v27 row_ror:1 row_mask:0xf bank_mask:0xf bound_ctrl:1
	v_mov_b32_dpp v28, v27 row_ror:2 row_mask:0xf bank_mask:0xf bound_ctrl:1
	v_mov_b32_dpp v25, v17 row_shr:1 row_mask:0xf bank_mask:0xf
	v_mov_b32_dpp v24, v15 row_shr:1 row_mask:0xf bank_mask:0xf
	v_mov_b32_e32 v26, v15
	v_mov_b32_e32 v27, v17
	v_pk_mul_f32 v[24:25], v[58:59], v[24:25]
	v_mov_b32_dpp v29, v17 row_shr:2 row_mask:0xf bank_mask:0xf
	v_mov_b32_dpp v28, v15 row_shr:2 row_mask:0xf bank_mask:0xf
	v_pk_fma_f32 v[24:25], v[26:27], v[56:57], v[24:25]
	v_pk_add_f32 v[10:11], v[54:55], v[10:11]
	v_pk_fma_f32 v[24:25], v[60:61], v[28:29], v[24:25]
	v_mul_f32_e32 v9, 0xbfb8aa3b, v11
	v_pk_add_f32 v[24:25], v[62:63], v[24:25]
	v_exp_f32_e32 v9, v9
	v_mul_f32_e32 v13, 0xbfb8aa3b, v25
	v_exp_f32_e32 v13, v13
	v_add_f32_e32 v9, 1.0, v9
	v_rcp_f32_e32 v9, v9
	v_add_f32_e32 v13, 1.0, v13
	v_rcp_f32_e32 v13, v13
	v_mul_f32_e32 v9, v11, v9
	v_mul_f32_e32 v9, v10, v9
	v_mul_f32_e32 v10, v25, v13
	v_mul_f32_e32 v10, v24, v10
	v_cvt_pk_bf16_f32 v9, v9, v10
	v_mov_b32_e32 v232, v244
	v_mov_b32_e32 v233, v245
	v_mov_b32_e32 v234, v8
	v_mov_b32_e32 v235, v9
	s_nop 1
	v_permlane16_swap_b32_e32 v232, v234
	v_permlane16_swap_b32_e32 v233, v235
	v_lshl_add_u64 v[236:237], v[78:79], 0, v[238:239]
	global_store_dwordx4 v[236:237], v[232:235], off
	s_nop 1
	s_nop 0
	v_mov_b32_dpp v9, v16 row_ror:1 row_mask:0xf bank_mask:0xf bound_ctrl:1
	v_mov_b32_dpp v8, v14 row_ror:1 row_mask:0xf bank_mask:0xf bound_ctrl:1
	v_mov_b32_dpp v11, v16 row_ror:2 row_mask:0xf bank_mask:0xf bound_ctrl:1
	v_mov_b32_dpp v9, v18 row_shr:1 row_mask:0xf bank_mask:0xf
	v_mov_b32_dpp v8, v22 row_shr:1 row_mask:0xf bank_mask:0xf
	v_mov_b32_dpp v10, v14 row_ror:2 row_mask:0xf bank_mask:0xf bound_ctrl:1
	v_mov_b32_e32 v24, v22
	v_mov_b32_e32 v25, v18
	v_pk_mul_f32 v[8:9], v[46:47], v[8:9]
	v_mov_b32_dpp v11, v18 row_shr:2 row_mask:0xf bank_mask:0xf
	v_mov_b32_dpp v10, v22 row_shr:2 row_mask:0xf bank_mask:0xf
	v_pk_fma_f32 v[8:9], v[24:25], v[42:43], v[8:9]
	v_mov_b32_dpp v16, v15 row_ror:2 row_mask:0xf bank_mask:0xf bound_ctrl:1
	v_pk_fma_f32 v[8:9], v[50:51], v[10:11], v[8:9]
	v_mov_b32_dpp v11, v17 row_ror:1 row_mask:0xf bank_mask:0xf bound_ctrl:1
	v_pk_add_f32 v[8:9], v[54:55], v[8:9]
	v_mov_b32_dpp v17, v17 row_ror:2 row_mask:0xf bank_mask:0xf bound_ctrl:1
	v_mul_f32_e32 v10, 0xbfb8aa3b, v9
	v_exp_f32_e32 v13, v10
	v_mov_b32_dpp v11, v19 row_shr:1 row_mask:0xf bank_mask:0xf
	v_mov_b32_dpp v10, v15 row_ror:1 row_mask:0xf bank_mask:0xf bound_ctrl:1
	v_mov_b32_e32 v14, v23
	v_mov_b32_e32 v15, v19
	v_mov_b32_dpp v10, v23 row_shr:1 row_mask:0xf bank_mask:0xf
	v_pk_mul_f32 v[10:11], v[58:59], v[10:11]
	v_mov_b32_dpp v17, v19 row_shr:2 row_mask:0xf bank_mask:0xf
	v_mov_b32_dpp v16, v23 row_shr:2 row_mask:0xf bank_mask:0xf
	v_pk_fma_f32 v[10:11], v[14:15], v[56:57], v[10:11]
	v_add_f32_e32 v13, 1.0, v13
	v_pk_fma_f32 v[10:11], v[60:61], v[16:17], v[10:11]
	v_rcp_f32_e32 v13, v13
	v_pk_add_f32 v[10:11], v[62:63], v[10:11]
	v_mul_f32_e32 v9, v9, v13
	v_mul_f32_e32 v14, 0xbfb8aa3b, v11
	v_exp_f32_e32 v14, v14
	v_mul_f32_e32 v8, v8, v9
	v_add_f32_e32 v14, 1.0, v14
	v_rcp_f32_e32 v14, v14
	s_nop 0
	v_mul_f32_e32 v9, v11, v14
	v_mul_f32_e32 v9, v10, v9
	v_cvt_pk_bf16_f32 v13, v8, v9
	v_mov_b32_e32 v232, v246
	v_mov_b32_e32 v233, v247
	v_mov_b32_e32 v234, v12
	v_mov_b32_e32 v235, v13
	s_nop 1
	v_permlane16_swap_b32_e32 v232, v234
	v_permlane16_swap_b32_e32 v233, v235
	v_lshl_add_u64 v[236:237], v[82:83], 0, v[238:239]
	global_store_dwordx4 v[236:237], v[232:235], off
	s_nop 1
	s_nop 0
	v_mov_b32_dpp v9, v18 row_ror:1 row_mask:0xf bank_mask:0xf bound_ctrl:1
	v_mov_b32_dpp v8, v22 row_ror:1 row_mask:0xf bank_mask:0xf bound_ctrl:1
	v_mov_b32_dpp v11, v18 row_ror:2 row_mask:0xf bank_mask:0xf bound_ctrl:1
	v_mov_b32_dpp v9, v6 row_shr:1 row_mask:0xf bank_mask:0xf
	v_mov_b32_dpp v8, v2 row_shr:1 row_mask:0xf bank_mask:0xf
	v_mov_b32_dpp v10, v22 row_ror:2 row_mask:0xf bank_mask:0xf bound_ctrl:1
	v_mov_b32_e32 v12, v2
	v_mov_b32_e32 v13, v6
	v_pk_mul_f32 v[8:9], v[46:47], v[8:9]
	v_mov_b32_dpp v11, v6 row_shr:2 row_mask:0xf bank_mask:0xf
	v_mov_b32_dpp v10, v2 row_shr:2 row_mask:0xf bank_mask:0xf
	v_pk_fma_f32 v[8:9], v[12:13], v[42:43], v[8:9]
	v_mov_b32_dpp v13, v19 row_ror:2 row_mask:0xf bank_mask:0xf bound_ctrl:1
	v_pk_fma_f32 v[8:9], v[50:51], v[10:11], v[8:9]
	v_mov_b32_dpp v11, v19 row_ror:1 row_mask:0xf bank_mask:0xf bound_ctrl:1
	v_pk_add_f32 v[8:9], v[54:55], v[8:9]
	v_mov_b32_dpp v12, v23 row_ror:2 row_mask:0xf bank_mask:0xf bound_ctrl:1
	v_mul_f32_e32 v10, 0xbfb8aa3b, v9
	v_exp_f32_e32 v16, v10
	v_mov_b32_dpp v11, v7 row_shr:1 row_mask:0xf bank_mask:0xf
	v_mov_b32_dpp v10, v23 row_ror:1 row_mask:0xf bank_mask:0xf bound_ctrl:1
	v_mov_b32_e32 v14, v3
	v_mov_b32_e32 v15, v7
	v_mov_b32_dpp v10, v3 row_shr:1 row_mask:0xf bank_mask:0xf
	v_pk_mul_f32 v[10:11], v[58:59], v[10:11]
	v_mov_b32_dpp v13, v7 row_shr:2 row_mask:0xf bank_mask:0xf
	v_mov_b32_dpp v12, v3 row_shr:2 row_mask:0xf bank_mask:0xf
	v_pk_fma_f32 v[10:11], v[14:15], v[56:57], v[10:11]
	s_nop 0
	v_pk_fma_f32 v[10:11], v[60:61], v[12:13], v[10:11]
	v_add_f32_e32 v13, 1.0, v16
	v_pk_add_f32 v[10:11], v[62:63], v[10:11]
	v_rcp_f32_e32 v13, v13
	v_mul_f32_e32 v12, 0xbfb8aa3b, v11
	v_exp_f32_e32 v12, v12
	v_mul_f32_e32 v9, v9, v13
	v_mul_f32_e32 v8, v8, v9
	v_add_f32_e32 v12, 1.0, v12
	v_rcp_f32_e32 v12, v12
	s_nop 0
	v_mul_f32_e32 v9, v11, v12
	v_mul_f32_e32 v9, v10, v9
	v_cvt_pk_bf16_f32 v21, v8, v9
	v_mov_b32_e32 v232, v248
	v_mov_b32_e32 v233, v249
	v_mov_b32_e32 v234, v20
	v_mov_b32_e32 v235, v21
	s_nop 1
	v_permlane16_swap_b32_e32 v232, v234
	v_permlane16_swap_b32_e32 v233, v235
	v_lshl_add_u64 v[236:237], v[86:87], 0, v[238:239]
	global_store_dwordx4 v[236:237], v[232:235], off
	s_nop 1
	s_and_saveexec_b64 s[62:63], s[4:5]
	s_cbranch_execz .LBB0_519
	v_add_co_u32_e32 v8, vcc, 0x2000, v74
	global_store_dwordx4 v[74:75], v[4:7], off offset:64
	s_nop 0
	v_addc_co_u32_e32 v9, vcc, 0, v75, vcc
	v_cmp_lt_u32_e32 vcc, s94, v122
	global_store_dwordx4 v[8:9], v[0:3], off offset:3136
	s_and_b64 exec, exec, vcc
	s_cbranch_execz .LBB0_519
	v_add_u32_e32 v8, s57, v122
	v_mul_hi_i32_i24_e32 v9, 0x5800, v8
	v_mul_i32_i24_e32 v8, 0x5800, v8
	v_lshl_add_u64 v[8:9], s[18:19], 0, v[8:9]
	v_lshl_add_u64 v[10:11], v[146:147], 2, v[8:9]
	global_store_dwordx4 v[10:11], v[4:7], off offset:64
	s_nop 1
	v_lshl_add_u64 v[4:5], v[72:73], 2, v[8:9]
	v_add_co_u32_e32 v4, vcc, 0x2000, v4
	s_nop 1
	v_addc_co_u32_e32 v5, vcc, 0, v5, vcc
	global_store_dwordx4 v[4:5], v[0:3], off offset:3072

.LBB0_1209:
	ds_read_b128 v[146:149], v216
	ds_read_b128 v[150:153], v216 offset:1024
	ds_read_b128 v[154:157], v216 offset:2048
	ds_read_b128 v[158:161], v216 offset:3072
	ds_read_b128 v[162:165], v217
	ds_read_b128 v[166:169], v217 offset:1024
	ds_read_b128 v[170:173], v217 offset:2048
	ds_read_b128 v[174:177], v217 offset:3072
	s_add_u32 s62, s60, 0xfffc0080
	s_addc_u32 s63, s61, -1
	s_cmp_eq_u32 s89, 12
	s_cselect_b32 s65, s51, s63
	s_cselect_b32 s64, s57, s62
	s_cselect_b32 s63, s45, s88
	s_cselect_b32 s62, s59, s87
	v_lshl_add_u64 v[220:221], s[60:61], 0, v[138:139]
	s_add_i32 m0, s69, 0xc000
	ds_read_b128 v[178:181], v218
	ds_read_b128 v[182:185], v218 offset:1024
	ds_read_b128 v[186:189], v218 offset:2048
	ds_read_b128 v[190:193], v218 offset:3072
	ds_read_b128 v[194:197], v218 offset:4096
	ds_read_b128 v[198:201], v218 offset:5120
	ds_read_b128 v[202:205], v218 offset:6144
	ds_read_b128 v[206:209], v218 offset:7168
	global_load_lds_dwordx4 v[220:221], off
	v_lshl_add_u64 v[220:221], s[60:61], 0, v[140:141]
	s_add_i32 m0, s69, 0xe000
	s_nop 0
	global_load_lds_dwordx4 v[220:221], off
	s_waitcnt vmcnt(8)
	s_waitcnt lgkmcnt(0)
	s_barrier
	s_setprio 1
	s_waitcnt lgkmcnt(0)
	v_mfma_f32_16x16x32_bf16 v[124:127], v[146:149], v[178:181], v[124:127]
	v_mfma_f32_16x16x32_bf16 v[60:63], v[154:157], v[178:181], v[60:63]
	v_mfma_f32_16x16x32_bf16 v[116:119], v[146:149], v[186:189], v[116:119]
	v_mfma_f32_16x16x32_bf16 v[52:55], v[154:157], v[186:189], v[52:55]
	v_mfma_f32_16x16x32_bf16 v[112:115], v[146:149], v[194:197], v[112:115]
	v_mfma_f32_16x16x32_bf16 v[48:51], v[154:157], v[194:197], v[48:51]
	v_mfma_f32_16x16x32_bf16 v[108:111], v[146:149], v[202:205], v[108:111]
	v_mfma_f32_16x16x32_bf16 v[40:43], v[154:157], v[202:205], v[40:43]
	v_mfma_f32_16x16x32_bf16 v[124:127], v[150:153], v[182:185], v[124:127]
	v_mfma_f32_16x16x32_bf16 v[60:63], v[158:161], v[182:185], v[60:63]
	v_mfma_f32_16x16x32_bf16 v[116:119], v[150:153], v[190:193], v[116:119]
	v_mfma_f32_16x16x32_bf16 v[52:55], v[158:161], v[190:193], v[52:55]
	v_mfma_f32_16x16x32_bf16 v[112:115], v[150:153], v[198:201], v[112:115]
	v_mfma_f32_16x16x32_bf16 v[48:51], v[158:161], v[198:201], v[48:51]
	v_mfma_f32_16x16x32_bf16 v[108:111], v[150:153], v[206:209], v[108:111]
	v_mfma_f32_16x16x32_bf16 v[40:43], v[158:161], v[206:209], v[40:43]
	s_setprio 0
	s_setprio 1
	v_mfma_f32_16x16x32_bf16 v[120:123], v[162:165], v[178:181], v[120:123]
	v_mfma_f32_16x16x32_bf16 v[56:59], v[170:173], v[178:181], v[56:59]
	v_mfma_f32_16x16x32_bf16 v[104:107], v[162:165], v[186:189], v[104:107]
	v_mfma_f32_16x16x32_bf16 v[44:47], v[170:173], v[186:189], v[44:47]
	v_mfma_f32_16x16x32_bf16 v[100:103], v[162:165], v[194:197], v[100:103]
	v_mfma_f32_16x16x32_bf16 v[36:39], v[170:173], v[194:197], v[36:39]
	v_mfma_f32_16x16x32_bf16 v[96:99], v[162:165], v[202:205], v[96:99]
	v_mfma_f32_16x16x32_bf16 v[32:35], v[170:173], v[202:205], v[32:35]
	v_mfma_f32_16x16x32_bf16 v[120:123], v[166:169], v[182:185], v[120:123]
	v_mfma_f32_16x16x32_bf16 v[56:59], v[174:177], v[182:185], v[56:59]
	v_mfma_f32_16x16x32_bf16 v[104:107], v[166:169], v[190:193], v[104:107]
	v_mfma_f32_16x16x32_bf16 v[44:47], v[174:177], v[190:193], v[44:47]
	v_mfma_f32_16x16x32_bf16 v[100:103], v[166:169], v[198:201], v[100:103]
	v_mfma_f32_16x16x32_bf16 v[36:39], v[174:177], v[198:201], v[36:39]
	v_mfma_f32_16x16x32_bf16 v[96:99], v[166:169], v[206:209], v[96:99]
	v_mfma_f32_16x16x32_bf16 v[32:35], v[174:177], v[206:209], v[32:35]
	s_setprio 0
	s_barrier
	s_add_i32 s90, s82, s68
	v_lshl_add_u64 v[220:221], s[62:63], 0, v[128:129]
	s_mov_b32 m0, s90
	ds_read_b128 v[178:181], v218 offset:16384
	ds_read_b128 v[182:185], v218 offset:17408
	ds_read_b128 v[186:189], v218 offset:18432
	ds_read_b128 v[190:193], v218 offset:19456
	ds_read_b128 v[194:197], v218 offset:20480
	ds_read_b128 v[198:201], v218 offset:21504
	ds_read_b128 v[202:205], v218 offset:22528
	ds_read_b128 v[206:209], v218 offset:23552
	global_load_lds_dwordx4 v[220:221], off
	s_add_i32 m0, s90, 0x2000
	s_add_u32 s90, s62, 0x40000
	v_lshl_add_u64 v[222:223], s[62:63], 0, v[130:131]
	s_addc_u32 s91, s63, 0
	s_add_i32 s92, s83, s68
	global_load_lds_dwordx4 v[222:223], off
	v_lshl_add_u64 v[224:225], s[90:91], 0, v[128:129]
	s_mov_b32 m0, s92
	v_lshl_add_u64 v[226:227], s[64:65], 0, v[130:131]
	global_load_lds_dwordx4 v[224:225], off
	v_lshl_add_u64 v[224:225], s[90:91], 0, v[130:131]
	s_add_i32 m0, s92, 0x2000
	s_nop 0
	global_load_lds_dwordx4 v[224:225], off
	v_lshl_add_u64 v[224:225], s[64:65], 0, v[128:129]
	s_mov_b32 m0, s69
	s_nop 0
	global_load_lds_dwordx4 v[224:225], off
	s_mov_b32 m0, s70
	s_nop 0
	global_load_lds_dwordx4 v[226:227], off
	s_waitcnt vmcnt(8)
	s_waitcnt lgkmcnt(0)
	s_barrier
	s_setprio 1
	s_waitcnt lgkmcnt(0)
	v_mfma_f32_16x16x32_bf16 v[92:95], v[146:149], v[178:181], v[92:95]
	v_mfma_f32_16x16x32_bf16 v[28:31], v[154:157], v[178:181], v[28:31]
	v_mfma_f32_16x16x32_bf16 v[84:87], v[146:149], v[186:189], v[84:87]
	v_mfma_f32_16x16x32_bf16 v[20:23], v[154:157], v[186:189], v[20:23]
	v_mfma_f32_16x16x32_bf16 v[80:83], v[146:149], v[194:197], v[80:83]
	v_mfma_f32_16x16x32_bf16 v[16:19], v[154:157], v[194:197], v[16:19]
	v_mfma_f32_16x16x32_bf16 v[76:79], v[146:149], v[202:205], v[76:79]
	v_mfma_f32_16x16x32_bf16 v[8:11], v[154:157], v[202:205], v[8:11]
	v_mfma_f32_16x16x32_bf16 v[92:95], v[150:153], v[182:185], v[92:95]
	v_mfma_f32_16x16x32_bf16 v[28:31], v[158:161], v[182:185], v[28:31]
	v_mfma_f32_16x16x32_bf16 v[84:87], v[150:153], v[190:193], v[84:87]
	v_mfma_f32_16x16x32_bf16 v[20:23], v[158:161], v[190:193], v[20:23]
	v_mfma_f32_16x16x32_bf16 v[80:83], v[150:153], v[198:201], v[80:83]
	v_mfma_f32_16x16x32_bf16 v[16:19], v[158:161], v[198:201], v[16:19]
	v_mfma_f32_16x16x32_bf16 v[76:79], v[150:153], v[206:209], v[76:79]
	v_mfma_f32_16x16x32_bf16 v[8:11], v[158:161], v[206:209], v[8:11]
	s_setprio 0
	s_setprio 1
	v_mfma_f32_16x16x32_bf16 v[88:91], v[162:165], v[178:181], v[88:91]
	v_mfma_f32_16x16x32_bf16 v[24:27], v[170:173], v[178:181], v[24:27]
	v_mfma_f32_16x16x32_bf16 v[72:75], v[162:165], v[186:189], v[72:75]
	v_mfma_f32_16x16x32_bf16 v[12:15], v[170:173], v[186:189], v[12:15]
	v_mfma_f32_16x16x32_bf16 v[68:71], v[162:165], v[194:197], v[68:71]
	v_mfma_f32_16x16x32_bf16 v[4:7], v[170:173], v[194:197], v[4:7]
	v_mfma_f32_16x16x32_bf16 v[64:67], v[162:165], v[202:205], v[64:67]
	v_mfma_f32_16x16x32_bf16 v[0:3], v[170:173], v[202:205], v[0:3]
	v_mfma_f32_16x16x32_bf16 v[88:91], v[166:169], v[182:185], v[88:91]
	v_mfma_f32_16x16x32_bf16 v[24:27], v[174:177], v[182:185], v[24:27]
	v_mfma_f32_16x16x32_bf16 v[72:75], v[166:169], v[190:193], v[72:75]
	v_mfma_f32_16x16x32_bf16 v[12:15], v[174:177], v[190:193], v[12:15]
	v_mfma_f32_16x16x32_bf16 v[68:71], v[166:169], v[198:201], v[68:71]
	v_mfma_f32_16x16x32_bf16 v[4:7], v[174:177], v[198:201], v[4:7]
	v_mfma_f32_16x16x32_bf16 v[64:67], v[166:169], v[206:209], v[64:67]
	v_mfma_f32_16x16x32_bf16 v[0:3], v[174:177], v[206:209], v[0:3]
	s_setprio 0
	s_barrier
	s_add_i32 s90, 0, 0x18000
	s_add_i32 s91, 0, 0x1c000
	v_add_u32_e32 v158, s90, v211
	v_add_u32_e32 v174, s91, v211
	ds_read_b128 v[146:149], v158
	ds_read_b128 v[150:153], v158 offset:1024
	ds_read_b128 v[154:157], v158 offset:2048
	ds_read_b128 v[158:161], v158 offset:3072
	ds_read_b128 v[162:165], v174
	ds_read_b128 v[166:169], v174 offset:1024
	ds_read_b128 v[170:173], v174 offset:2048
	ds_read_b128 v[174:177], v174 offset:3072
	s_add_u32 s64, s64, 0x40000
	s_addc_u32 s65, s65, 0
	s_mov_b32 m0, s71
	v_lshl_add_u64 v[228:229], s[64:65], 0, v[128:129]
	ds_read_b128 v[178:181], v218 offset:32768
	ds_read_b128 v[182:185], v218 offset:33792
	ds_read_b128 v[186:189], v218 offset:34816
	ds_read_b128 v[190:193], v218 offset:35840
	ds_read_b128 v[194:197], v218 offset:36864
	ds_read_b128 v[198:201], v218 offset:37888
	ds_read_b128 v[202:205], v218 offset:38912
	ds_read_b128 v[206:209], v218 offset:39936
	global_load_lds_dwordx4 v[228:229], off
	v_lshl_add_u64 v[228:229], s[64:65], 0, v[130:131]
	s_mov_b32 m0, s72
	s_nop 0
	global_load_lds_dwordx4 v[228:229], off
	s_waitcnt vmcnt(8)
	s_waitcnt lgkmcnt(0)
	s_barrier
	s_setprio 1
	s_waitcnt lgkmcnt(0)
	v_mfma_f32_16x16x32_bf16 v[124:127], v[146:149], v[178:181], v[124:127]
	v_mfma_f32_16x16x32_bf16 v[60:63], v[154:157], v[178:181], v[60:63]
	v_mfma_f32_16x16x32_bf16 v[116:119], v[146:149], v[186:189], v[116:119]
	v_mfma_f32_16x16x32_bf16 v[52:55], v[154:157], v[186:189], v[52:55]
	v_mfma_f32_16x16x32_bf16 v[112:115], v[146:149], v[194:197], v[112:115]
	v_mfma_f32_16x16x32_bf16 v[48:51], v[154:157], v[194:197], v[48:51]
	v_mfma_f32_16x16x32_bf16 v[108:111], v[146:149], v[202:205], v[108:111]
	v_mfma_f32_16x16x32_bf16 v[40:43], v[154:157], v[202:205], v[40:43]
	v_mfma_f32_16x16x32_bf16 v[124:127], v[150:153], v[182:185], v[124:127]
	v_mfma_f32_16x16x32_bf16 v[60:63], v[158:161], v[182:185], v[60:63]
	v_mfma_f32_16x16x32_bf16 v[116:119], v[150:153], v[190:193], v[116:119]
	v_mfma_f32_16x16x32_bf16 v[52:55], v[158:161], v[190:193], v[52:55]
	v_mfma_f32_16x16x32_bf16 v[112:115], v[150:153], v[198:201], v[112:115]
	v_mfma_f32_16x16x32_bf16 v[48:51], v[158:161], v[198:201], v[48:51]
	v_mfma_f32_16x16x32_bf16 v[108:111], v[150:153], v[206:209], v[108:111]
	v_mfma_f32_16x16x32_bf16 v[40:43], v[158:161], v[206:209], v[40:43]
	s_setprio 0
	s_setprio 1
	v_mfma_f32_16x16x32_bf16 v[120:123], v[162:165], v[178:181], v[120:123]
	v_mfma_f32_16x16x32_bf16 v[56:59], v[170:173], v[178:181], v[56:59]
	v_mfma_f32_16x16x32_bf16 v[104:107], v[162:165], v[186:189], v[104:107]
	v_mfma_f32_16x16x32_bf16 v[44:47], v[170:173], v[186:189], v[44:47]
	v_mfma_f32_16x16x32_bf16 v[100:103], v[162:165], v[194:197], v[100:103]
	v_mfma_f32_16x16x32_bf16 v[36:39], v[170:173], v[194:197], v[36:39]
	v_mfma_f32_16x16x32_bf16 v[96:99], v[162:165], v[202:205], v[96:99]
	v_mfma_f32_16x16x32_bf16 v[32:35], v[170:173], v[202:205], v[32:35]
	v_mfma_f32_16x16x32_bf16 v[120:123], v[166:169], v[182:185], v[120:123]
	v_mfma_f32_16x16x32_bf16 v[56:59], v[174:177], v[182:185], v[56:59]
	v_mfma_f32_16x16x32_bf16 v[104:107], v[166:169], v[190:193], v[104:107]
	v_mfma_f32_16x16x32_bf16 v[44:47], v[174:177], v[190:193], v[44:47]
	v_mfma_f32_16x16x32_bf16 v[100:103], v[166:169], v[198:201], v[100:103]
	v_mfma_f32_16x16x32_bf16 v[36:39], v[174:177], v[198:201], v[36:39]
	v_mfma_f32_16x16x32_bf16 v[96:99], v[166:169], v[206:209], v[96:99]
	v_mfma_f32_16x16x32_bf16 v[32:35], v[174:177], v[206:209], v[32:35]
	s_setprio 0
	s_barrier
	s_add_i32 s64, s90, s68
	v_lshl_add_u64 v[220:221], v[220:221], 0, s[20:21]
	s_mov_b32 m0, s64
	ds_read_b128 v[178:181], v218 offset:49152
	ds_read_b128 v[182:185], v218 offset:50176
	ds_read_b128 v[186:189], v218 offset:51200
	ds_read_b128 v[190:193], v218 offset:52224
	ds_read_b128 v[194:197], v218 offset:53248
	ds_read_b128 v[198:201], v218 offset:54272
	ds_read_b128 v[202:205], v218 offset:55296
	ds_read_b128 v[206:209], v218 offset:56320
	global_load_lds_dwordx4 v[220:221], off
	s_add_i32 m0, s64, 0x2000
	s_add_u32 s62, s62, 0x40080
	v_lshl_add_u64 v[220:221], v[222:223], 0, s[20:21]
	s_addc_u32 s63, s63, 0
	s_add_i32 s64, s91, s68
	global_load_lds_dwordx4 v[220:221], off
	v_lshl_add_u64 v[220:221], s[62:63], 0, v[128:129]
	s_mov_b32 m0, s64
	s_nop 0
	global_load_lds_dwordx4 v[220:221], off
	v_lshl_add_u64 v[220:221], s[62:63], 0, v[130:131]
	s_add_i32 m0, s64, 0x2000
	s_nop 0
	global_load_lds_dwordx4 v[220:221], off
	v_lshl_add_u64 v[220:221], v[224:225], 0, s[20:21]
	s_mov_b32 m0, s79
	s_nop 0
	global_load_lds_dwordx4 v[220:221], off
	v_lshl_add_u64 v[220:221], v[226:227], 0, s[20:21]
	s_mov_b32 m0, s80
	s_nop 0
	global_load_lds_dwordx4 v[220:221], off
	s_waitcnt vmcnt(8)
	s_waitcnt lgkmcnt(0)
	s_barrier
	s_setprio 1
	s_waitcnt lgkmcnt(0)
	v_mfma_f32_16x16x32_bf16 v[92:95], v[146:149], v[178:181], v[92:95]
	v_mfma_f32_16x16x32_bf16 v[28:31], v[154:157], v[178:181], v[28:31]
	v_mfma_f32_16x16x32_bf16 v[84:87], v[146:149], v[186:189], v[84:87]
	v_mfma_f32_16x16x32_bf16 v[20:23], v[154:157], v[186:189], v[20:23]
	v_mfma_f32_16x16x32_bf16 v[80:83], v[146:149], v[194:197], v[80:83]
	v_mfma_f32_16x16x32_bf16 v[16:19], v[154:157], v[194:197], v[16:19]
	v_mfma_f32_16x16x32_bf16 v[76:79], v[146:149], v[202:205], v[76:79]
	v_mfma_f32_16x16x32_bf16 v[8:11], v[154:157], v[202:205], v[8:11]
	v_mfma_f32_16x16x32_bf16 v[92:95], v[150:153], v[182:185], v[92:95]
	v_mfma_f32_16x16x32_bf16 v[28:31], v[158:161], v[182:185], v[28:31]
	v_mfma_f32_16x16x32_bf16 v[84:87], v[150:153], v[190:193], v[84:87]
	v_mfma_f32_16x16x32_bf16 v[20:23], v[158:161], v[190:193], v[20:23]
	v_mfma_f32_16x16x32_bf16 v[80:83], v[150:153], v[198:201], v[80:83]
	v_mfma_f32_16x16x32_bf16 v[16:19], v[158:161], v[198:201], v[16:19]
	v_mfma_f32_16x16x32_bf16 v[76:79], v[150:153], v[206:209], v[76:79]
	v_mfma_f32_16x16x32_bf16 v[8:11], v[158:161], v[206:209], v[8:11]
	s_setprio 0
	s_setprio 1
	v_mfma_f32_16x16x32_bf16 v[88:91], v[162:165], v[178:181], v[88:91]
	v_mfma_f32_16x16x32_bf16 v[24:27], v[170:173], v[178:181], v[24:27]
	v_mfma_f32_16x16x32_bf16 v[72:75], v[162:165], v[186:189], v[72:75]
	v_mfma_f32_16x16x32_bf16 v[12:15], v[170:173], v[186:189], v[12:15]
	v_mfma_f32_16x16x32_bf16 v[68:71], v[162:165], v[194:197], v[68:71]
	v_mfma_f32_16x16x32_bf16 v[4:7], v[170:173], v[194:197], v[4:7]
	v_mfma_f32_16x16x32_bf16 v[64:67], v[162:165], v[202:205], v[64:67]
	v_mfma_f32_16x16x32_bf16 v[0:3], v[170:173], v[202:205], v[0:3]
	v_mfma_f32_16x16x32_bf16 v[88:91], v[166:169], v[182:185], v[88:91]
	v_mfma_f32_16x16x32_bf16 v[24:27], v[174:177], v[182:185], v[24:27]
	v_mfma_f32_16x16x32_bf16 v[72:75], v[166:169], v[190:193], v[72:75]
	v_mfma_f32_16x16x32_bf16 v[12:15], v[174:177], v[190:193], v[12:15]
	v_mfma_f32_16x16x32_bf16 v[68:71], v[166:169], v[198:201], v[68:71]
	v_mfma_f32_16x16x32_bf16 v[4:7], v[174:177], v[198:201], v[4:7]
	v_mfma_f32_16x16x32_bf16 v[64:67], v[166:169], v[206:209], v[64:67]
	v_mfma_f32_16x16x32_bf16 v[0:3], v[174:177], v[206:209], v[0:3]
	s_setprio 0
	s_barrier
	s_add_i32 s89, s89, 2
	s_add_u32 s60, s60, 0x100
	s_addc_u32 s61, s61, 0
	s_add_u32 s87, s87, 0x100
	s_addc_u32 s88, s88, 0
	s_cmp_gt_u32 s89, 13
	s_cbranch_scc0 .LBB0_1209
	v_mbcnt_lo_u32_b32 v238, -1, 0
	v_mbcnt_hi_u32_b32 v238, -1, v238
	v_bfe_u32 v238, v238, 4, 1
	v_mul_u32_u24_e32 v238, 24, v238
	v_mov_b32_e32 v239, 0
	s_and_b64 vcc, exec, s[22:23]
	s_cbranch_vccz .LBB0_1212
	s_barrier

.LBB0_1216:
	s_or_b64 exec, exec, s[58:59]
	s_ashr_i32 s45, s51, 12
	s_and_b32 s45, s45, -2
	v_pk_mul_f32 v[104:105], v[118:119], v[162:163] op_sel_hi:[1,0]
	v_pk_mul_f32 v[106:107], v[106:107], v[162:163] op_sel_hi:[1,0]
	v_pk_mul_f32 v[112:113], v[114:115], v[160:161] op_sel_hi:[1,0]
	v_pk_mul_f32 v[114:115], v[102:103], v[160:161] op_sel_hi:[1,0]
	v_pk_mul_f32 v[102:103], v[110:111], v[158:159] op_sel_hi:[1,0]
	v_pk_mul_f32 v[98:99], v[98:99], v[158:159] op_sel_hi:[1,0]
	s_addk_i32 s45, 0xe002
	v_mov_b32_dpp v85, v126 row_ror:1 row_mask:0xf bank_mask:0xf bound_ctrl:1
	v_mov_b32_dpp v84, v122 row_ror:1 row_mask:0xf bank_mask:0xf bound_ctrl:1
	v_mov_b32_e32 v120, v184
	v_mov_b32_dpp v85, v104 row_shr:1 row_mask:0xf bank_mask:0xf
	v_mov_b32_dpp v84, v106 row_shr:1 row_mask:0xf bank_mask:0xf
	v_mov_b32_e32 v121, v192
	v_mov_b32_dpp v111, v126 row_ror:2 row_mask:0xf bank_mask:0xf bound_ctrl:1
	v_mov_b32_dpp v110, v122 row_ror:2 row_mask:0xf bank_mask:0xf bound_ctrl:1
	v_mov_b32_e32 v116, v106
	v_mov_b32_e32 v117, v104
	v_mov_b32_e32 v118, v180
	v_mov_b32_e32 v119, v190
	v_pk_mul_f32 v[84:85], v[120:121], v[84:85]
	v_mov_b32_dpp v111, v104 row_shr:2 row_mask:0xf bank_mask:0xf
	v_mov_b32_dpp v110, v106 row_shr:2 row_mask:0xf bank_mask:0xf
	v_pk_fma_f32 v[84:85], v[116:117], v[118:119], v[84:85]
	v_mov_b32_e32 v124, v178
	v_mov_b32_e32 v125, v186
	v_pk_fma_f32 v[84:85], v[124:125], v[110:111], v[84:85]
	v_mov_b32_dpp v111, v127 row_ror:1 row_mask:0xf bank_mask:0xf bound_ctrl:1
	v_mov_b32_dpp v110, v123 row_ror:1 row_mask:0xf bank_mask:0xf bound_ctrl:1
	v_mov_b32_dpp v117, v127 row_ror:2 row_mask:0xf bank_mask:0xf bound_ctrl:1
	v_mov_b32_dpp v111, v105 row_shr:1 row_mask:0xf bank_mask:0xf
	v_mov_b32_dpp v110, v107 row_shr:1 row_mask:0xf bank_mask:0xf
	v_mov_b32_e32 v126, v185
	v_mov_b32_e32 v127, v193
	v_mov_b32_dpp v116, v123 row_ror:2 row_mask:0xf bank_mask:0xf bound_ctrl:1
	v_mov_b32_e32 v198, v107
	v_mov_b32_e32 v199, v105
	v_mov_b32_e32 v122, v181
	v_mov_b32_e32 v123, v191
	v_pk_mul_f32 v[110:111], v[126:127], v[110:111]
	v_mov_b32_dpp v117, v105 row_shr:2 row_mask:0xf bank_mask:0xf
	v_mov_b32_dpp v116, v107 row_shr:2 row_mask:0xf bank_mask:0xf
	v_pk_fma_f32 v[110:111], v[198:199], v[122:123], v[110:111]
	v_mov_b32_e32 v198, v179
	v_mov_b32_e32 v199, v187
	v_pk_fma_f32 v[110:111], v[198:199], v[116:117], v[110:111]
	v_mov_b32_e32 v200, v183
	v_mov_b32_e32 v201, v189
	v_mov_b32_e32 v196, v182
	v_mov_b32_e32 v197, v188
	v_pk_add_f32 v[110:111], v[200:201], v[110:111]
	v_pk_add_f32 v[84:85], v[196:197], v[84:85]
	v_mul_f32_e32 v77, 0xbfb8aa3b, v111
	v_mul_f32_e32 v73, 0xbfb8aa3b, v85
	v_exp_f32_e32 v77, v77
	v_exp_f32_e32 v73, v73
	v_add_f32_e32 v77, 1.0, v77
	v_add_f32_e32 v73, 1.0, v73
	v_rcp_f32_e32 v77, v77
	v_rcp_f32_e32 v73, v73
	v_mul_f32_e32 v77, v111, v77
	v_mul_f32_e32 v73, v85, v73
	v_mul_f32_e32 v77, v110, v77
	v_mov_b64_e32 v[110:111], s[48:49]
	v_mul_f32_e32 v73, v84, v73
	v_mad_i64_i32 v[84:85], s[58:59], v170, s85, v[110:111]
	v_lshlrev_b64 v[170:171], 1, v[146:147]
	v_lshl_add_u64 v[84:85], v[84:85], 0, v[170:171]
	v_cvt_pk_bf16_f32 v73, v73, v77
	v_mov_b32_e32 v230, v72
	v_mov_b32_e32 v231, v73
	s_nop 0
	v_mov_b32_dpp v73, v104 row_ror:1 row_mask:0xf bank_mask:0xf bound_ctrl:1
	v_mov_b32_dpp v72, v106 row_ror:1 row_mask:0xf bank_mask:0xf bound_ctrl:1
	v_mov_b32_dpp v117, v104 row_ror:2 row_mask:0xf bank_mask:0xf bound_ctrl:1
	v_mov_b32_dpp v73, v112 row_shr:1 row_mask:0xf bank_mask:0xf
	v_mov_b32_dpp v72, v114 row_shr:1 row_mask:0xf bank_mask:0xf
	v_mov_b32_dpp v116, v106 row_ror:2 row_mask:0xf bank_mask:0xf bound_ctrl:1
	v_mov_b32_e32 v202, v114
	v_mov_b32_e32 v203, v112
	v_pk_mul_f32 v[72:73], v[120:121], v[72:73]
	v_mov_b32_dpp v117, v112 row_shr:2 row_mask:0xf bank_mask:0xf
	v_mov_b32_dpp v116, v114 row_shr:2 row_mask:0xf bank_mask:0xf
	v_pk_fma_f32 v[72:73], v[202:203], v[118:119], v[72:73]
	v_mov_b32_dpp v104, v107 row_ror:2 row_mask:0xf bank_mask:0xf bound_ctrl:1
	v_pk_fma_f32 v[72:73], v[124:125], v[116:117], v[72:73]
	v_mov_b32_dpp v117, v105 row_ror:1 row_mask:0xf bank_mask:0xf bound_ctrl:1
	v_mov_b32_dpp v116, v107 row_ror:1 row_mask:0xf bank_mask:0xf bound_ctrl:1
	v_mov_b32_dpp v105, v105 row_ror:2 row_mask:0xf bank_mask:0xf bound_ctrl:1
	v_mov_b32_dpp v117, v113 row_shr:1 row_mask:0xf bank_mask:0xf
	v_mov_b32_dpp v116, v115 row_shr:1 row_mask:0xf bank_mask:0xf
	v_mov_b32_e32 v106, v115
	v_mov_b32_e32 v107, v113
	v_pk_mul_f32 v[116:117], v[126:127], v[116:117]
	v_mov_b32_dpp v105, v113 row_shr:2 row_mask:0xf bank_mask:0xf
	v_mov_b32_dpp v104, v115 row_shr:2 row_mask:0xf bank_mask:0xf
	v_pk_fma_f32 v[106:107], v[106:107], v[122:123], v[116:117]
	v_pk_add_f32 v[72:73], v[196:197], v[72:73]
	v_pk_fma_f32 v[104:105], v[198:199], v[104:105], v[106:107]
	v_mul_f32_e32 v77, 0xbfb8aa3b, v73
	v_pk_add_f32 v[104:105], v[200:201], v[104:105]
	v_exp_f32_e32 v77, v77
	v_mul_f32_e32 v106, 0xbfb8aa3b, v105
	v_exp_f32_e32 v106, v106
	v_add_f32_e32 v77, 1.0, v77
	v_rcp_f32_e32 v77, v77
	v_add_f32_e32 v106, 1.0, v106
	v_rcp_f32_e32 v106, v106
	v_mul_f32_e32 v73, v73, v77
	v_mul_f32_e32 v72, v72, v73
	v_mul_f32_e32 v73, v105, v106
	v_mul_f32_e32 v73, v104, v73
	v_cvt_pk_bf16_f32 v77, v72, v73
	v_mad_i64_i32 v[72:73], s[58:59], v168, s85, v[110:111]
	v_lshl_add_u64 v[104:105], v[72:73], 0, v[170:171]
	v_mov_b32_e32 v240, v76
	v_mov_b32_e32 v241, v77
	v_mov_b32_dpp v73, v112 row_ror:1 row_mask:0xf bank_mask:0xf bound_ctrl:1
	v_mov_b32_dpp v72, v114 row_ror:1 row_mask:0xf bank_mask:0xf bound_ctrl:1
	v_mov_b32_dpp v77, v112 row_ror:2 row_mask:0xf bank_mask:0xf bound_ctrl:1
	v_mov_b32_dpp v73, v102 row_shr:1 row_mask:0xf bank_mask:0xf
	v_mov_b32_dpp v72, v98 row_shr:1 row_mask:0xf bank_mask:0xf
	v_mov_b32_dpp v76, v114 row_ror:2 row_mask:0xf bank_mask:0xf bound_ctrl:1
	v_mov_b32_e32 v106, v98
	v_mov_b32_e32 v107, v102
	v_pk_mul_f32 v[72:73], v[120:121], v[72:73]
	v_mov_b32_dpp v77, v102 row_shr:2 row_mask:0xf bank_mask:0xf
	v_mov_b32_dpp v76, v98 row_shr:2 row_mask:0xf bank_mask:0xf
	v_pk_fma_f32 v[72:73], v[106:107], v[118:119], v[72:73]
	v_mov_b32_dpp v107, v113 row_ror:2 row_mask:0xf bank_mask:0xf bound_ctrl:1
	v_pk_fma_f32 v[72:73], v[124:125], v[76:77], v[72:73]
	v_mov_b32_dpp v77, v113 row_ror:1 row_mask:0xf bank_mask:0xf bound_ctrl:1
	v_pk_add_f32 v[72:73], v[196:197], v[72:73]
	v_mov_b32_dpp v106, v115 row_ror:2 row_mask:0xf bank_mask:0xf bound_ctrl:1
	v_mul_f32_e32 v76, 0xbfb8aa3b, v73
	v_exp_f32_e32 v109, v76
	v_mov_b32_dpp v77, v103 row_shr:1 row_mask:0xf bank_mask:0xf
	v_mov_b32_dpp v76, v115 row_ror:1 row_mask:0xf bank_mask:0xf bound_ctrl:1
	v_mov_b32_e32 v112, v99
	v_mov_b32_e32 v113, v103
	v_mov_b32_dpp v76, v99 row_shr:1 row_mask:0xf bank_mask:0xf
	v_pk_mul_f32 v[76:77], v[126:127], v[76:77]
	v_mov_b32_dpp v107, v103 row_shr:2 row_mask:0xf bank_mask:0xf
	v_mov_b32_dpp v106, v99 row_shr:2 row_mask:0xf bank_mask:0xf
	v_pk_fma_f32 v[76:77], v[112:113], v[122:123], v[76:77]
	s_nop 0
	v_pk_fma_f32 v[76:77], v[198:199], v[106:107], v[76:77]
	v_add_f32_e32 v107, 1.0, v109
	v_pk_add_f32 v[76:77], v[200:201], v[76:77]
	v_rcp_f32_e32 v107, v107
	v_mul_f32_e32 v106, 0xbfb8aa3b, v77
	v_exp_f32_e32 v106, v106
	v_mul_f32_e32 v73, v73, v107
	v_mul_f32_e32 v72, v72, v73
	v_add_f32_e32 v106, 1.0, v106
	v_rcp_f32_e32 v106, v106
	s_nop 0
	v_mul_f32_e32 v73, v77, v106
	v_mul_f32_e32 v73, v76, v73
	v_cvt_pk_bf16_f32 v109, v72, v73
	v_mad_i64_i32 v[72:73], s[58:59], v166, s85, v[110:111]
	v_lshl_add_u64 v[106:107], v[72:73], 0, v[170:171]
	v_lshl_add_u64 v[72:73], v[134:135], 0, s[56:57]
	v_lshl_add_u64 v[76:77], v[146:147], 2, v[72:73]
	v_and_b32_e32 v166, 0x1fff, v166
	v_mov_b32_e32 v242, v108
	v_mov_b32_e32 v243, v109
	s_and_saveexec_b64 s[56:57], s[4:5]
	s_cbranch_execz .LBB0_1219
	v_add_co_u32_e32 v72, vcc, 0x2000, v76
	global_store_dwordx4 v[76:77], v[100:103], off
	s_nop 0
	v_addc_co_u32_e32 v73, vcc, 0, v77, vcc
	v_cmp_lt_u32_e32 vcc, s86, v166
	global_store_dwordx4 v[72:73], v[96:99], off offset:3072
	s_and_b64 exec, exec, vcc
	s_cbranch_execz .LBB0_1219
	v_add_u32_e32 v72, s45, v166
	v_mul_hi_i32_i24_e32 v73, 0x5800, v72
	v_mul_i32_i24_e32 v72, 0x5800, v72
	v_lshl_add_u64 v[72:73], s[14:15], 0, v[72:73]
	v_lshl_add_u64 v[72:73], v[146:147], 2, v[72:73]
	global_store_dwordx4 v[72:73], v[100:103], off
	v_add_co_u32_e32 v72, vcc, 0x2000, v72
	s_nop 1
	v_addc_co_u32_e32 v73, vcc, 0, v73, vcc
	global_store_dwordx4 v[72:73], v[96:99], off offset:3072

.LBB0_1223:
	s_or_b64 exec, exec, s[58:59]
	s_ashr_i32 s51, s51, 12
	s_and_b32 s51, s51, -2
	v_pk_mul_f32 v[86:87], v[86:87], v[152:153] op_sel_hi:[1,0]
	v_pk_mul_f32 v[74:75], v[74:75], v[152:153] op_sel_hi:[1,0]
	v_pk_mul_f32 v[92:93], v[70:71], v[150:151] op_sel_hi:[1,0]
	v_pk_mul_f32 v[70:71], v[78:79], v[148:149] op_sel_hi:[1,0]
	v_pk_mul_f32 v[66:67], v[66:67], v[148:149] op_sel_hi:[1,0]
	s_addk_i32 s51, 0xe002
	v_pk_mul_f32 v[88:89], v[82:83], v[150:151] op_sel_hi:[1,0]
	v_or_b32_e32 v149, 16, v157
	v_or_b32_e32 v151, 32, v157
	v_or_b32_e32 v153, 48, v157
	v_mov_b32_dpp v79, v94 row_ror:1 row_mask:0xf bank_mask:0xf bound_ctrl:1
	v_mov_b32_dpp v78, v90 row_ror:1 row_mask:0xf bank_mask:0xf bound_ctrl:1
	v_mov_b32_dpp v83, v94 row_ror:2 row_mask:0xf bank_mask:0xf bound_ctrl:1
	v_mov_b32_dpp v79, v86 row_shr:1 row_mask:0xf bank_mask:0xf
	v_mov_b32_dpp v78, v74 row_shr:1 row_mask:0xf bank_mask:0xf
	v_mov_b32_dpp v82, v90 row_ror:2 row_mask:0xf bank_mask:0xf bound_ctrl:1
	v_mov_b32_e32 v168, v74
	v_mov_b32_e32 v169, v86
	v_pk_mul_f32 v[78:79], v[120:121], v[78:79]
	v_mov_b32_dpp v83, v86 row_shr:2 row_mask:0xf bank_mask:0xf
	v_mov_b32_dpp v82, v74 row_shr:2 row_mask:0xf bank_mask:0xf
	v_pk_fma_f32 v[78:79], v[168:169], v[118:119], v[78:79]
	v_mov_b32_dpp v94, v91 row_ror:2 row_mask:0xf bank_mask:0xf bound_ctrl:1
	v_pk_fma_f32 v[78:79], v[124:125], v[82:83], v[78:79]
	v_mov_b32_dpp v83, v95 row_ror:1 row_mask:0xf bank_mask:0xf bound_ctrl:1
	v_pk_add_f32 v[78:79], v[196:197], v[78:79]
	v_mov_b32_dpp v95, v95 row_ror:2 row_mask:0xf bank_mask:0xf bound_ctrl:1
	v_mul_f32_e32 v82, 0xbfb8aa3b, v79
	v_exp_f32_e32 v155, v82
	v_mov_b32_dpp v83, v87 row_shr:1 row_mask:0xf bank_mask:0xf
	v_mov_b32_dpp v82, v91 row_ror:1 row_mask:0xf bank_mask:0xf bound_ctrl:1
	v_mov_b32_e32 v90, v75
	v_mov_b32_e32 v91, v87
	v_mov_b32_dpp v82, v75 row_shr:1 row_mask:0xf bank_mask:0xf
	v_pk_mul_f32 v[82:83], v[126:127], v[82:83]
	v_mov_b32_dpp v95, v87 row_shr:2 row_mask:0xf bank_mask:0xf
	v_mov_b32_dpp v94, v75 row_shr:2 row_mask:0xf bank_mask:0xf
	v_pk_fma_f32 v[82:83], v[90:91], v[122:123], v[82:83]
	v_add_f32_e32 v91, 1.0, v155
	v_pk_fma_f32 v[82:83], v[198:199], v[94:95], v[82:83]
	v_rcp_f32_e32 v91, v91
	v_pk_add_f32 v[82:83], v[200:201], v[82:83]
	v_mul_f32_e32 v79, v79, v91
	v_mul_f32_e32 v90, 0xbfb8aa3b, v83
	v_exp_f32_e32 v90, v90
	v_mul_f32_e32 v78, v78, v79
	v_add_f32_e32 v90, 1.0, v90
	v_rcp_f32_e32 v90, v90
	s_nop 0
	v_mul_f32_e32 v79, v83, v90
	v_mul_f32_e32 v79, v82, v79
	v_mov_b64_e32 v[90:91], s[48:49]
	v_cvt_pk_bf16_f32 v173, v78, v79
	v_mad_i64_i32 v[78:79], s[58:59], v149, s85, v[90:91]
	v_lshl_add_u64 v[78:79], v[78:79], 0, v[170:171]
	v_mov_b32_e32 v244, v172
	v_mov_b32_e32 v245, v173
	v_mov_b32_dpp v83, v86 row_ror:1 row_mask:0xf bank_mask:0xf bound_ctrl:1
	v_mov_b32_dpp v82, v74 row_ror:1 row_mask:0xf bank_mask:0xf bound_ctrl:1
	v_mov_b32_dpp v95, v86 row_ror:2 row_mask:0xf bank_mask:0xf bound_ctrl:1
	v_mov_b32_dpp v83, v88 row_shr:1 row_mask:0xf bank_mask:0xf
	v_mov_b32_dpp v82, v92 row_shr:1 row_mask:0xf bank_mask:0xf
	v_mov_b32_dpp v94, v74 row_ror:2 row_mask:0xf bank_mask:0xf bound_ctrl:1
	v_mov_b32_e32 v168, v92
	v_mov_b32_e32 v169, v88
	v_pk_mul_f32 v[82:83], v[120:121], v[82:83]
	v_mov_b32_dpp v95, v88 row_shr:2 row_mask:0xf bank_mask:0xf
	v_mov_b32_dpp v94, v92 row_shr:2 row_mask:0xf bank_mask:0xf
	v_pk_fma_f32 v[82:83], v[168:169], v[118:119], v[82:83]
	v_mov_b32_dpp v86, v75 row_ror:2 row_mask:0xf bank_mask:0xf bound_ctrl:1
	v_pk_fma_f32 v[82:83], v[124:125], v[94:95], v[82:83]
	v_mov_b32_dpp v95, v87 row_ror:1 row_mask:0xf bank_mask:0xf bound_ctrl:1
	v_pk_add_f32 v[82:83], v[196:197], v[82:83]
	v_mov_b32_dpp v94, v75 row_ror:1 row_mask:0xf bank_mask:0xf bound_ctrl:1
	v_mul_f32_e32 v74, 0xbfb8aa3b, v83
	v_mov_b32_dpp v95, v89 row_shr:1 row_mask:0xf bank_mask:0xf
	v_mov_b32_dpp v94, v93 row_shr:1 row_mask:0xf bank_mask:0xf
	v_exp_f32_e32 v149, v74
	v_mov_b32_dpp v87, v87 row_ror:2 row_mask:0xf bank_mask:0xf bound_ctrl:1
	v_mov_b32_e32 v74, v93
	v_mov_b32_e32 v75, v89
	v_pk_mul_f32 v[94:95], v[126:127], v[94:95]
	v_mov_b32_dpp v87, v89 row_shr:2 row_mask:0xf bank_mask:0xf
	v_mov_b32_dpp v86, v93 row_shr:2 row_mask:0xf bank_mask:0xf
	v_pk_fma_f32 v[74:75], v[74:75], v[122:123], v[94:95]
	s_nop 0
	v_pk_fma_f32 v[74:75], v[198:199], v[86:87], v[74:75]
	v_add_f32_e32 v87, 1.0, v149
	v_pk_add_f32 v[74:75], v[200:201], v[74:75]
	v_rcp_f32_e32 v87, v87
	v_mul_f32_e32 v86, 0xbfb8aa3b, v75
	v_exp_f32_e32 v86, v86
	v_mul_f32_e32 v83, v83, v87
	v_mul_f32_e32 v82, v82, v83
	v_add_f32_e32 v86, 1.0, v86
	v_rcp_f32_e32 v86, v86
	s_nop 0
	v_mul_f32_e32 v75, v75, v86
	v_mul_f32_e32 v74, v74, v75
	v_cvt_pk_bf16_f32 v175, v82, v74
	v_mad_i64_i32 v[74:75], s[58:59], v151, s85, v[90:91]
	v_lshl_add_u64 v[82:83], v[74:75], 0, v[170:171]
	v_mov_b32_e32 v246, v174
	v_mov_b32_e32 v247, v175
	v_mov_b32_dpp v75, v88 row_ror:1 row_mask:0xf bank_mask:0xf bound_ctrl:1
	v_mov_b32_dpp v74, v92 row_ror:1 row_mask:0xf bank_mask:0xf bound_ctrl:1
	v_mov_b32_dpp v87, v88 row_ror:2 row_mask:0xf bank_mask:0xf bound_ctrl:1
	v_mov_b32_dpp v75, v70 row_shr:1 row_mask:0xf bank_mask:0xf
	v_mov_b32_dpp v74, v66 row_shr:1 row_mask:0xf bank_mask:0xf
	v_mov_b32_dpp v86, v92 row_ror:2 row_mask:0xf bank_mask:0xf bound_ctrl:1
	v_mov_b32_e32 v94, v66
	v_mov_b32_e32 v95, v70
	v_pk_mul_f32 v[74:75], v[120:121], v[74:75]
	v_mov_b32_dpp v87, v70 row_shr:2 row_mask:0xf bank_mask:0xf
	v_mov_b32_dpp v86, v66 row_shr:2 row_mask:0xf bank_mask:0xf
	v_pk_fma_f32 v[74:75], v[94:95], v[118:119], v[74:75]
	v_mov_b32_dpp v88, v93 row_ror:2 row_mask:0xf bank_mask:0xf bound_ctrl:1
	v_pk_fma_f32 v[74:75], v[124:125], v[86:87], v[74:75]
	v_mov_b32_dpp v87, v89 row_ror:1 row_mask:0xf bank_mask:0xf bound_ctrl:1
	v_pk_add_f32 v[74:75], v[196:197], v[74:75]
	v_mov_b32_dpp v89, v89 row_ror:2 row_mask:0xf bank_mask:0xf bound_ctrl:1
	v_mul_f32_e32 v86, 0xbfb8aa3b, v75
	v_exp_f32_e32 v94, v86
	v_mov_b32_dpp v87, v71 row_shr:1 row_mask:0xf bank_mask:0xf
	v_mov_b32_dpp v86, v93 row_ror:1 row_mask:0xf bank_mask:0xf bound_ctrl:1
	v_mov_b32_e32 v92, v67
	v_mov_b32_e32 v93, v71
	v_mov_b32_dpp v86, v67 row_shr:1 row_mask:0xf bank_mask:0xf
	v_pk_mul_f32 v[86:87], v[126:127], v[86:87]
	v_mov_b32_dpp v89, v71 row_shr:2 row_mask:0xf bank_mask:0xf
	v_mov_b32_dpp v88, v67 row_shr:2 row_mask:0xf bank_mask:0xf
	v_pk_fma_f32 v[86:87], v[92:93], v[122:123], v[86:87]
	v_and_b32_e32 v122, 0x1fff, v153
	v_pk_fma_f32 v[86:87], v[198:199], v[88:89], v[86:87]
	v_add_f32_e32 v89, 1.0, v94
	v_pk_add_f32 v[86:87], v[200:201], v[86:87]
	v_rcp_f32_e32 v89, v89
	v_mul_f32_e32 v88, 0xbfb8aa3b, v87
	v_exp_f32_e32 v88, v88
	v_mul_f32_e32 v75, v75, v89
	v_mul_f32_e32 v74, v74, v75
	v_add_f32_e32 v88, 1.0, v88
	v_rcp_f32_e32 v88, v88
	s_nop 0
	v_mul_f32_e32 v75, v87, v88
	v_mul_f32_e32 v75, v86, v75
	v_cvt_pk_bf16_f32 v177, v74, v75
	v_mad_i64_i32 v[74:75], s[58:59], v153, s85, v[90:91]
	v_lshl_add_u64 v[86:87], v[74:75], 0, v[170:171]
	v_lshl_add_u64 v[74:75], v[134:135], 0, s[56:57]
	v_lshl_add_u64 v[74:75], v[146:147], 2, v[74:75]
	v_mov_b32_e32 v248, v176
	v_mov_b32_e32 v249, v177
	s_and_saveexec_b64 s[56:57], s[4:5]
	s_cbranch_execz .LBB0_1226
	v_add_co_u32_e32 v88, vcc, 0x2000, v74
	global_store_dwordx4 v[74:75], v[68:71], off
	s_nop 0
	v_addc_co_u32_e32 v89, vcc, 0, v75, vcc
	v_cmp_lt_u32_e32 vcc, s86, v122
	global_store_dwordx4 v[88:89], v[64:67], off offset:3072
	s_and_b64 exec, exec, vcc
	s_cbranch_execz .LBB0_1226
	v_add_u32_e32 v88, s51, v122
	v_mul_hi_i32_i24_e32 v89, 0x5800, v88
	v_mul_i32_i24_e32 v88, 0x5800, v88
	v_lshl_add_u64 v[88:89], s[14:15], 0, v[88:89]
	v_lshl_add_u64 v[88:89], v[146:147], 2, v[88:89]
	global_store_dwordx4 v[88:89], v[68:71], off
	s_nop 1
	v_add_co_u32_e32 v68, vcc, 0x2000, v88
	s_nop 1
	v_addc_co_u32_e32 v69, vcc, 0, v89, vcc
	global_store_dwordx4 v[68:69], v[64:67], off offset:3072
.LBB0_1226:
	s_or_b64 exec, exec, s[56:57]
	v_mov_b32_e32 v165, v164
	v_mov_b32_e32 v163, v162
	v_mov_b32_e32 v161, v160
	v_mov_b32_e32 v159, v158
	v_mov_b32_e32 v155, v154
	v_mov_b32_e32 v153, v152
	v_mov_b32_e32 v151, v150
	v_mov_b32_e32 v149, v148
	v_mov_b32_e32 v64, v164
	v_mov_b32_e32 v65, v164
	v_pk_mul_f32 v[62:63], v[62:63], v[64:65]
	v_pk_mul_f32 v[60:61], v[60:61], v[164:165]
	v_pk_mul_f32 v[58:59], v[58:59], v[64:65]
	v_pk_mul_f32 v[56:57], v[56:57], v[164:165]
	v_pk_mul_f32 v[52:53], v[52:53], v[162:163]
	v_pk_mul_f32 v[64:65], v[44:45], v[162:163]
	v_pk_mul_f32 v[48:49], v[48:49], v[160:161]
	v_pk_mul_f32 v[44:45], v[36:37], v[160:161]
	v_pk_mul_f32 v[36:37], v[40:41], v[158:159]
	v_pk_mul_f32 v[32:33], v[32:33], v[158:159]
	v_pk_mul_f32 v[28:29], v[28:29], v[154:155]
	v_pk_mul_f32 v[24:25], v[24:25], v[154:155]
	v_pk_mul_f32 v[120:121], v[20:21], v[152:153]
	v_pk_mul_f32 v[12:13], v[12:13], v[152:153]
	v_pk_mul_f32 v[20:21], v[4:5], v[150:151]
	v_pk_mul_f32 v[4:5], v[8:9], v[148:149]
	v_pk_mul_f32 v[0:1], v[0:1], v[148:149]
	v_pk_mul_f32 v[118:119], v[16:17], v[150:151]
	s_waitcnt vmcnt(6)
	v_mul_f32_dpp v16, v60, v116 row_shr:1 row_mask:0xf bank_mask:0xf bound_ctrl:1
	v_mov_b32_dpp v9, v60 row_shr:2 row_mask:0xf bank_mask:0xf bound_ctrl:1
	s_waitcnt vmcnt(5)
	v_fmac_f32_e32 v16, v60, v114
	v_fmac_f32_e32 v16, v110, v9
	s_waitcnt vmcnt(4)
	v_add_f32_e32 v16, v112, v16
	v_mul_f32_e32 v9, 0xbfb8aa3b, v16
	v_exp_f32_e32 v17, v9
	s_waitcnt vmcnt(2)
	v_mul_f32_dpp v41, v56, v108 row_shr:1 row_mask:0xf bank_mask:0xf bound_ctrl:1
	v_mov_b32_dpp v40, v56 row_shr:2 row_mask:0xf bank_mask:0xf bound_ctrl:1
	s_waitcnt vmcnt(1)
	v_fmac_f32_e32 v41, v56, v100
	v_add_f32_e32 v17, 1.0, v17
	v_rcp_f32_e32 v17, v17
	v_fmac_f32_e32 v41, v98, v40
	s_waitcnt vmcnt(0)
	v_add_f32_e32 v40, v102, v41
	v_mul_f32_dpp v66, v57, v109 row_shr:1 row_mask:0xf bank_mask:0xf bound_ctrl:1
	v_mul_f32_dpp v41, v61, v117 row_shr:1 row_mask:0xf bank_mask:0xf bound_ctrl:1
	v_mul_f32_e32 v16, v16, v17
	v_mov_b32_dpp v17, v61 row_shr:2 row_mask:0xf bank_mask:0xf bound_ctrl:1
	v_fmac_f32_e32 v41, v61, v115
	v_fmac_f32_e32 v41, v111, v17
	v_add_f32_e32 v17, v113, v41
	v_mul_f32_e32 v41, 0xbfb8aa3b, v17
	v_exp_f32_e32 v41, v41
	v_mul_f32_e32 v16, v40, v16
	v_mov_b32_dpp v40, v57 row_shr:2 row_mask:0xf bank_mask:0xf bound_ctrl:1
	v_fmac_f32_e32 v66, v57, v101
	v_add_f32_e32 v41, 1.0, v41
	v_rcp_f32_e32 v41, v41
	v_fmac_f32_e32 v66, v99, v40
	v_add_f32_e32 v40, v103, v66
	v_or_b32_e32 v8, 18, v146
	v_mul_f32_e32 v17, v17, v41
	v_mul_f32_e32 v17, v40, v17
	v_cvt_pk_bf16_f32 v94, v16, v17
	v_ashrrev_i32_e32 v9, 31, v8
	v_mov_b32_dpp v16, v60 row_ror:1 row_mask:0xf bank_mask:0xf bound_ctrl:1
	v_mov_b32_dpp v17, v60 row_ror:2 row_mask:0xf bank_mask:0xf bound_ctrl:1
	v_mov_b32_dpp v40, v56 row_ror:1 row_mask:0xf bank_mask:0xf bound_ctrl:1
	v_mov_b32_dpp v16, v52 row_shr:1 row_mask:0xf bank_mask:0xf
	v_mul_f32_e32 v16, v116, v16
	v_mov_b32_dpp v17, v52 row_shr:2 row_mask:0xf bank_mask:0xf
	v_fmac_f32_e32 v16, v52, v114
	v_fmac_f32_e32 v16, v110, v17
	v_add_f32_e32 v16, v112, v16
	v_mul_f32_e32 v17, 0xbfb8aa3b, v16
	v_exp_f32_e32 v17, v17
	v_mov_b32_dpp v40, v64 row_shr:1 row_mask:0xf bank_mask:0xf
	v_mov_b32_dpp v41, v56 row_ror:2 row_mask:0xf bank_mask:0xf bound_ctrl:1
	v_mul_f32_e32 v40, v108, v40
	v_add_f32_e32 v17, 1.0, v17
	v_rcp_f32_e32 v17, v17
	v_mov_b32_dpp v41, v64 row_shr:2 row_mask:0xf bank_mask:0xf
	v_fmac_f32_e32 v40, v64, v100
	v_fmac_f32_e32 v40, v98, v41
	v_mul_f32_e32 v16, v16, v17
	v_mov_b32_dpp v17, v61 row_ror:1 row_mask:0xf bank_mask:0xf bound_ctrl:1
	v_add_f32_e32 v40, v102, v40
	v_mul_f32_e32 v16, v40, v16
	v_mov_b32_dpp v17, v53 row_shr:1 row_mask:0xf bank_mask:0xf
	v_mov_b32_dpp v40, v61 row_ror:2 row_mask:0xf bank_mask:0xf bound_ctrl:1
	v_mul_f32_e32 v17, v117, v17
	v_fmac_f32_e32 v17, v53, v115
	v_mov_b32_dpp v40, v53 row_shr:2 row_mask:0xf bank_mask:0xf
	v_fmac_f32_e32 v17, v111, v40
	v_add_f32_e32 v17, v113, v17
	v_mul_f32_e32 v40, 0xbfb8aa3b, v17
	v_exp_f32_e32 v40, v40
	v_mov_b32_dpp v41, v57 row_ror:1 row_mask:0xf bank_mask:0xf bound_ctrl:1
	v_mov_b32_dpp v66, v57 row_ror:2 row_mask:0xf bank_mask:0xf bound_ctrl:1
	v_add_f32_e32 v40, 1.0, v40
	v_mov_b32_dpp v41, v65 row_shr:1 row_mask:0xf bank_mask:0xf
	v_rcp_f32_e32 v40, v40
	v_mul_f32_e32 v41, v109, v41
	v_mov_b32_dpp v66, v65 row_shr:2 row_mask:0xf bank_mask:0xf
	v_fmac_f32_e32 v41, v65, v101
	v_fmac_f32_e32 v41, v99, v66
	v_add_f32_e32 v41, v103, v41
	v_mul_f32_e32 v17, v17, v40
	v_mul_f32_e32 v17, v41, v17
	v_cvt_pk_bf16_f32 v88, v16, v17
	v_mov_b32_dpp v16, v52 row_ror:1 row_mask:0xf bank_mask:0xf bound_ctrl:1
	s_nop 0
	v_mov_b32_dpp v17, v52 row_ror:2 row_mask:0xf bank_mask:0xf bound_ctrl:1
	v_mov_b32_dpp v40, v64 row_ror:1 row_mask:0xf bank_mask:0xf bound_ctrl:1
	v_mov_b32_dpp v16, v48 row_shr:1 row_mask:0xf bank_mask:0xf
	v_mul_f32_e32 v16, v116, v16
	v_mov_b32_dpp v17, v48 row_shr:2 row_mask:0xf bank_mask:0xf
	v_fmac_f32_e32 v16, v48, v114
	v_fmac_f32_e32 v16, v110, v17
	v_add_f32_e32 v16, v112, v16
	v_mul_f32_e32 v17, 0xbfb8aa3b, v16
	v_exp_f32_e32 v17, v17
	v_mov_b32_dpp v40, v44 row_shr:1 row_mask:0xf bank_mask:0xf
	v_mov_b32_dpp v41, v64 row_ror:2 row_mask:0xf bank_mask:0xf bound_ctrl:1
	v_mul_f32_e32 v40, v108, v40
	v_add_f32_e32 v17, 1.0, v17
	v_rcp_f32_e32 v17, v17
	v_mov_b32_dpp v41, v44 row_shr:2 row_mask:0xf bank_mask:0xf
	v_fmac_f32_e32 v40, v44, v100
	v_fmac_f32_e32 v40, v98, v41
	v_mul_f32_e32 v16, v16, v17
	v_mov_b32_dpp v17, v53 row_ror:1 row_mask:0xf bank_mask:0xf bound_ctrl:1
	v_add_f32_e32 v40, v102, v40
	v_mul_f32_e32 v16, v40, v16
	v_mov_b32_dpp v17, v49 row_shr:1 row_mask:0xf bank_mask:0xf
	v_mov_b32_dpp v40, v53 row_ror:2 row_mask:0xf bank_mask:0xf bound_ctrl:1
	v_mul_f32_e32 v17, v117, v17
	v_fmac_f32_e32 v17, v49, v115
	v_mov_b32_dpp v40, v49 row_shr:2 row_mask:0xf bank_mask:0xf
	v_fmac_f32_e32 v17, v111, v40
	v_add_f32_e32 v17, v113, v17
	v_mul_f32_e32 v40, 0xbfb8aa3b, v17
	v_exp_f32_e32 v40, v40
	v_mov_b32_dpp v41, v65 row_ror:1 row_mask:0xf bank_mask:0xf bound_ctrl:1
	v_mov_b32_dpp v52, v65 row_ror:2 row_mask:0xf bank_mask:0xf bound_ctrl:1
	v_add_f32_e32 v40, 1.0, v40
	v_mov_b32_dpp v41, v45 row_shr:1 row_mask:0xf bank_mask:0xf
	v_rcp_f32_e32 v40, v40
	v_mul_f32_e32 v41, v109, v41
	v_mov_b32_dpp v52, v45 row_shr:2 row_mask:0xf bank_mask:0xf
	v_fmac_f32_e32 v41, v45, v101
	v_fmac_f32_e32 v41, v99, v52
	v_add_f32_e32 v41, v103, v41
	v_mul_f32_e32 v17, v17, v40
	v_mul_f32_e32 v17, v41, v17
	v_cvt_pk_bf16_f32 v90, v16, v17
	v_mov_b32_dpp v16, v48 row_ror:1 row_mask:0xf bank_mask:0xf bound_ctrl:1
	s_nop 0
	v_mov_b32_dpp v17, v48 row_ror:2 row_mask:0xf bank_mask:0xf bound_ctrl:1
	v_mov_b32_dpp v40, v44 row_ror:1 row_mask:0xf bank_mask:0xf bound_ctrl:1
	v_mov_b32_dpp v16, v36 row_shr:1 row_mask:0xf bank_mask:0xf
	v_mul_f32_e32 v16, v116, v16
	v_mov_b32_dpp v17, v36 row_shr:2 row_mask:0xf bank_mask:0xf
	v_fmac_f32_e32 v16, v36, v114
	v_fmac_f32_e32 v16, v110, v17
	v_add_f32_e32 v16, v112, v16
	v_mul_f32_e32 v17, 0xbfb8aa3b, v16
	v_exp_f32_e32 v17, v17
	v_mov_b32_dpp v40, v32 row_shr:1 row_mask:0xf bank_mask:0xf
	v_mov_b32_dpp v41, v44 row_ror:2 row_mask:0xf bank_mask:0xf bound_ctrl:1
	v_mul_f32_e32 v40, v108, v40
	v_add_f32_e32 v17, 1.0, v17
	v_rcp_f32_e32 v17, v17
	v_mov_b32_dpp v41, v32 row_shr:2 row_mask:0xf bank_mask:0xf
	v_fmac_f32_e32 v40, v32, v100
	v_fmac_f32_e32 v40, v98, v41
	v_mul_f32_e32 v16, v16, v17
	v_mov_b32_dpp v17, v49 row_ror:1 row_mask:0xf bank_mask:0xf bound_ctrl:1
	v_add_f32_e32 v40, v102, v40
	v_mul_f32_e32 v16, v40, v16
	v_mov_b32_dpp v17, v37 row_shr:1 row_mask:0xf bank_mask:0xf
	v_mov_b32_dpp v40, v49 row_ror:2 row_mask:0xf bank_mask:0xf bound_ctrl:1
	v_mul_f32_e32 v17, v117, v17
	v_fmac_f32_e32 v17, v37, v115
	v_mov_b32_dpp v40, v37 row_shr:2 row_mask:0xf bank_mask:0xf
	v_fmac_f32_e32 v17, v111, v40
	v_add_f32_e32 v17, v113, v17
	v_mul_f32_e32 v40, 0xbfb8aa3b, v17
	v_exp_f32_e32 v40, v40
	v_mov_b32_dpp v41, v45 row_ror:1 row_mask:0xf bank_mask:0xf bound_ctrl:1
	v_mov_b32_dpp v44, v45 row_ror:2 row_mask:0xf bank_mask:0xf bound_ctrl:1
	v_add_f32_e32 v40, 1.0, v40
	v_mov_b32_dpp v41, v33 row_shr:1 row_mask:0xf bank_mask:0xf
	v_rcp_f32_e32 v40, v40
	v_mul_f32_e32 v41, v109, v41
	v_mov_b32_dpp v44, v33 row_shr:2 row_mask:0xf bank_mask:0xf
	v_fmac_f32_e32 v41, v33, v101
	v_fmac_f32_e32 v41, v99, v44
	v_add_f32_e32 v41, v103, v41
	v_mul_f32_e32 v17, v17, v40
	v_mul_f32_e32 v17, v41, v17
	v_cvt_pk_bf16_f32 v92, v16, v17
	v_lshlrev_b64 v[8:9], 2, v[8:9]
	v_lshl_add_u64 v[16:17], s[16:17], 0, v[8:9]
	v_lshl_add_u64 v[40:41], s[8:9], 0, v[8:9]
	v_lshl_add_u64 v[44:45], s[24:25], 0, v[8:9]
	global_load_dwordx2 v[52:53], v[16:17], off
	global_load_dwordx2 v[68:69], v[40:41], off
	global_load_dwordx2 v[66:67], v[44:45], off
	v_lshl_add_u64 v[16:17], s[18:19], 0, v[8:9]
	global_load_dwordx2 v[64:65], v[16:17], off
	v_lshl_add_u64 v[16:17], s[26:27], 0, v[8:9]
	v_lshl_add_u64 v[40:41], s[28:29], 0, v[8:9]
	v_lshl_add_u64 v[44:45], s[30:31], 0, v[8:9]
	global_load_dwordx2 v[16:17], v[16:17], off
	s_nop 0
	global_load_dwordx2 v[48:49], v[40:41], off
	s_nop 0
	global_load_dwordx2 v[40:41], v[44:45], off
	v_lshl_add_u64 v[8:9], s[42:43], 0, v[8:9]
	global_load_dwordx2 v[44:45], v[8:9], off
	v_mul_f32_dpp v71, v24, v108 row_shr:1 row_mask:0xf bank_mask:0xf bound_ctrl:1
	v_mul_f32_dpp v9, v28, v116 row_shr:1 row_mask:0xf bank_mask:0xf bound_ctrl:1
	v_mov_b32_dpp v8, v28 row_shr:2 row_mask:0xf bank_mask:0xf bound_ctrl:1
	v_fmac_f32_e32 v9, v28, v114
	v_fmac_f32_e32 v9, v110, v8
	v_add_f32_e32 v8, v112, v9
	v_mul_f32_e32 v9, 0xbfb8aa3b, v8
	v_exp_f32_e32 v9, v9
	v_mov_b32_dpp v70, v24 row_shr:2 row_mask:0xf bank_mask:0xf bound_ctrl:1
	v_fmac_f32_e32 v71, v24, v100
	v_fmac_f32_e32 v71, v98, v70
	v_add_f32_e32 v9, 1.0, v9
	v_rcp_f32_e32 v9, v9
	v_add_f32_e32 v70, v102, v71
	v_mul_f32_dpp v71, v29, v117 row_shr:1 row_mask:0xf bank_mask:0xf bound_ctrl:1
	v_fmac_f32_e32 v71, v29, v115
	v_mul_f32_e32 v8, v8, v9
	v_mov_b32_dpp v9, v29 row_shr:2 row_mask:0xf bank_mask:0xf bound_ctrl:1
	v_fmac_f32_e32 v71, v111, v9
	v_add_f32_e32 v9, v113, v71
	v_mul_f32_e32 v71, 0xbfb8aa3b, v9
	v_exp_f32_e32 v71, v71
	v_mul_f32_dpp v89, v25, v109 row_shr:1 row_mask:0xf bank_mask:0xf bound_ctrl:1
	v_mul_f32_e32 v8, v70, v8
	v_mov_b32_dpp v70, v25 row_shr:2 row_mask:0xf bank_mask:0xf bound_ctrl:1
	v_add_f32_e32 v71, 1.0, v71
	v_rcp_f32_e32 v71, v71
	v_fmac_f32_e32 v89, v25, v101
	v_fmac_f32_e32 v89, v99, v70
	v_add_f32_e32 v70, v103, v89
	v_mul_f32_e32 v9, v9, v71
	v_mul_f32_e32 v9, v70, v9
	v_cvt_pk_bf16_f32 v70, v8, v9
	v_mov_b32_dpp v8, v28 row_ror:1 row_mask:0xf bank_mask:0xf bound_ctrl:1
	s_nop 0
	v_mov_b32_dpp v9, v28 row_ror:2 row_mask:0xf bank_mask:0xf bound_ctrl:1
	v_mov_b32_dpp v71, v24 row_ror:1 row_mask:0xf bank_mask:0xf bound_ctrl:1
	v_mov_b32_dpp v8, v120 row_shr:1 row_mask:0xf bank_mask:0xf
	v_mul_f32_e32 v8, v116, v8
	v_mov_b32_dpp v9, v120 row_shr:2 row_mask:0xf bank_mask:0xf
	v_fmac_f32_e32 v8, v120, v114
	v_fmac_f32_e32 v8, v110, v9
	v_add_f32_e32 v8, v112, v8
	v_mul_f32_e32 v9, 0xbfb8aa3b, v8
	v_exp_f32_e32 v9, v9
	v_mov_b32_dpp v71, v12 row_shr:1 row_mask:0xf bank_mask:0xf
	v_mov_b32_dpp v89, v24 row_ror:2 row_mask:0xf bank_mask:0xf bound_ctrl:1
	v_mul_f32_e32 v71, v108, v71
	v_add_f32_e32 v9, 1.0, v9
	v_rcp_f32_e32 v9, v9
	v_mov_b32_dpp v89, v12 row_shr:2 row_mask:0xf bank_mask:0xf
	v_fmac_f32_e32 v71, v12, v100
	v_fmac_f32_e32 v71, v98, v89
	v_mul_f32_e32 v8, v8, v9
	v_mov_b32_dpp v9, v29 row_ror:1 row_mask:0xf bank_mask:0xf bound_ctrl:1
	v_add_f32_e32 v71, v102, v71
	v_mul_f32_e32 v8, v71, v8
	v_mov_b32_dpp v9, v121 row_shr:1 row_mask:0xf bank_mask:0xf
	v_mov_b32_dpp v71, v29 row_ror:2 row_mask:0xf bank_mask:0xf bound_ctrl:1
	v_mul_f32_e32 v9, v117, v9
	v_fmac_f32_e32 v9, v121, v115
	v_mov_b32_dpp v71, v121 row_shr:2 row_mask:0xf bank_mask:0xf
	v_fmac_f32_e32 v9, v111, v71
	v_add_f32_e32 v9, v113, v9
	v_mul_f32_e32 v71, 0xbfb8aa3b, v9
	v_exp_f32_e32 v71, v71
	v_mov_b32_dpp v89, v25 row_ror:1 row_mask:0xf bank_mask:0xf bound_ctrl:1
	v_mov_b32_dpp v91, v25 row_ror:2 row_mask:0xf bank_mask:0xf bound_ctrl:1
	v_add_f32_e32 v71, 1.0, v71
	v_mov_b32_dpp v89, v13 row_shr:1 row_mask:0xf bank_mask:0xf
	v_rcp_f32_e32 v71, v71
	v_mul_f32_e32 v89, v109, v89
	v_mov_b32_dpp v91, v13 row_shr:2 row_mask:0xf bank_mask:0xf
	v_fmac_f32_e32 v89, v13, v101
	v_fmac_f32_e32 v89, v99, v91
	v_add_f32_e32 v89, v103, v89
	v_mul_f32_e32 v9, v9, v71
	v_mul_f32_e32 v9, v89, v9
	v_cvt_pk_bf16_f32 v8, v8, v9
	s_nop 1
	v_mov_b32_dpp v9, v120 row_ror:1 row_mask:0xf bank_mask:0xf bound_ctrl:1
	v_mov_b32_dpp v71, v120 row_ror:2 row_mask:0xf bank_mask:0xf bound_ctrl:1
	v_mov_b32_dpp v89, v12 row_ror:1 row_mask:0xf bank_mask:0xf bound_ctrl:1
	v_mov_b32_dpp v9, v118 row_shr:1 row_mask:0xf bank_mask:0xf
	v_mul_f32_e32 v9, v116, v9
	v_mov_b32_dpp v71, v118 row_shr:2 row_mask:0xf bank_mask:0xf
	v_fmac_f32_e32 v9, v118, v114
	v_fmac_f32_e32 v9, v110, v71
	v_add_f32_e32 v9, v112, v9
	v_mul_f32_e32 v71, 0xbfb8aa3b, v9
	v_exp_f32_e32 v71, v71
	v_mov_b32_dpp v89, v20 row_shr:1 row_mask:0xf bank_mask:0xf
	v_mov_b32_dpp v12, v12 row_ror:2 row_mask:0xf bank_mask:0xf bound_ctrl:1
	v_mul_f32_e32 v89, v108, v89
	v_add_f32_e32 v71, 1.0, v71
	v_rcp_f32_e32 v71, v71
	v_mov_b32_dpp v12, v20 row_shr:2 row_mask:0xf bank_mask:0xf
	v_fmac_f32_e32 v89, v20, v100
	v_fmac_f32_e32 v89, v98, v12
	v_add_f32_e32 v12, v102, v89
	v_mul_f32_e32 v9, v9, v71
	v_mul_f32_e32 v9, v12, v9
	v_mov_b32_dpp v12, v121 row_ror:1 row_mask:0xf bank_mask:0xf bound_ctrl:1
	v_mov_b32_dpp v71, v121 row_ror:2 row_mask:0xf bank_mask:0xf bound_ctrl:1
	v_mov_b32_dpp v89, v13 row_ror:1 row_mask:0xf bank_mask:0xf bound_ctrl:1
	v_mov_b32_dpp v12, v119 row_shr:1 row_mask:0xf bank_mask:0xf
	v_mul_f32_e32 v12, v117, v12
	v_mov_b32_dpp v71, v119 row_shr:2 row_mask:0xf bank_mask:0xf
	v_fmac_f32_e32 v12, v119, v115
	v_fmac_f32_e32 v12, v111, v71
	v_add_f32_e32 v12, v113, v12
	v_mul_f32_e32 v71, 0xbfb8aa3b, v12
	v_exp_f32_e32 v71, v71
	v_mov_b32_dpp v89, v21 row_shr:1 row_mask:0xf bank_mask:0xf
	v_mov_b32_dpp v13, v13 row_ror:2 row_mask:0xf bank_mask:0xf bound_ctrl:1
	v_mul_f32_e32 v89, v109, v89
	v_add_f32_e32 v71, 1.0, v71
	v_rcp_f32_e32 v71, v71
	v_mov_b32_dpp v13, v21 row_shr:2 row_mask:0xf bank_mask:0xf
	v_fmac_f32_e32 v89, v21, v101
	v_fmac_f32_e32 v89, v99, v13
	v_add_f32_e32 v13, v103, v89
	v_mul_f32_e32 v12, v12, v71
	v_mul_f32_e32 v12, v13, v12
	v_cvt_pk_bf16_f32 v12, v9, v12
	v_mov_b32_dpp v9, v118 row_ror:1 row_mask:0xf bank_mask:0xf bound_ctrl:1
	v_mov_b32_dpp v13, v118 row_ror:2 row_mask:0xf bank_mask:0xf bound_ctrl:1
	v_mov_b32_dpp v71, v20 row_ror:1 row_mask:0xf bank_mask:0xf bound_ctrl:1
	v_mov_b32_dpp v9, v4 row_shr:1 row_mask:0xf bank_mask:0xf
	v_mul_f32_e32 v9, v116, v9
	v_mov_b32_dpp v13, v4 row_shr:2 row_mask:0xf bank_mask:0xf
	v_fmac_f32_e32 v9, v4, v114
	v_fmac_f32_e32 v9, v110, v13
	v_add_f32_e32 v9, v112, v9
	v_mul_f32_e32 v13, 0xbfb8aa3b, v9
	v_exp_f32_e32 v13, v13
	v_mov_b32_dpp v71, v0 row_shr:1 row_mask:0xf bank_mask:0xf
	v_mov_b32_dpp v20, v20 row_ror:2 row_mask:0xf bank_mask:0xf bound_ctrl:1
	v_mul_f32_e32 v71, v108, v71
	v_add_f32_e32 v13, 1.0, v13
	v_rcp_f32_e32 v13, v13
	v_mov_b32_dpp v20, v0 row_shr:2 row_mask:0xf bank_mask:0xf
	v_fmac_f32_e32 v71, v0, v100
	v_fmac_f32_e32 v71, v98, v20
	v_mul_f32_e32 v9, v9, v13
	v_mov_b32_dpp v13, v119 row_ror:1 row_mask:0xf bank_mask:0xf bound_ctrl:1
	v_add_f32_e32 v20, v102, v71
	v_mul_f32_e32 v9, v20, v9
	v_mov_b32_dpp v13, v5 row_shr:1 row_mask:0xf bank_mask:0xf
	v_mov_b32_dpp v20, v119 row_ror:2 row_mask:0xf bank_mask:0xf bound_ctrl:1
	v_mul_f32_e32 v13, v117, v13
	v_fmac_f32_e32 v13, v5, v115
	v_mov_b32_dpp v20, v5 row_shr:2 row_mask:0xf bank_mask:0xf
	v_fmac_f32_e32 v13, v111, v20
	v_add_f32_e32 v13, v113, v13
	v_mul_f32_e32 v20, 0xbfb8aa3b, v13
	v_exp_f32_e32 v20, v20
	v_mov_b32_dpp v71, v21 row_ror:1 row_mask:0xf bank_mask:0xf bound_ctrl:1
	v_mov_b32_dpp v21, v21 row_ror:2 row_mask:0xf bank_mask:0xf bound_ctrl:1
	v_add_f32_e32 v20, 1.0, v20
	v_mov_b32_dpp v71, v1 row_shr:1 row_mask:0xf bank_mask:0xf
	v_rcp_f32_e32 v20, v20
	v_mul_f32_e32 v71, v109, v71
	v_mov_b32_dpp v21, v1 row_shr:2 row_mask:0xf bank_mask:0xf
	v_fmac_f32_e32 v71, v1, v101
	v_fmac_f32_e32 v71, v99, v21
	v_add_f32_e32 v21, v103, v71
	v_mul_f32_e32 v13, v13, v20
	v_mul_f32_e32 v13, v21, v13
	v_cvt_pk_bf16_f32 v20, v9, v13
	s_waitcnt vmcnt(6)
	s_nop 0
	v_mul_f32_dpp v13, v62, v68 row_shr:1 row_mask:0xf bank_mask:0xf bound_ctrl:1
	v_mov_b32_dpp v9, v62 row_shr:2 row_mask:0xf bank_mask:0xf bound_ctrl:1
	s_waitcnt vmcnt(5)
	v_fmac_f32_e32 v13, v62, v66
	v_fmac_f32_e32 v13, v52, v9
	s_waitcnt vmcnt(4)
	v_add_f32_e32 v9, v64, v13
	v_mul_f32_e32 v13, 0xbfb8aa3b, v9
	v_exp_f32_e32 v13, v13
	s_waitcnt vmcnt(2)
	v_mul_f32_dpp v71, v58, v48 row_shr:1 row_mask:0xf bank_mask:0xf bound_ctrl:1
	v_mov_b32_dpp v21, v58 row_shr:2 row_mask:0xf bank_mask:0xf bound_ctrl:1
	s_waitcnt vmcnt(1)
	v_fmac_f32_e32 v71, v58, v40
	v_add_f32_e32 v13, 1.0, v13
	v_rcp_f32_e32 v13, v13
	v_fmac_f32_e32 v71, v16, v21
	s_waitcnt vmcnt(0)
	v_add_f32_e32 v21, v44, v71
	v_mul_f32_dpp v89, v59, v49 row_shr:1 row_mask:0xf bank_mask:0xf bound_ctrl:1
	v_mul_f32_dpp v71, v63, v69 row_shr:1 row_mask:0xf bank_mask:0xf bound_ctrl:1
	v_mul_f32_e32 v9, v9, v13
	v_mov_b32_dpp v13, v63 row_shr:2 row_mask:0xf bank_mask:0xf bound_ctrl:1
	v_fmac_f32_e32 v71, v63, v67
	v_fmac_f32_e32 v71, v53, v13
	v_add_f32_e32 v13, v65, v71
	v_mul_f32_e32 v71, 0xbfb8aa3b, v13
	v_exp_f32_e32 v71, v71
	v_mul_f32_e32 v9, v21, v9
	v_mov_b32_dpp v21, v59 row_shr:2 row_mask:0xf bank_mask:0xf bound_ctrl:1
	v_fmac_f32_e32 v89, v59, v41
	v_add_f32_e32 v71, 1.0, v71
	v_rcp_f32_e32 v71, v71
	v_fmac_f32_e32 v89, v17, v21
	v_add_f32_e32 v21, v45, v89
	v_mul_f32_e32 v13, v13, v71
	v_mul_f32_e32 v13, v21, v13
	v_cvt_pk_bf16_f32 v95, v9, v13
	s_and_saveexec_b64 s[56:57], s[2:3]
	s_xor_b64 s[56:57], exec, s[56:57]
	s_cbranch_execz .LBB0_1228
	v_mov_b64_e32 v[80:81], s[48:49]
	v_mad_i64_i32 v[80:81], s[58:59], v156, s85, v[80:81]
	v_lshl_add_u64 v[80:81], v[146:147], 1, v[80:81]
	global_store_dwordx2 v[80:81], v[94:95], off offset:32

.LBB0_1230:
	s_or_b64 exec, exec, s[56:57]
	v_mov_b32_e32 v161, v160
	v_mov_b32_e32 v159, v158
	v_mov_b32_e32 v163, v162
	v_pk_mul_f32 v[100:101], v[38:39], v[160:161]
	v_pk_mul_f32 v[38:39], v[42:43], v[158:159]
	v_pk_mul_f32 v[34:35], v[34:35], v[158:159]
	v_pk_mul_f32 v[80:81], v[54:55], v[162:163]
	v_pk_mul_f32 v[94:95], v[46:47], v[162:163]
	v_pk_mul_f32 v[98:99], v[50:51], v[160:161]
	v_mov_b32_dpp v51, v62 row_ror:1 row_mask:0xf bank_mask:0xf bound_ctrl:1
	v_mov_b32_dpp v50, v58 row_ror:1 row_mask:0xf bank_mask:0xf bound_ctrl:1
	v_mov_b32_e32 v46, v48
	v_mov_b32_dpp v51, v80 row_shr:1 row_mask:0xf bank_mask:0xf
	v_mov_b32_dpp v50, v94 row_shr:1 row_mask:0xf bank_mask:0xf
	v_mov_b32_e32 v47, v68
	v_mov_b32_dpp v55, v62 row_ror:2 row_mask:0xf bank_mask:0xf bound_ctrl:1
	v_mov_b32_dpp v54, v58 row_ror:2 row_mask:0xf bank_mask:0xf bound_ctrl:1
	v_mov_b32_e32 v56, v94
	v_mov_b32_e32 v57, v80
	v_mov_b32_e32 v42, v40
	v_mov_b32_e32 v43, v66
	v_pk_mul_f32 v[50:51], v[46:47], v[50:51]
	v_mov_b32_dpp v55, v80 row_shr:2 row_mask:0xf bank_mask:0xf
	v_mov_b32_dpp v54, v94 row_shr:2 row_mask:0xf bank_mask:0xf
	v_pk_fma_f32 v[56:57], v[56:57], v[42:43], v[50:51]
	v_mov_b32_e32 v50, v16
	v_mov_b32_e32 v51, v52
	v_mov_b32_dpp v61, v63 row_ror:1 row_mask:0xf bank_mask:0xf bound_ctrl:1
	v_mov_b32_dpp v60, v59 row_ror:1 row_mask:0xf bank_mask:0xf bound_ctrl:1
	v_pk_fma_f32 v[56:57], v[50:51], v[54:55], v[56:57]
	v_mov_b32_e32 v54, v44
	v_mov_b32_e32 v55, v64
	v_mov_b32_dpp v61, v81 row_shr:1 row_mask:0xf bank_mask:0xf
	v_mov_b32_dpp v60, v95 row_shr:1 row_mask:0xf bank_mask:0xf
	v_mov_b32_dpp v62, v59 row_ror:2 row_mask:0xf bank_mask:0xf bound_ctrl:1
	v_mov_b32_e32 v58, v49
	v_mov_b32_e32 v59, v69
	v_pk_add_f32 v[102:103], v[54:55], v[56:57]
	v_mov_b32_dpp v63, v63 row_ror:2 row_mask:0xf bank_mask:0xf bound_ctrl:1
	v_mov_b32_e32 v108, v95
	v_mov_b32_e32 v109, v81
	v_mov_b32_e32 v56, v41
	v_mov_b32_e32 v57, v67
	v_pk_mul_f32 v[60:61], v[58:59], v[60:61]
	v_mov_b32_dpp v63, v81 row_shr:2 row_mask:0xf bank_mask:0xf
	v_mov_b32_dpp v62, v95 row_shr:2 row_mask:0xf bank_mask:0xf
	v_pk_fma_f32 v[108:109], v[108:109], v[56:57], v[60:61]
	v_mov_b32_e32 v60, v17
	v_mov_b32_e32 v61, v53
	v_pk_fma_f32 v[108:109], v[60:61], v[62:63], v[108:109]
	v_mov_b32_e32 v62, v45
	v_mov_b32_e32 v63, v65
	v_pk_add_f32 v[108:109], v[62:63], v[108:109]
	v_mul_f32_e32 v9, 0xbfb8aa3b, v103
	v_mul_f32_e32 v13, 0xbfb8aa3b, v109
	v_exp_f32_e32 v9, v9
	v_exp_f32_e32 v13, v13
	v_add_f32_e32 v9, 1.0, v9
	v_add_f32_e32 v13, 1.0, v13
	v_rcp_f32_e32 v9, v9
	v_rcp_f32_e32 v13, v13
	v_mul_f32_e32 v9, v103, v9
	v_mul_f32_e32 v13, v109, v13
	v_mul_f32_e32 v9, v102, v9
	v_mul_f32_e32 v13, v108, v13
	v_cvt_pk_bf16_f32 v89, v9, v13
	v_mov_b32_e32 v232, v230
	v_mov_b32_e32 v233, v231
	v_mov_b32_e32 v234, v88
	v_mov_b32_e32 v235, v89
	s_nop 1
	v_permlane16_swap_b32_e32 v232, v234
	v_permlane16_swap_b32_e32 v233, v235
	v_lshl_add_u64 v[236:237], v[84:85], 0, v[238:239]
	global_store_dwordx4 v[236:237], v[232:235], off
	s_nop 1
	v_mov_b32_dpp v85, v80 row_ror:1 row_mask:0xf bank_mask:0xf bound_ctrl:1
	v_mov_b32_dpp v84, v94 row_ror:1 row_mask:0xf bank_mask:0xf bound_ctrl:1
	v_mov_b32_dpp v89, v80 row_ror:2 row_mask:0xf bank_mask:0xf bound_ctrl:1
	v_mov_b32_dpp v85, v98 row_shr:1 row_mask:0xf bank_mask:0xf
	v_mov_b32_dpp v84, v100 row_shr:1 row_mask:0xf bank_mask:0xf
	v_mov_b32_dpp v88, v94 row_ror:2 row_mask:0xf bank_mask:0xf bound_ctrl:1
	v_mov_b32_e32 v102, v100
	v_mov_b32_e32 v103, v98
	v_pk_mul_f32 v[84:85], v[46:47], v[84:85]
	v_mov_b32_dpp v89, v98 row_shr:2 row_mask:0xf bank_mask:0xf
	v_mov_b32_dpp v88, v100 row_shr:2 row_mask:0xf bank_mask:0xf
	v_pk_fma_f32 v[84:85], v[102:103], v[42:43], v[84:85]
	v_mov_b32_dpp v80, v95 row_ror:2 row_mask:0xf bank_mask:0xf bound_ctrl:1
	v_pk_fma_f32 v[84:85], v[50:51], v[88:89], v[84:85]
	v_mov_b32_dpp v89, v81 row_ror:1 row_mask:0xf bank_mask:0xf bound_ctrl:1
	v_mov_b32_dpp v88, v95 row_ror:1 row_mask:0xf bank_mask:0xf bound_ctrl:1
	v_mov_b32_dpp v81, v81 row_ror:2 row_mask:0xf bank_mask:0xf bound_ctrl:1
	v_mov_b32_dpp v89, v99 row_shr:1 row_mask:0xf bank_mask:0xf
	v_mov_b32_dpp v88, v101 row_shr:1 row_mask:0xf bank_mask:0xf
	v_mov_b32_e32 v94, v101
	v_mov_b32_e32 v95, v99
	v_pk_mul_f32 v[88:89], v[58:59], v[88:89]
	v_mov_b32_dpp v81, v99 row_shr:2 row_mask:0xf bank_mask:0xf
	v_mov_b32_dpp v80, v101 row_shr:2 row_mask:0xf bank_mask:0xf
	v_pk_fma_f32 v[88:89], v[94:95], v[56:57], v[88:89]
	v_pk_add_f32 v[84:85], v[54:55], v[84:85]
	v_pk_fma_f32 v[80:81], v[60:61], v[80:81], v[88:89]
	v_mul_f32_e32 v9, 0xbfb8aa3b, v85
	v_pk_add_f32 v[80:81], v[62:63], v[80:81]
	v_exp_f32_e32 v9, v9
	v_mul_f32_e32 v13, 0xbfb8aa3b, v81
	v_exp_f32_e32 v13, v13
	v_add_f32_e32 v9, 1.0, v9
	v_rcp_f32_e32 v9, v9
	v_add_f32_e32 v13, 1.0, v13
	v_rcp_f32_e32 v13, v13
	v_mul_f32_e32 v9, v85, v9
	v_mul_f32_e32 v9, v84, v9
	v_mul_f32_e32 v13, v81, v13
	v_mul_f32_e32 v13, v80, v13
	v_cvt_pk_bf16_f32 v91, v9, v13
	v_mov_b32_e32 v232, v240
	v_mov_b32_e32 v233, v241
	v_mov_b32_e32 v234, v90
	v_mov_b32_e32 v235, v91
	s_nop 1
	v_permlane16_swap_b32_e32 v232, v234
	v_permlane16_swap_b32_e32 v233, v235
	v_lshl_add_u64 v[236:237], v[104:105], 0, v[238:239]
	global_store_dwordx4 v[236:237], v[232:235], off
	s_nop 1
	v_mov_b32_dpp v81, v98 row_ror:1 row_mask:0xf bank_mask:0xf bound_ctrl:1
	v_mov_b32_dpp v80, v100 row_ror:1 row_mask:0xf bank_mask:0xf bound_ctrl:1
	v_mov_b32_dpp v85, v98 row_ror:2 row_mask:0xf bank_mask:0xf bound_ctrl:1
	v_mov_b32_dpp v81, v38 row_shr:1 row_mask:0xf bank_mask:0xf
	v_mov_b32_dpp v80, v34 row_shr:1 row_mask:0xf bank_mask:0xf
	v_mov_b32_dpp v84, v100 row_ror:2 row_mask:0xf bank_mask:0xf bound_ctrl:1
	v_mov_b32_e32 v88, v34
	v_mov_b32_e32 v89, v38
	v_pk_mul_f32 v[80:81], v[46:47], v[80:81]
	v_mov_b32_dpp v85, v38 row_shr:2 row_mask:0xf bank_mask:0xf
	v_mov_b32_dpp v84, v34 row_shr:2 row_mask:0xf bank_mask:0xf
	v_pk_fma_f32 v[80:81], v[88:89], v[42:43], v[80:81]
	v_mov_b32_dpp v89, v99 row_ror:2 row_mask:0xf bank_mask:0xf bound_ctrl:1
	v_pk_fma_f32 v[80:81], v[50:51], v[84:85], v[80:81]
	v_mov_b32_dpp v85, v99 row_ror:1 row_mask:0xf bank_mask:0xf bound_ctrl:1
	v_mov_b32_dpp v84, v101 row_ror:1 row_mask:0xf bank_mask:0xf bound_ctrl:1
	v_mov_b32_dpp v88, v101 row_ror:2 row_mask:0xf bank_mask:0xf bound_ctrl:1
	v_mov_b32_dpp v85, v39 row_shr:1 row_mask:0xf bank_mask:0xf
	v_mov_b32_dpp v84, v35 row_shr:1 row_mask:0xf bank_mask:0xf
	v_mov_b32_e32 v90, v35
	v_mov_b32_e32 v91, v39
	v_pk_mul_f32 v[84:85], v[58:59], v[84:85]
	v_mov_b32_dpp v89, v39 row_shr:2 row_mask:0xf bank_mask:0xf
	v_mov_b32_dpp v88, v35 row_shr:2 row_mask:0xf bank_mask:0xf
	v_pk_fma_f32 v[84:85], v[90:91], v[56:57], v[84:85]
	v_pk_add_f32 v[80:81], v[54:55], v[80:81]
	v_pk_fma_f32 v[84:85], v[60:61], v[88:89], v[84:85]
	v_mul_f32_e32 v9, 0xbfb8aa3b, v81
	v_pk_add_f32 v[84:85], v[62:63], v[84:85]
	v_exp_f32_e32 v9, v9
	v_mul_f32_e32 v13, 0xbfb8aa3b, v85
	v_exp_f32_e32 v13, v13
	v_add_f32_e32 v9, 1.0, v9
	v_rcp_f32_e32 v9, v9
	v_add_f32_e32 v13, 1.0, v13
	v_rcp_f32_e32 v13, v13
	v_mul_f32_e32 v9, v81, v9
	v_mul_f32_e32 v9, v80, v9
	v_mul_f32_e32 v13, v85, v13
	v_mul_f32_e32 v13, v84, v13
	v_cvt_pk_bf16_f32 v93, v9, v13
	v_mov_b32_e32 v232, v242
	v_mov_b32_e32 v233, v243
	v_mov_b32_e32 v234, v92
	v_mov_b32_e32 v235, v93
	s_nop 1
	v_permlane16_swap_b32_e32 v232, v234
	v_permlane16_swap_b32_e32 v233, v235
	v_lshl_add_u64 v[236:237], v[106:107], 0, v[238:239]
	global_store_dwordx4 v[236:237], v[232:235], off
	s_nop 1
	s_and_saveexec_b64 s[56:57], s[4:5]
	s_cbranch_execz .LBB0_1233
	global_store_dwordx4 v[76:77], v[36:39], off offset:64
	v_add_co_u32_e32 v76, vcc, 0x2000, v76
	s_nop 1
	v_addc_co_u32_e32 v77, vcc, 0, v77, vcc
	v_cmp_lt_u32_e32 vcc, s86, v166
	global_store_dwordx4 v[76:77], v[32:35], off offset:3136
	s_and_b64 exec, exec, vcc
	s_cbranch_execz .LBB0_1233
	v_add_u32_e32 v9, s45, v166
	v_mul_hi_i32_i24_e32 v77, 0x5800, v9
	v_mul_i32_i24_e32 v76, 0x5800, v9
	v_lshl_add_u64 v[76:77], s[14:15], 0, v[76:77]
	v_lshl_add_u64 v[80:81], v[146:147], 2, v[76:77]
	global_store_dwordx4 v[80:81], v[36:39], off offset:64
	s_nop 1
	v_lshl_add_u64 v[36:37], v[72:73], 2, v[76:77]
	v_add_co_u32_e32 v36, vcc, 0x2000, v36
	s_nop 1
	v_addc_co_u32_e32 v37, vcc, 0, v37, vcc
	global_store_dwordx4 v[36:37], v[32:35], off offset:3072

.LBB0_1237:
	s_or_b64 exec, exec, s[56:57]
	v_mov_b32_e32 v153, v152
	v_mov_b32_e32 v151, v150
	v_mov_b32_e32 v149, v148
	v_pk_mul_f32 v[16:17], v[22:23], v[152:153]
	v_pk_mul_f32 v[22:23], v[6:7], v[150:151]
	v_pk_mul_f32 v[6:7], v[10:11], v[148:149]
	v_pk_mul_f32 v[2:3], v[2:3], v[148:149]
	v_pk_mul_f32 v[14:15], v[14:15], v[152:153]
	v_pk_mul_f32 v[18:19], v[18:19], v[150:151]
	v_mov_b32_dpp v11, v30 row_ror:1 row_mask:0xf bank_mask:0xf bound_ctrl:1
	v_mov_b32_dpp v10, v26 row_ror:1 row_mask:0xf bank_mask:0xf bound_ctrl:1
	v_mov_b32_dpp v25, v30 row_ror:2 row_mask:0xf bank_mask:0xf bound_ctrl:1
	v_mov_b32_dpp v11, v16 row_shr:1 row_mask:0xf bank_mask:0xf
	v_mov_b32_dpp v10, v14 row_shr:1 row_mask:0xf bank_mask:0xf
	v_mov_b32_dpp v24, v26 row_ror:2 row_mask:0xf bank_mask:0xf bound_ctrl:1
	v_mov_b32_e32 v28, v14
	v_mov_b32_e32 v29, v16
	v_pk_mul_f32 v[10:11], v[46:47], v[10:11]
	v_mov_b32_dpp v25, v16 row_shr:2 row_mask:0xf bank_mask:0xf
	v_mov_b32_dpp v24, v14 row_shr:2 row_mask:0xf bank_mask:0xf
	v_pk_fma_f32 v[10:11], v[28:29], v[42:43], v[10:11]
	v_mov_b32_dpp v29, v31 row_ror:2 row_mask:0xf bank_mask:0xf bound_ctrl:1
	v_pk_fma_f32 v[10:11], v[50:51], v[24:25], v[10:11]
	v_mov_b32_dpp v25, v31 row_ror:1 row_mask:0xf bank_mask:0xf bound_ctrl:1
	v_mov_b32_dpp v24, v27 row_ror:1 row_mask:0xf bank_mask:0xf bound_ctrl:1
	v_mov_b32_dpp v28, v27 row_ror:2 row_mask:0xf bank_mask:0xf bound_ctrl:1
	v_mov_b32_dpp v25, v17 row_shr:1 row_mask:0xf bank_mask:0xf
	v_mov_b32_dpp v24, v15 row_shr:1 row_mask:0xf bank_mask:0xf
	v_mov_b32_e32 v26, v15
	v_mov_b32_e32 v27, v17
	v_pk_mul_f32 v[24:25], v[58:59], v[24:25]
	v_mov_b32_dpp v29, v17 row_shr:2 row_mask:0xf bank_mask:0xf
	v_mov_b32_dpp v28, v15 row_shr:2 row_mask:0xf bank_mask:0xf
	v_pk_fma_f32 v[24:25], v[26:27], v[56:57], v[24:25]
	v_pk_add_f32 v[10:11], v[54:55], v[10:11]
	v_pk_fma_f32 v[24:25], v[60:61], v[28:29], v[24:25]
	v_mul_f32_e32 v9, 0xbfb8aa3b, v11
	v_pk_add_f32 v[24:25], v[62:63], v[24:25]
	v_exp_f32_e32 v9, v9
	v_mul_f32_e32 v13, 0xbfb8aa3b, v25
	v_exp_f32_e32 v13, v13
	v_add_f32_e32 v9, 1.0, v9
	v_rcp_f32_e32 v9, v9
	v_add_f32_e32 v13, 1.0, v13
	v_rcp_f32_e32 v13, v13
	v_mul_f32_e32 v9, v11, v9
	v_mul_f32_e32 v9, v10, v9
	v_mul_f32_e32 v10, v25, v13
	v_mul_f32_e32 v10, v24, v10
	v_cvt_pk_bf16_f32 v9, v9, v10
	v_mov_b32_e32 v232, v244
	v_mov_b32_e32 v233, v245
	v_mov_b32_e32 v234, v8
	v_mov_b32_e32 v235, v9
	s_nop 1
	v_permlane16_swap_b32_e32 v232, v234
	v_permlane16_swap_b32_e32 v233, v235
	v_lshl_add_u64 v[236:237], v[78:79], 0, v[238:239]
	global_store_dwordx4 v[236:237], v[232:235], off
	s_nop 1
	s_nop 0
	v_mov_b32_dpp v9, v16 row_ror:1 row_mask:0xf bank_mask:0xf bound_ctrl:1
	v_mov_b32_dpp v8, v14 row_ror:1 row_mask:0xf bank_mask:0xf bound_ctrl:1
	v_mov_b32_dpp v11, v16 row_ror:2 row_mask:0xf bank_mask:0xf bound_ctrl:1
	v_mov_b32_dpp v9, v18 row_shr:1 row_mask:0xf bank_mask:0xf
	v_mov_b32_dpp v8, v22 row_shr:1 row_mask:0xf bank_mask:0xf
	v_mov_b32_dpp v10, v14 row_ror:2 row_mask:0xf bank_mask:0xf bound_ctrl:1
	v_mov_b32_e32 v24, v22
	v_mov_b32_e32 v25, v18
	v_pk_mul_f32 v[8:9], v[46:47], v[8:9]
	v_mov_b32_dpp v11, v18 row_shr:2 row_mask:0xf bank_mask:0xf
	v_mov_b32_dpp v10, v22 row_shr:2 row_mask:0xf bank_mask:0xf
	v_pk_fma_f32 v[8:9], v[24:25], v[42:43], v[8:9]
	v_mov_b32_dpp v16, v15 row_ror:2 row_mask:0xf bank_mask:0xf bound_ctrl:1
	v_pk_fma_f32 v[8:9], v[50:51], v[10:11], v[8:9]
	v_mov_b32_dpp v11, v17 row_ror:1 row_mask:0xf bank_mask:0xf bound_ctrl:1
	v_pk_add_f32 v[8:9], v[54:55], v[8:9]
	v_mov_b32_dpp v17, v17 row_ror:2 row_mask:0xf bank_mask:0xf bound_ctrl:1
	v_mul_f32_e32 v10, 0xbfb8aa3b, v9
	v_exp_f32_e32 v13, v10
	v_mov_b32_dpp v11, v19 row_shr:1 row_mask:0xf bank_mask:0xf
	v_mov_b32_dpp v10, v15 row_ror:1 row_mask:0xf bank_mask:0xf bound_ctrl:1
	v_mov_b32_e32 v14, v23
	v_mov_b32_e32 v15, v19
	v_mov_b32_dpp v10, v23 row_shr:1 row_mask:0xf bank_mask:0xf
	v_pk_mul_f32 v[10:11], v[58:59], v[10:11]
	v_mov_b32_dpp v17, v19 row_shr:2 row_mask:0xf bank_mask:0xf
	v_mov_b32_dpp v16, v23 row_shr:2 row_mask:0xf bank_mask:0xf
	v_pk_fma_f32 v[10:11], v[14:15], v[56:57], v[10:11]
	v_add_f32_e32 v13, 1.0, v13
	v_pk_fma_f32 v[10:11], v[60:61], v[16:17], v[10:11]
	v_rcp_f32_e32 v13, v13
	v_pk_add_f32 v[10:11], v[62:63], v[10:11]
	v_mul_f32_e32 v9, v9, v13
	v_mul_f32_e32 v14, 0xbfb8aa3b, v11
	v_exp_f32_e32 v14, v14
	v_mul_f32_e32 v8, v8, v9
	v_add_f32_e32 v14, 1.0, v14
	v_rcp_f32_e32 v14, v14
	s_nop 0
	v_mul_f32_e32 v9, v11, v14
	v_mul_f32_e32 v9, v10, v9
	v_cvt_pk_bf16_f32 v13, v8, v9
	v_mov_b32_e32 v232, v246
	v_mov_b32_e32 v233, v247
	v_mov_b32_e32 v234, v12
	v_mov_b32_e32 v235, v13
	s_nop 1
	v_permlane16_swap_b32_e32 v232, v234
	v_permlane16_swap_b32_e32 v233, v235
	v_lshl_add_u64 v[236:237], v[82:83], 0, v[238:239]
	global_store_dwordx4 v[236:237], v[232:235], off
	s_nop 1
	s_nop 0
	v_mov_b32_dpp v9, v18 row_ror:1 row_mask:0xf bank_mask:0xf bound_ctrl:1
	v_mov_b32_dpp v8, v22 row_ror:1 row_mask:0xf bank_mask:0xf bound_ctrl:1
	v_mov_b32_dpp v11, v18 row_ror:2 row_mask:0xf bank_mask:0xf bound_ctrl:1
	v_mov_b32_dpp v9, v6 row_shr:1 row_mask:0xf bank_mask:0xf
	v_mov_b32_dpp v8, v2 row_shr:1 row_mask:0xf bank_mask:0xf
	v_mov_b32_dpp v10, v22 row_ror:2 row_mask:0xf bank_mask:0xf bound_ctrl:1
	v_mov_b32_e32 v12, v2
	v_mov_b32_e32 v13, v6
	v_pk_mul_f32 v[8:9], v[46:47], v[8:9]
	v_mov_b32_dpp v11, v6 row_shr:2 row_mask:0xf bank_mask:0xf
	v_mov_b32_dpp v10, v2 row_shr:2 row_mask:0xf bank_mask:0xf
	v_pk_fma_f32 v[8:9], v[12:13], v[42:43], v[8:9]
	v_mov_b32_dpp v13, v19 row_ror:2 row_mask:0xf bank_mask:0xf bound_ctrl:1
	v_pk_fma_f32 v[8:9], v[50:51], v[10:11], v[8:9]
	v_mov_b32_dpp v11, v19 row_ror:1 row_mask:0xf bank_mask:0xf bound_ctrl:1
	v_pk_add_f32 v[8:9], v[54:55], v[8:9]
	v_mov_b32_dpp v12, v23 row_ror:2 row_mask:0xf bank_mask:0xf bound_ctrl:1
	v_mul_f32_e32 v10, 0xbfb8aa3b, v9
	v_exp_f32_e32 v16, v10
	v_mov_b32_dpp v11, v7 row_shr:1 row_mask:0xf bank_mask:0xf
	v_mov_b32_dpp v10, v23 row_ror:1 row_mask:0xf bank_mask:0xf bound_ctrl:1
	v_mov_b32_e32 v14, v3
	v_mov_b32_e32 v15, v7
	v_mov_b32_dpp v10, v3 row_shr:1 row_mask:0xf bank_mask:0xf
	v_pk_mul_f32 v[10:11], v[58:59], v[10:11]
	v_mov_b32_dpp v13, v7 row_shr:2 row_mask:0xf bank_mask:0xf
	v_mov_b32_dpp v12, v3 row_shr:2 row_mask:0xf bank_mask:0xf
	v_pk_fma_f32 v[10:11], v[14:15], v[56:57], v[10:11]
	s_nop 0
	v_pk_fma_f32 v[10:11], v[60:61], v[12:13], v[10:11]
	v_add_f32_e32 v13, 1.0, v16
	v_pk_add_f32 v[10:11], v[62:63], v[10:11]
	v_rcp_f32_e32 v13, v13
	v_mul_f32_e32 v12, 0xbfb8aa3b, v11
	v_exp_f32_e32 v12, v12
	v_mul_f32_e32 v9, v9, v13
	v_mul_f32_e32 v8, v8, v9
	v_add_f32_e32 v12, 1.0, v12
	v_rcp_f32_e32 v12, v12
	s_nop 0
	v_mul_f32_e32 v9, v11, v12
	v_mul_f32_e32 v9, v10, v9
	v_cvt_pk_bf16_f32 v21, v8, v9
	v_mov_b32_e32 v232, v248
	v_mov_b32_e32 v233, v249
	v_mov_b32_e32 v234, v20
	v_mov_b32_e32 v235, v21
	s_nop 1
	v_permlane16_swap_b32_e32 v232, v234
	v_permlane16_swap_b32_e32 v233, v235
	v_lshl_add_u64 v[236:237], v[86:87], 0, v[238:239]
	global_store_dwordx4 v[236:237], v[232:235], off
	s_nop 1
	s_and_saveexec_b64 s[56:57], s[4:5]
	s_cbranch_execz .LBB0_1240
	v_add_co_u32_e32 v8, vcc, 0x2000, v74
	global_store_dwordx4 v[74:75], v[4:7], off offset:64
	s_nop 0
	v_addc_co_u32_e32 v9, vcc, 0, v75, vcc
	v_cmp_lt_u32_e32 vcc, s86, v122
	global_store_dwordx4 v[8:9], v[0:3], off offset:3136
	s_and_b64 exec, exec, vcc
	s_cbranch_execz .LBB0_1240
	v_add_u32_e32 v8, s51, v122
	v_mul_hi_i32_i24_e32 v9, 0x5800, v8
	v_mul_i32_i24_e32 v8, 0x5800, v8
	v_lshl_add_u64 v[8:9], s[14:15], 0, v[8:9]
	v_lshl_add_u64 v[10:11], v[146:147], 2, v[8:9]
	global_store_dwordx4 v[10:11], v[4:7], off offset:64
	s_nop 1
	v_lshl_add_u64 v[4:5], v[72:73], 2, v[8:9]
	v_add_co_u32_e32 v4, vcc, 0x2000, v4
	s_nop 1
	v_addc_co_u32_e32 v5, vcc, 0, v5, vcc
	global_store_dwordx4 v[4:5], v[0:3], off offset:3072
